# GLU epilogue: bias vectors preloaded once and store-ack waits relaxed to counted waits; first grid sync also on XCD barrier (own word set in unused HEND area, zeroed by WG0 at entry with ready flag)
# speedup vs baseline: 1.1853x; 1.0256x over previous
_Z10fwd_kernel6Params:
	s_cmp_lg_u32 s2, 0
	s_cbranch_scc1 .Lb1_init_done
	v_cmp_eq_u32_e64 s[96:97], 0, v0
	s_and_saveexec_b64 s[98:99], s[96:97]
	s_cbranch_execz .Lb1_init_skip
	s_load_dwordx2 s[100:101], s[0:1], 0xf8
	v_mov_b32_e32 v251, 0
	v_mov_b32_e32 v252, 0
	s_waitcnt lgkmcnt(0)
	s_add_u32 s100, s100, 0x1ac40000
	s_addc_u32 s101, s101, 0
	global_store_dword v251, v252, s[100:101] sc0 sc1
	v_add_u32_e32 v251, 0x1000, v251
	global_store_dword v251, v252, s[100:101] sc0 sc1
	v_add_u32_e32 v251, 0x1000, v251
	global_store_dword v251, v252, s[100:101] sc0 sc1
	v_add_u32_e32 v251, 0x1000, v251
	global_store_dword v251, v252, s[100:101] sc0 sc1
	v_add_u32_e32 v251, 0x1000, v251
	global_store_dword v251, v252, s[100:101] sc0 sc1
	v_add_u32_e32 v251, 0x1000, v251
	global_store_dword v251, v252, s[100:101] sc0 sc1
	v_add_u32_e32 v251, 0x1000, v251
	global_store_dword v251, v252, s[100:101] sc0 sc1
	v_add_u32_e32 v251, 0x1000, v251
	global_store_dword v251, v252, s[100:101] sc0 sc1
	v_add_u32_e32 v251, 0x1000, v251
	global_store_dword v251, v252, s[100:101] sc0 sc1
	v_add_u32_e32 v251, 0x1000, v251
	global_store_dword v251, v252, s[100:101] sc0 sc1
	v_add_u32_e32 v251, 0x1000, v251
	global_store_dword v251, v252, s[100:101] sc0 sc1
	v_add_u32_e32 v251, 0x1000, v251
	global_store_dword v251, v252, s[100:101] sc0 sc1
	v_add_u32_e32 v251, 0x1000, v251
	global_store_dword v251, v252, s[100:101] sc0 sc1
	v_add_u32_e32 v251, 0x1000, v251
	global_store_dword v251, v252, s[100:101] sc0 sc1
	v_add_u32_e32 v251, 0x1000, v251
	global_store_dword v251, v252, s[100:101] sc0 sc1
	v_add_u32_e32 v251, 0x1000, v251
	global_store_dword v251, v252, s[100:101] sc0 sc1
	v_add_u32_e32 v251, 0x1000, v251
	global_store_dword v251, v252, s[100:101] sc0 sc1
	v_add_u32_e32 v251, 0x1000, v251
	global_store_dword v251, v252, s[100:101] sc0 sc1
	v_add_u32_e32 v251, 0x1000, v251
	global_store_dword v251, v252, s[100:101] sc0 sc1
	v_add_u32_e32 v251, 0x1000, v251
	global_store_dword v251, v252, s[100:101] sc0 sc1
	v_add_u32_e32 v251, 0x1000, v251
	global_store_dword v251, v252, s[100:101] sc0 sc1
	v_add_u32_e32 v251, 0x1000, v251
	global_store_dword v251, v252, s[100:101] sc0 sc1
	v_add_u32_e32 v251, 0x1000, v251
	global_store_dword v251, v252, s[100:101] sc0 sc1
	v_add_u32_e32 v251, 0x1000, v251
	global_store_dword v251, v252, s[100:101] sc0 sc1
	v_add_u32_e32 v251, 0x1000, v251
	global_store_dword v251, v252, s[100:101] sc0 sc1
	v_add_u32_e32 v251, 0x1000, v251
	global_store_dword v251, v252, s[100:101] sc0 sc1
	v_add_u32_e32 v251, 0x1000, v251
	global_store_dword v251, v252, s[100:101] sc0 sc1
	v_add_u32_e32 v251, 0x1000, v251
	global_store_dword v251, v252, s[100:101] sc0 sc1
	v_add_u32_e32 v251, 0x1000, v251
	global_store_dword v251, v252, s[100:101] sc0 sc1
	v_add_u32_e32 v251, 0x1000, v251
	global_store_dword v251, v252, s[100:101] sc0 sc1
	v_add_u32_e32 v251, 0x1000, v251
	global_store_dword v251, v252, s[100:101] sc0 sc1
	v_add_u32_e32 v251, 0x1000, v251
	global_store_dword v251, v252, s[100:101] sc0 sc1
	v_add_u32_e32 v251, 0x1000, v251
	global_store_dword v251, v252, s[100:101] sc0 sc1
	v_add_u32_e32 v251, 0x1000, v251
	global_store_dword v251, v252, s[100:101] sc0 sc1
	v_add_u32_e32 v251, 0x1000, v251
	buffer_wbl2 sc1
	s_waitcnt vmcnt(0)
	v_mov_b32_e32 v251, 0x28000
	v_mov_b32_e32 v252, 0x5ca1ab1e
	global_store_dword v251, v252, s[100:101] sc0 sc1
	buffer_wbl2 sc1
	s_waitcnt vmcnt(0)
.Lb1_init_skip:
	s_or_b64 exec, exec, s[98:99]
.Lb1_init_done:
	s_load_dwordx16 s[8:23], s[0:1], 0x40
	s_load_dwordx16 s[52:67], s[0:1], 0x80
	s_load_dwordx16 s[36:51], s[0:1], 0xc0
	s_load_dword s34, s[0:1], 0x100
	s_add_u32 s94, s0, 0x100
	s_addc_u32 s95, s1, 0
	v_and_b32_e32 v196, 0x3ff, v0
	v_and_b32_e32 v199, 63, v0
	v_bfe_u32 v201, v0, 6, 4
	s_cmp_gt_i32 s2, 11
	v_and_b32_e32 v198, 15, v0
	s_cbranch_scc1 .LBB0_10
	v_lshl_add_u32 v34, s2, 3, v201
	s_movk_i32 s3, 0x60
	v_cmp_gt_i32_e32 vcc, s3, v34
	s_and_saveexec_b64 s[4:5], vcc
	s_cbranch_execz .LBB0_9
	s_waitcnt lgkmcnt(0)
	v_mov_b32_e32 v2, s20
	v_mov_b32_e32 v3, s21
	v_ashrrev_i32_e32 v35, 31, v34
	v_lshl_add_u64 v[2:3], v[34:35], 2, v[2:3]
	global_load_dword v1, v[2:3], off
	v_lshl_or_b32 v2, v34, 6, v199
	v_ashrrev_i32_e32 v3, 31, v2
	v_lshlrev_b64 v[4:5], 2, v[2:3]
	v_lshl_add_u64 v[6:7], s[18:19], 0, v[4:5]
	global_load_dword v33, v[6:7], off
	v_lshl_add_u64 v[4:5], s[16:17], 0, v[4:5]
	global_load_dword v32, v[4:5], off
	v_mov_b32_e32 v5, 0xb9500d01
	v_mov_b32_e32 v6, 0xbab60b61
	s_waitcnt vmcnt(2)
	v_mul_f32_e32 v1, 0x3fb8aa3b, v1
	v_exp_f32_e32 v1, v1
	s_waitcnt vmcnt(1)
	v_mul_f32_e32 v4, v33, v1
	v_mul_f32_e32 v7, 0.15915494, v4
	v_rndne_f32_e32 v7, v7
	v_fma_f32 v4, v4, 0.15915494, -v7
	v_mul_f32_e32 v7, 4.0, v4
	v_rndne_f32_e32 v7, v7
	v_fma_f32 v4, v4, 4.0, -v7
	v_mul_f32_e32 v8, 0x3fc90fdb, v4
	v_cvt_i32_f32_e32 v7, v7
	v_mul_f32_e32 v9, v8, v8
	v_fmac_f32_e32 v5, 0x3638ef1d, v9
	v_fmac_f32_e32 v6, 0x37d00d01, v9
	v_fmaak_f32 v5, v9, v5, 0x3c088889
	v_fmaak_f32 v6, v9, v6, 0x3d2aaaab
	v_fmaak_f32 v5, v9, v5, 0xbe2aaaab
	v_and_b32_e32 v4, 3, v7
	v_fma_f32 v6, v9, v6, -0.5
	v_fma_f32 v5, v9, v5, 1.0
	v_fma_f32 v30, v9, v6, 1.0
	v_mul_f32_e32 v31, v8, v5
	v_cmp_lt_i32_e32 vcc, 0, v4
	s_and_saveexec_b64 s[6:7], vcc
	s_cbranch_execz .LBB0_8
	v_cmp_ne_u32_e32 vcc, 1, v4
	s_and_saveexec_b64 s[16:17], vcc
	s_xor_b64 s[16:17], exec, s[16:17]
	v_cmp_eq_u32_e32 vcc, 2, v4
	s_nop 1
	v_cndmask_b32_e32 v4, v30, v31, vcc
	v_xor_b32_e32 v5, 0x80000000, v4
	v_cndmask_b32_e64 v4, v31, -v30, vcc
	v_mov_b64_e32 v[30:31], v[4:5]
	s_andn2_saveexec_b64 s[16:17], s[16:17]
	v_xor_b32_e32 v4, 0x80000000, v31
	v_mov_b32_e32 v5, v30
	v_mov_b64_e32 v[30:31], v[4:5]
	s_or_b64 exec, exec, s[16:17]

.LBB0_162:
	s_or_b64 exec, exec, s[0:1]
	v_lshrrev_b32_e32 v1, 20, v0
	v_lshrrev_b32_e32 v0, 10, v0
	s_waitcnt vmcnt(0)
	v_or_b32_e32 v0, v0, v1
	s_movk_i32 s0, 0x3ff
	v_and_or_b32 v0, v0, s0, v196
	v_cmp_eq_u32_e64 s[0:1], 0, v0
	s_barrier
	s_and_saveexec_b64 s[4:5], s[0:1]
	s_cbranch_execz .LBB0_172
	s_sub_u32 s6, s94, 8
	s_subb_u32 s7, s95, 0
	s_load_dwordx2 s[6:7], s[6:7], 0x0
	s_getreg_b32 s3, hwreg(HW_REG_XCC_ID, 0, 4)
	v_mov_b32_e32 v3, 1
	s_lshl_b32 s3, s3, 12
	v_mov_b32_e32 v0, s3
	s_waitcnt lgkmcnt(0)
	s_add_u32 s6, s6, 0x1ac40000
	s_addc_u32 s7, s7, 0
	v_mov_b32_e32 v2, 0x28000
	s_mov_b32 s23, 0
.Lgs1_flag:
	global_load_dword v1, v2, s[6:7] sc1
	s_add_u32 s23, s23, 1
	s_waitcnt vmcnt(0)
	v_readfirstlane_b32 s22, v1
	s_cmp_eq_u32 s22, 0x5ca1ab1e
	s_cbranch_scc1 .Lgs1_flag_ok
	s_sleep 1
	s_cmp_lt_u32 s23, 0x20000
	s_cbranch_scc1 .Lgs1_flag
.Lgs1_flag_ok:
	v_mov_b32_e32 v2, 0x20000
	global_atomic_add v1, v0, v3, s[6:7] sc0
	s_waitcnt vmcnt(0)
	v_readfirstlane_b32 s10, v1
	v_add_u32_e32 v0, 0x10000, v0
	s_and_b32 s22, s10, 31
	s_lshr_b32 s11, s10, 5
	s_cmp_eq_u32 s22, 31
	s_cbranch_scc1 .Lgs1_lead
	s_mov_b32 s23, 0
.Lgs1_spin_a:
	s_sleep 1
	global_load_dword v1, v0, s[6:7] sc1
	s_add_u32 s23, s23, 1
	s_waitcnt vmcnt(0)
	v_readfirstlane_b32 s22, v1
	s_cmp_lg_u32 s22, s11
	s_cbranch_scc1 .Lgs1_acq
	s_cmp_lt_u32 s23, 0x20000
	s_cbranch_scc1 .Lgs1_spin_a
	s_branch .Lgs1_acq
.Lgs1_lead:
	buffer_wbl2 sc1
	s_waitcnt vmcnt(0)
	global_atomic_add v1, v2, v3, s[6:7] sc0
	s_waitcnt vmcnt(0)
	v_readfirstlane_b32 s10, v1
	v_mov_b32_e32 v2, 0x21000
	s_and_b32 s22, s10, 7
	s_lshr_b32 s11, s10, 3
	s_cmp_eq_u32 s22, 7
	s_cbranch_scc0 .Lgs1_spin_b0
	global_atomic_add v2, v3, s[6:7]
	s_branch .Lgs1_rel

.Lgs1_spin_b:
	s_sleep 1
	global_load_dword v1, v2, s[6:7] sc1
	s_add_u32 s23, s23, 1
	s_waitcnt vmcnt(0)
	v_readfirstlane_b32 s22, v1
	s_cmp_lg_u32 s22, s11
	s_cbranch_scc1 .Lgs1_rel
	s_cmp_lt_u32 s23, 0x20000
	s_cbranch_scc1 .Lgs1_spin_b
.Lgs1_rel:
	global_atomic_add v0, v3, s[6:7]
.Lgs1_acq:
	buffer_inv sc1
	s_waitcnt vmcnt(0)
.LBB0_172:
	s_or_b64 exec, exec, s[4:5]
	v_cmp_gt_u32_e64 s[4:5], 64, v196
	s_barrier
	s_and_saveexec_b64 s[6:7], s[4:5]
	s_cbranch_execz .LBB0_174
	s_waitcnt vmcnt(0)
	buffer_inv sc1
	s_waitcnt vmcnt(0)

.LBB0_414:
	s_waitcnt lgkmcnt(0)
	v_lshl_or_b32 v136, s85, 8, v223
	v_lshl_add_u32 v138, s84, 8, v203
	v_ashrrev_i32_e32 v137, 31, v136
	v_mov_b64_e32 v[140:141], s[22:23]
	v_lshl_add_u64 v[2:3], v[136:137], 2, s[62:63]
	global_load_dwordx4 v[180:183], v[2:3], off
	global_load_dwordx4 v[184:187], v[2:3], off offset:64
	global_load_dwordx4 v[188:191], v[2:3], off offset:512
	global_load_dwordx4 v[192:195], v[2:3], off offset:576
	v_mad_i64_i32 v[142:143], s[6:7], v138, s81, v[140:141]
	v_lshlrev_b64 v[136:137], 1, v[136:137]
	v_ashrrev_i32_e32 v139, 31, v138
	v_lshl_add_u64 v[150:151], v[142:143], 0, v[136:137]
	v_lshlrev_b64 v[142:143], 13, v[138:139]
	v_lshl_add_u64 v[142:143], s[26:27], 0, v[142:143]
	v_lshl_add_u64 v[154:155], v[142:143], 0, v[136:137]
	global_load_dwordx2 v[144:145], v[150:151], off
	global_load_dwordx2 v[148:149], v[154:155], off offset:3072
	v_lshlrev_b64 v[142:143], 12, v[138:139]
	global_load_dwordx2 v[146:147], v[150:151], off offset:32
	global_load_dwordx2 v[152:153], v[150:151], off offset:256
	s_nop 0
	global_load_dwordx2 v[150:151], v[150:151], off offset:288
	s_nop 0
	global_load_dwordx2 v[158:159], v[154:155], off offset:3104
	global_load_dwordx2 v[156:157], v[154:155], off offset:3328
	s_nop 0
	global_load_dwordx2 v[154:155], v[154:155], off offset:3360
	s_mov_b32 s85, s82
	s_mov_b32 s84, s83
	s_mov_b64 s[58:59], s[44:45]
	s_waitcnt vmcnt(0)
	v_add_f32_e32 v1, v128, v180
	v_add_f32_e32 v128, v129, v181
	v_add_f32_e32 v130, v130, v182
	v_add_f32_e32 v131, v131, v183
	v_mul_f32_e32 v1, 0xbfb8aa3b, v1
	v_mul_f32_e32 v132, 0xbfb8aa3b, v128
	v_mul_f32_e32 v133, 0xbfb8aa3b, v130
	v_mul_f32_e32 v134, 0xbfb8aa3b, v131
	v_exp_f32_e32 v130, v1
	v_exp_f32_e32 v131, v132
	v_lshlrev_b32_e32 v1, 16, v148
	v_and_b32_e32 v139, 0xffff0000, v148
	v_exp_f32_e32 v132, v133
	v_exp_f32_e32 v133, v134
	v_mul_f32_e32 v134, 0xbfb8aa3b, v1
	v_mul_f32_e32 v135, 0xbfb8aa3b, v139
	v_exp_f32_e32 v134, v134
	v_exp_f32_e32 v135, v135
	v_pk_add_f32 v[130:131], v[130:131], 1.0 op_sel_hi:[1,0]
	v_lshlrev_b32_e32 v128, 16, v144
	v_div_scale_f32 v160, s[6:7], v131, v131, 1.0
	v_div_scale_f32 v162, s[6:7], v130, v130, 1.0
	v_rcp_f32_e32 v164, v160
	v_rcp_f32_e32 v165, v162
	v_pk_add_f32 v[134:135], v[134:135], 1.0 op_sel_hi:[1,0]
	v_div_scale_f32 v161, vcc, 1.0, v131, 1.0
	v_div_scale_f32 v166, s[8:9], v135, v135, v139
	v_div_scale_f32 v168, s[10:11], v134, v134, v1
	v_rcp_f32_e32 v170, v166
	v_rcp_f32_e32 v171, v168
	v_fma_f32 v172, -v160, v164, 1.0
	v_fma_f32 v173, -v162, v165, 1.0
	v_div_scale_f32 v163, s[6:7], 1.0, v130, 1.0
	v_fmac_f32_e32 v164, v172, v164
	v_fmac_f32_e32 v165, v173, v165
	v_mul_f32_e32 v172, v161, v164
	v_mul_f32_e32 v173, v163, v165
	v_fma_f32 v174, -v166, v170, 1.0
	v_div_scale_f32 v167, s[8:9], v139, v135, v139
	v_fma_f32 v175, -v168, v171, 1.0
	v_fma_f32 v176, -v160, v172, v161
	v_fma_f32 v177, -v162, v173, v163
	v_fmac_f32_e32 v170, v174, v170
	v_div_scale_f32 v169, s[10:11], v1, v134, v1
	v_fmac_f32_e32 v171, v175, v171
	v_fmac_f32_e32 v172, v176, v164
	v_fmac_f32_e32 v173, v177, v165
	v_mul_f32_e32 v174, v167, v170
	v_mul_f32_e32 v175, v169, v171
	v_fma_f32 v160, -v160, v172, v161
	v_fma_f32 v161, -v162, v173, v163
	v_fma_f32 v162, -v166, v174, v167
	v_fma_f32 v163, -v168, v175, v169
	v_div_fmas_f32 v160, v160, v164, v172
	v_fmac_f32_e32 v174, v162, v170
	s_mov_b64 vcc, s[6:7]
	v_fmac_f32_e32 v175, v163, v171
	v_div_fixup_f32 v131, v160, v131, 1.0
	v_div_fmas_f32 v160, v161, v165, v173
	v_fma_f32 v161, -v166, v174, v167
	s_mov_b64 vcc, s[8:9]
	v_and_b32_e32 v129, 0xffff0000, v144
	v_fma_f32 v162, -v168, v175, v169
	v_div_fixup_f32 v130, v160, v130, 1.0
	v_div_fmas_f32 v160, v161, v170, v174
	s_mov_b64 vcc, s[10:11]
	v_pk_add_f32 v[132:133], v[132:133], 1.0 op_sel_hi:[1,0]
	v_pk_mul_f32 v[128:129], v[130:131], v[128:129]
	v_div_fmas_f32 v130, v162, v171, v175
	v_div_fixup_f32 v131, v160, v135, v139
	v_div_fixup_f32 v130, v130, v134, v1
	v_div_scale_f32 v1, s[6:7], v133, v133, 1.0
	v_pk_mul_f32 v[128:129], v[130:131], v[128:129]
	v_rcp_f32_e32 v131, v1
	v_lshlrev_b32_e32 v144, 16, v149
	v_and_b32_e32 v148, 0xffff0000, v149
	v_mul_f32_e32 v149, 0xbfb8aa3b, v144
	v_fma_f32 v139, -v1, v131, 1.0
	v_fmac_f32_e32 v131, v139, v131
	v_div_scale_f32 v139, vcc, 1.0, v133, 1.0
	v_lshlrev_b32_e32 v134, 16, v145
	v_and_b32_e32 v135, 0xffff0000, v145
	v_mul_f32_e32 v145, v139, v131
	v_exp_f32_e32 v130, v149
	v_fma_f32 v149, -v1, v145, v139
	v_fmac_f32_e32 v145, v149, v131
	v_fma_f32 v1, -v1, v145, v139
	v_div_scale_f32 v139, s[6:7], v132, v132, 1.0
	v_rcp_f32_e32 v149, v139
	v_div_fmas_f32 v1, v1, v131, v145
	v_mul_f32_e32 v131, 0xbfb8aa3b, v148
	v_div_fixup_f32 v133, v1, v133, 1.0
	v_fma_f32 v1, -v139, v149, 1.0
	v_exp_f32_e32 v131, v131
	v_fmac_f32_e32 v149, v1, v149
	v_div_scale_f32 v1, vcc, 1.0, v132, 1.0
	v_mul_f32_e32 v145, v1, v149
	v_fma_f32 v160, -v139, v145, v1
	v_fmac_f32_e32 v145, v160, v149
	v_pk_add_f32 v[130:131], v[130:131], 1.0 op_sel_hi:[1,0]
	v_fma_f32 v1, -v139, v145, v1
	v_div_scale_f32 v139, s[6:7], v131, v131, v148
	v_rcp_f32_e32 v160, v139
	v_div_fmas_f32 v1, v1, v149, v145
	v_div_fixup_f32 v132, v1, v132, 1.0
	v_pk_mul_f32 v[132:133], v[132:133], v[134:135]
	v_fma_f32 v1, -v139, v160, 1.0
	v_fmac_f32_e32 v160, v1, v160
	v_div_scale_f32 v1, vcc, v148, v131, v148
	v_mul_f32_e32 v134, v1, v160
	v_fma_f32 v135, -v139, v134, v1
	v_fmac_f32_e32 v134, v135, v160
	v_div_scale_f32 v135, s[6:7], v130, v130, v144
	v_fma_f32 v1, -v139, v134, v1
	v_rcp_f32_e32 v139, v135
	v_div_fmas_f32 v1, v1, v160, v134
	v_div_fixup_f32 v131, v1, v131, v148
	v_fma_f32 v1, -v135, v139, 1.0
	v_fmac_f32_e32 v139, v1, v139
	v_div_scale_f32 v1, vcc, v144, v130, v144
	v_mul_f32_e32 v134, v1, v139
	v_fma_f32 v145, -v135, v134, v1
	v_fmac_f32_e32 v134, v145, v139
	v_fma_f32 v1, -v135, v134, v1
	v_div_fmas_f32 v1, v1, v139, v134
	v_div_fixup_f32 v130, v1, v130, v144
	v_pk_mul_f32 v[130:131], v[130:131], v[132:133]
	v_cvt_pk_bf16_f32 v132, v128, v129
	v_lshl_add_u64 v[128:129], s[24:25], 0, v[142:143]
	v_cvt_pk_bf16_f32 v133, v130, v131
	v_lshl_add_u64 v[128:129], v[128:129], 0, v[136:137]
	global_store_dwordx2 v[128:129], v[132:133], off
	v_lshlrev_b32_e32 v134, 16, v146
	v_and_b32_e32 v135, 0xffff0000, v146
	v_lshlrev_b32_e32 v1, 16, v158
	v_and_b32_e32 v139, 0xffff0000, v158
	s_waitcnt vmcnt(1)
	v_add_f32_e32 v124, v124, v184
	v_add_f32_e32 v125, v125, v185
	v_mul_f32_e32 v124, 0xbfb8aa3b, v124
	v_mul_f32_e32 v125, 0xbfb8aa3b, v125
	v_exp_f32_e32 v124, v124
	v_exp_f32_e32 v125, v125
	v_mul_f32_e32 v130, 0xbfb8aa3b, v1
	v_mul_f32_e32 v131, 0xbfb8aa3b, v139
	v_exp_f32_e32 v130, v130
	v_pk_add_f32 v[124:125], v[124:125], 1.0 op_sel_hi:[1,0]
	v_exp_f32_e32 v131, v131
	v_div_scale_f32 v142, s[6:7], v125, v125, 1.0
	v_rcp_f32_e32 v145, v142
	v_div_scale_f32 v144, s[6:7], v124, v124, 1.0
	v_rcp_f32_e32 v146, v144
	v_fma_f32 v149, -v142, v145, 1.0
	v_div_scale_f32 v143, vcc, 1.0, v125, 1.0
	v_fmac_f32_e32 v145, v149, v145
	v_mul_f32_e32 v149, v143, v145
	v_fma_f32 v160, -v142, v149, v143
	v_fma_f32 v158, -v144, v146, 1.0
	v_fmac_f32_e32 v149, v160, v145
	v_div_scale_f32 v148, s[6:7], 1.0, v124, 1.0
	v_fmac_f32_e32 v146, v158, v146
	v_fma_f32 v142, -v142, v149, v143
	v_mul_f32_e32 v158, v148, v146
	v_div_fmas_f32 v142, v142, v145, v149
	v_div_fixup_f32 v125, v142, v125, 1.0
	v_fma_f32 v142, -v144, v158, v148
	v_pk_add_f32 v[130:131], v[130:131], 1.0 op_sel_hi:[1,0]
	v_fmac_f32_e32 v158, v142, v146
	v_div_scale_f32 v143, s[8:9], v131, v131, v139
	v_fma_f32 v142, -v144, v158, v148
	v_rcp_f32_e32 v144, v143
	s_mov_b64 vcc, s[6:7]
	v_div_fmas_f32 v142, v142, v146, v158
	v_div_fixup_f32 v124, v142, v124, 1.0
	v_pk_mul_f32 v[124:125], v[124:125], v[134:135]
	v_fma_f32 v134, -v143, v144, 1.0
	v_fmac_f32_e32 v144, v134, v144
	v_div_scale_f32 v134, vcc, v139, v131, v139
	v_mul_f32_e32 v135, v134, v144
	v_fma_f32 v142, -v143, v135, v134
	v_fmac_f32_e32 v135, v142, v144
	v_div_scale_f32 v142, s[6:7], v130, v130, v1
	v_fma_f32 v134, -v143, v135, v134
	v_rcp_f32_e32 v143, v142
	v_div_fmas_f32 v134, v134, v144, v135
	v_div_fixup_f32 v131, v134, v131, v139
	v_fma_f32 v134, -v142, v143, 1.0
	v_fmac_f32_e32 v143, v134, v143
	v_div_scale_f32 v134, vcc, v1, v130, v1
	v_mul_f32_e32 v135, v134, v143
	v_fma_f32 v139, -v142, v135, v134
	v_fmac_f32_e32 v135, v139, v143
	v_fma_f32 v134, -v142, v135, v134
	v_div_fmas_f32 v134, v134, v143, v135
	v_div_fixup_f32 v130, v134, v130, v1
	v_add_f32_e32 v1, v126, v186
	v_mul_f32_e32 v1, 0xbfb8aa3b, v1
	v_exp_f32_e32 v126, v1
	v_add_f32_e32 v1, v127, v187
	v_mul_f32_e32 v1, 0xbfb8aa3b, v1
	v_exp_f32_e32 v127, v1
	v_pk_mul_f32 v[124:125], v[130:131], v[124:125]
	v_lshlrev_b32_e32 v1, 16, v159
	v_and_b32_e32 v134, 0xffff0000, v159
	v_pk_add_f32 v[126:127], v[126:127], 1.0 op_sel_hi:[1,0]
	v_mul_f32_e32 v130, 0xbfb8aa3b, v1
	v_div_scale_f32 v131, s[6:7], v127, v127, 1.0
	v_rcp_f32_e32 v135, v131
	v_exp_f32_e32 v130, v130
	v_lshlrev_b32_e32 v132, 16, v147
	v_and_b32_e32 v133, 0xffff0000, v147
	v_fma_f32 v139, -v131, v135, 1.0
	v_fmac_f32_e32 v135, v139, v135
	v_div_scale_f32 v139, vcc, 1.0, v127, 1.0
	v_mul_f32_e32 v142, v139, v135
	v_fma_f32 v143, -v131, v142, v139
	v_fmac_f32_e32 v142, v143, v135
	v_fma_f32 v131, -v131, v142, v139
	v_div_scale_f32 v139, s[6:7], v126, v126, 1.0
	v_rcp_f32_e32 v143, v139
	v_div_fmas_f32 v131, v131, v135, v142
	v_div_fixup_f32 v127, v131, v127, 1.0
	v_div_scale_f32 v135, vcc, 1.0, v126, 1.0
	v_fma_f32 v131, -v139, v143, 1.0
	v_fmac_f32_e32 v143, v131, v143
	v_mul_f32_e32 v131, 0xbfb8aa3b, v134
	v_exp_f32_e32 v131, v131
	v_mul_f32_e32 v142, v135, v143
	v_fma_f32 v144, -v139, v142, v135
	v_fmac_f32_e32 v142, v144, v143
	v_pk_add_f32 v[130:131], v[130:131], 1.0 op_sel_hi:[1,0]
	v_fma_f32 v135, -v139, v142, v135
	v_div_scale_f32 v139, s[6:7], v131, v131, v134
	v_rcp_f32_e32 v144, v139
	v_div_fmas_f32 v135, v135, v143, v142
	v_div_fixup_f32 v126, v135, v126, 1.0
	v_pk_mul_f32 v[126:127], v[126:127], v[132:133]
	v_fma_f32 v132, -v139, v144, 1.0
	v_fmac_f32_e32 v144, v132, v144
	v_div_scale_f32 v132, vcc, v134, v131, v134
	v_mul_f32_e32 v133, v132, v144
	v_fma_f32 v135, -v139, v133, v132
	v_fmac_f32_e32 v133, v135, v144
	v_div_scale_f32 v135, s[6:7], v130, v130, v1
	v_fma_f32 v132, -v139, v133, v132
	v_rcp_f32_e32 v139, v135
	v_div_fmas_f32 v132, v132, v144, v133
	v_div_fixup_f32 v131, v132, v131, v134
	v_cvt_pk_bf16_f32 v124, v124, v125
	v_fma_f32 v132, -v135, v139, 1.0
	v_fmac_f32_e32 v139, v132, v139
	v_div_scale_f32 v132, vcc, v1, v130, v1
	v_mul_f32_e32 v133, v132, v139
	v_fma_f32 v134, -v135, v133, v132
	v_fmac_f32_e32 v133, v134, v139
	v_fma_f32 v132, -v135, v133, v132
	v_div_fmas_f32 v132, v132, v139, v133
	v_div_fixup_f32 v130, v132, v130, v1
	v_pk_mul_f32 v[126:127], v[130:131], v[126:127]
	v_and_b32_e32 v132, 0xffff0000, v156
	v_cvt_pk_bf16_f32 v125, v126, v127
	global_store_dwordx2 v[128:129], v[124:125], off offset:32
	v_lshlrev_b32_e32 v130, 16, v152
	v_and_b32_e32 v131, 0xffff0000, v152
	s_waitcnt vmcnt(2)
	v_add_f32_e32 v1, v120, v188
	v_mul_f32_e32 v1, 0xbfb8aa3b, v1
	v_exp_f32_e32 v120, v1
	v_add_f32_e32 v1, v121, v189
	v_mul_f32_e32 v1, 0xbfb8aa3b, v1
	v_exp_f32_e32 v121, v1
	v_lshlrev_b32_e32 v1, 16, v156
	v_mul_f32_e32 v124, 0xbfb8aa3b, v1
	v_exp_f32_e32 v124, v124
	v_pk_add_f32 v[120:121], v[120:121], 1.0 op_sel_hi:[1,0]
	s_nop 0
	v_div_scale_f32 v125, s[6:7], v121, v121, 1.0
	v_rcp_f32_e32 v133, v125
	s_nop 0
	v_fma_f32 v134, -v125, v133, 1.0
	v_fmac_f32_e32 v133, v134, v133
	v_div_scale_f32 v134, vcc, 1.0, v121, 1.0
	v_mul_f32_e32 v135, v134, v133
	v_fma_f32 v139, -v125, v135, v134
	v_fmac_f32_e32 v135, v139, v133
	v_fma_f32 v125, -v125, v135, v134
	v_div_scale_f32 v134, s[6:7], v120, v120, 1.0
	v_rcp_f32_e32 v139, v134
	v_div_fmas_f32 v125, v125, v133, v135
	v_div_fixup_f32 v121, v125, v121, 1.0
	v_div_scale_f32 v133, vcc, 1.0, v120, 1.0
	v_fma_f32 v125, -v134, v139, 1.0
	v_fmac_f32_e32 v139, v125, v139
	v_mul_f32_e32 v125, 0xbfb8aa3b, v132
	v_exp_f32_e32 v125, v125
	v_mul_f32_e32 v135, v133, v139
	v_fma_f32 v142, -v134, v135, v133
	v_fmac_f32_e32 v135, v142, v139
	v_pk_add_f32 v[124:125], v[124:125], 1.0 op_sel_hi:[1,0]
	v_fma_f32 v133, -v134, v135, v133
	v_div_scale_f32 v134, s[6:7], v125, v125, v132
	v_rcp_f32_e32 v142, v134
	v_div_fmas_f32 v133, v133, v139, v135
	v_div_fixup_f32 v120, v133, v120, 1.0
	v_pk_mul_f32 v[120:121], v[120:121], v[130:131]
	v_fma_f32 v130, -v134, v142, 1.0
	v_fmac_f32_e32 v142, v130, v142
	v_div_scale_f32 v130, vcc, v132, v125, v132
	v_mul_f32_e32 v131, v130, v142
	v_fma_f32 v133, -v134, v131, v130
	v_fmac_f32_e32 v131, v133, v142
	v_div_scale_f32 v133, s[6:7], v124, v124, v1
	v_fma_f32 v130, -v134, v131, v130
	v_rcp_f32_e32 v134, v133
	v_div_fmas_f32 v130, v130, v142, v131
	v_div_fixup_f32 v125, v130, v125, v132
	v_fma_f32 v130, -v133, v134, 1.0
	v_fmac_f32_e32 v134, v130, v134
	v_div_scale_f32 v130, vcc, v1, v124, v1
	v_mul_f32_e32 v131, v130, v134
	v_fma_f32 v132, -v133, v131, v130
	v_fmac_f32_e32 v131, v132, v134
	v_fma_f32 v130, -v133, v131, v130
	v_div_fmas_f32 v130, v130, v134, v131
	v_div_fixup_f32 v124, v130, v124, v1
	v_add_f32_e32 v1, v122, v190
	v_mul_f32_e32 v1, 0xbfb8aa3b, v1
	v_exp_f32_e32 v122, v1
	v_add_f32_e32 v1, v123, v191
	v_mul_f32_e32 v1, 0xbfb8aa3b, v1
	v_exp_f32_e32 v123, v1
	v_pk_mul_f32 v[120:121], v[124:125], v[120:121]
	v_lshlrev_b32_e32 v1, 16, v157
	v_and_b32_e32 v130, 0xffff0000, v157
	v_pk_add_f32 v[122:123], v[122:123], 1.0 op_sel_hi:[1,0]
	v_mul_f32_e32 v124, 0xbfb8aa3b, v1
	v_div_scale_f32 v125, s[6:7], v123, v123, 1.0
	v_rcp_f32_e32 v131, v125
	v_exp_f32_e32 v124, v124
	v_lshlrev_b32_e32 v126, 16, v153
	v_and_b32_e32 v127, 0xffff0000, v153
	v_fma_f32 v132, -v125, v131, 1.0
	v_fmac_f32_e32 v131, v132, v131
	v_div_scale_f32 v132, vcc, 1.0, v123, 1.0
	v_mul_f32_e32 v133, v132, v131
	v_fma_f32 v134, -v125, v133, v132
	v_fmac_f32_e32 v133, v134, v131
	v_fma_f32 v125, -v125, v133, v132
	v_div_scale_f32 v132, s[6:7], v122, v122, 1.0
	v_rcp_f32_e32 v134, v132
	v_div_fmas_f32 v125, v125, v131, v133
	v_div_fixup_f32 v123, v125, v123, 1.0
	v_div_scale_f32 v131, vcc, 1.0, v122, 1.0
	v_fma_f32 v125, -v132, v134, 1.0
	v_fmac_f32_e32 v134, v125, v134
	v_mul_f32_e32 v125, 0xbfb8aa3b, v130
	v_exp_f32_e32 v125, v125
	v_mul_f32_e32 v133, v131, v134
	v_fma_f32 v135, -v132, v133, v131
	v_fmac_f32_e32 v133, v135, v134
	v_pk_add_f32 v[124:125], v[124:125], 1.0 op_sel_hi:[1,0]
	v_fma_f32 v131, -v132, v133, v131
	v_div_scale_f32 v132, s[6:7], v125, v125, v130
	v_rcp_f32_e32 v135, v132
	v_div_fmas_f32 v131, v131, v134, v133
	v_div_fixup_f32 v122, v131, v122, 1.0
	v_pk_mul_f32 v[122:123], v[122:123], v[126:127]
	v_fma_f32 v126, -v132, v135, 1.0
	v_fmac_f32_e32 v135, v126, v135
	v_div_scale_f32 v126, vcc, v130, v125, v130
	v_mul_f32_e32 v127, v126, v135
	v_fma_f32 v131, -v132, v127, v126
	v_fmac_f32_e32 v127, v131, v135
	v_div_scale_f32 v131, s[6:7], v124, v124, v1
	v_fma_f32 v126, -v132, v127, v126
	v_rcp_f32_e32 v132, v131
	v_div_fmas_f32 v126, v126, v135, v127
	v_div_fixup_f32 v125, v126, v125, v130
	v_cvt_pk_bf16_f32 v120, v120, v121
	v_fma_f32 v126, -v131, v132, 1.0
	v_fmac_f32_e32 v132, v126, v132
	v_div_scale_f32 v126, vcc, v1, v124, v1
	v_mul_f32_e32 v127, v126, v132
	v_fma_f32 v130, -v131, v127, v126
	v_fmac_f32_e32 v127, v130, v132
	v_fma_f32 v126, -v131, v127, v126
	v_div_fmas_f32 v126, v126, v132, v127
	v_div_fixup_f32 v124, v126, v124, v1
	v_pk_mul_f32 v[122:123], v[124:125], v[122:123]
	v_and_b32_e32 v126, 0xffff0000, v154
	v_cvt_pk_bf16_f32 v121, v122, v123
	global_store_dwordx2 v[128:129], v[120:121], off offset:256
	v_lshlrev_b32_e32 v124, 16, v150
	v_and_b32_e32 v125, 0xffff0000, v150
	s_waitcnt vmcnt(3)
	v_add_f32_e32 v1, v116, v192
	v_mul_f32_e32 v1, 0xbfb8aa3b, v1
	v_exp_f32_e32 v116, v1
	v_add_f32_e32 v1, v117, v193
	v_mul_f32_e32 v1, 0xbfb8aa3b, v1
	v_exp_f32_e32 v117, v1
	v_lshlrev_b32_e32 v1, 16, v154
	v_mul_f32_e32 v120, 0xbfb8aa3b, v1
	v_exp_f32_e32 v120, v120
	v_pk_add_f32 v[116:117], v[116:117], 1.0 op_sel_hi:[1,0]
	s_nop 0
	v_div_scale_f32 v121, s[6:7], v117, v117, 1.0
	v_rcp_f32_e32 v127, v121
	s_nop 0
	v_fma_f32 v130, -v121, v127, 1.0
	v_fmac_f32_e32 v127, v130, v127
	v_div_scale_f32 v130, vcc, 1.0, v117, 1.0
	v_mul_f32_e32 v131, v130, v127
	v_fma_f32 v132, -v121, v131, v130
	v_fmac_f32_e32 v131, v132, v127
	v_fma_f32 v121, -v121, v131, v130
	v_div_scale_f32 v130, s[6:7], v116, v116, 1.0
	v_rcp_f32_e32 v132, v130
	v_div_fmas_f32 v121, v121, v127, v131
	v_div_fixup_f32 v117, v121, v117, 1.0
	v_div_scale_f32 v127, vcc, 1.0, v116, 1.0
	v_fma_f32 v121, -v130, v132, 1.0
	v_fmac_f32_e32 v132, v121, v132
	v_mul_f32_e32 v121, 0xbfb8aa3b, v126
	v_exp_f32_e32 v121, v121
	v_mul_f32_e32 v131, v127, v132
	v_fma_f32 v133, -v130, v131, v127
	v_fmac_f32_e32 v131, v133, v132
	v_pk_add_f32 v[120:121], v[120:121], 1.0 op_sel_hi:[1,0]
	v_fma_f32 v127, -v130, v131, v127
	v_div_scale_f32 v130, s[6:7], v121, v121, v126
	v_rcp_f32_e32 v133, v130
	v_div_fmas_f32 v127, v127, v132, v131
	v_div_fixup_f32 v116, v127, v116, 1.0
	v_pk_mul_f32 v[116:117], v[116:117], v[124:125]
	v_fma_f32 v124, -v130, v133, 1.0
	v_fmac_f32_e32 v133, v124, v133
	v_div_scale_f32 v124, vcc, v126, v121, v126
	v_mul_f32_e32 v125, v124, v133
	v_fma_f32 v127, -v130, v125, v124
	v_fmac_f32_e32 v125, v127, v133
	v_div_scale_f32 v127, s[6:7], v120, v120, v1
	v_fma_f32 v124, -v130, v125, v124
	v_rcp_f32_e32 v130, v127
	v_div_fmas_f32 v124, v124, v133, v125
	v_div_fixup_f32 v121, v124, v121, v126
	v_fma_f32 v124, -v127, v130, 1.0
	v_fmac_f32_e32 v130, v124, v130
	v_div_scale_f32 v124, vcc, v1, v120, v1
	v_mul_f32_e32 v125, v124, v130
	v_fma_f32 v126, -v127, v125, v124
	v_fmac_f32_e32 v125, v126, v130
	v_fma_f32 v124, -v127, v125, v124
	v_div_fmas_f32 v124, v124, v130, v125
	v_div_fixup_f32 v120, v124, v120, v1
	v_add_f32_e32 v1, v118, v194
	v_mul_f32_e32 v1, 0xbfb8aa3b, v1
	v_exp_f32_e32 v118, v1
	v_add_f32_e32 v1, v119, v195
	v_mul_f32_e32 v1, 0xbfb8aa3b, v1
	v_exp_f32_e32 v119, v1
	v_pk_mul_f32 v[116:117], v[120:121], v[116:117]
	v_lshlrev_b32_e32 v1, 16, v155
	v_and_b32_e32 v124, 0xffff0000, v155
	v_pk_add_f32 v[118:119], v[118:119], 1.0 op_sel_hi:[1,0]
	v_mul_f32_e32 v120, 0xbfb8aa3b, v1
	v_div_scale_f32 v121, s[6:7], v119, v119, 1.0
	v_rcp_f32_e32 v125, v121
	v_exp_f32_e32 v120, v120
	v_lshlrev_b32_e32 v122, 16, v151
	v_and_b32_e32 v123, 0xffff0000, v151
	v_fma_f32 v126, -v121, v125, 1.0
	v_fmac_f32_e32 v125, v126, v125
	v_div_scale_f32 v126, vcc, 1.0, v119, 1.0
	v_mul_f32_e32 v127, v126, v125
	v_fma_f32 v130, -v121, v127, v126
	v_fmac_f32_e32 v127, v130, v125
	v_fma_f32 v121, -v121, v127, v126
	v_div_scale_f32 v126, s[6:7], v118, v118, 1.0
	v_rcp_f32_e32 v130, v126
	v_div_fmas_f32 v121, v121, v125, v127
	v_div_fixup_f32 v119, v121, v119, 1.0
	v_div_scale_f32 v125, vcc, 1.0, v118, 1.0
	v_fma_f32 v121, -v126, v130, 1.0
	v_fmac_f32_e32 v130, v121, v130
	v_mul_f32_e32 v121, 0xbfb8aa3b, v124
	v_exp_f32_e32 v121, v121
	v_mul_f32_e32 v127, v125, v130
	v_fma_f32 v131, -v126, v127, v125
	v_fmac_f32_e32 v127, v131, v130
	v_pk_add_f32 v[120:121], v[120:121], 1.0 op_sel_hi:[1,0]
	v_fma_f32 v125, -v126, v127, v125
	v_div_scale_f32 v126, s[6:7], v121, v121, v124
	v_rcp_f32_e32 v131, v126
	v_div_fmas_f32 v125, v125, v130, v127
	v_div_fixup_f32 v118, v125, v118, 1.0
	v_pk_mul_f32 v[118:119], v[118:119], v[122:123]
	v_fma_f32 v122, -v126, v131, 1.0
	v_fmac_f32_e32 v131, v122, v131
	v_div_scale_f32 v122, vcc, v124, v121, v124
	v_mul_f32_e32 v123, v122, v131
	v_fma_f32 v125, -v126, v123, v122
	v_fmac_f32_e32 v123, v125, v131
	v_div_scale_f32 v125, s[6:7], v120, v120, v1
	v_fma_f32 v122, -v126, v123, v122
	v_rcp_f32_e32 v126, v125
	v_div_fmas_f32 v122, v122, v131, v123
	v_div_fixup_f32 v121, v122, v121, v124
	v_cvt_pk_bf16_f32 v116, v116, v117
	v_fma_f32 v122, -v125, v126, 1.0
	v_fmac_f32_e32 v126, v122, v126
	v_div_scale_f32 v122, vcc, v1, v120, v1
	v_mul_f32_e32 v123, v122, v126
	v_fma_f32 v124, -v125, v123, v122
	v_fmac_f32_e32 v123, v124, v126
	v_fma_f32 v122, -v125, v123, v122
	v_div_fmas_f32 v122, v122, v126, v123
	v_div_fixup_f32 v120, v122, v120, v1
	v_pk_mul_f32 v[118:119], v[120:121], v[118:119]
	v_or_b32_e32 v120, 16, v138
	v_cvt_pk_bf16_f32 v117, v118, v119
	global_store_dwordx2 v[128:129], v[116:117], off offset:288
	v_ashrrev_i32_e32 v121, 31, v120
	v_lshlrev_b64 v[122:123], 13, v[120:121]
	v_lshl_add_u64 v[122:123], s[26:27], 0, v[122:123]
	v_lshl_add_u64 v[128:129], v[122:123], 0, v[136:137]
	global_load_dwordx2 v[124:125], v[128:129], off offset:3072
	v_mad_i64_i32 v[122:123], s[6:7], v120, s81, v[140:141]
	v_lshl_add_u64 v[126:127], v[122:123], 0, v[136:137]
	global_load_dwordx2 v[122:123], v[126:127], off
	v_lshlrev_b64 v[120:121], 12, v[120:121]
	s_waitcnt vmcnt(6)
	v_add_f32_e32 v1, v112, v180
	v_mul_f32_e32 v1, 0xbfb8aa3b, v1
	v_exp_f32_e32 v116, v1
	v_add_f32_e32 v1, v113, v181
	v_mul_f32_e32 v1, 0xbfb8aa3b, v1
	v_exp_f32_e32 v117, v1
	s_waitcnt vmcnt(1)
	v_lshlrev_b32_e32 v1, 16, v124
	v_mul_f32_e32 v132, 0xbfb8aa3b, v1
	global_load_dwordx2 v[112:113], v[128:129], off offset:3104
	global_load_dwordx2 v[130:131], v[128:129], off offset:3328
	s_nop 0
	global_load_dwordx2 v[128:129], v[128:129], off offset:3360
	v_pk_add_f32 v[142:143], v[116:117], 1.0 op_sel_hi:[1,0]
	v_exp_f32_e32 v134, v132
	v_div_scale_f32 v135, s[6:7], v143, v143, 1.0
	v_rcp_f32_e32 v139, v135
	global_load_dwordx2 v[144:145], v[126:127], off offset:32
	global_load_dwordx2 v[132:133], v[126:127], off offset:256
	global_load_dwordx2 v[116:117], v[126:127], off offset:288
	s_waitcnt vmcnt(6)
	v_lshlrev_b32_e32 v126, 16, v122
	v_and_b32_e32 v127, 0xffff0000, v122
	v_fma_f32 v122, -v135, v139, 1.0
	v_fmac_f32_e32 v139, v122, v139
	v_div_scale_f32 v122, vcc, 1.0, v143, 1.0
	v_mul_f32_e32 v146, v122, v139
	v_fma_f32 v147, -v135, v146, v122
	v_fmac_f32_e32 v146, v147, v139
	v_div_scale_f32 v147, s[6:7], v142, v142, 1.0
	v_rcp_f32_e32 v148, v147
	v_and_b32_e32 v124, 0xffff0000, v124
	v_fma_f32 v122, -v135, v146, v122
	v_mul_f32_e32 v135, 0xbfb8aa3b, v124
	v_div_fmas_f32 v122, v122, v139, v146
	v_exp_f32_e32 v135, v135
	v_div_fixup_f32 v143, v122, v143, 1.0
	v_fma_f32 v122, -v147, v148, 1.0
	v_fmac_f32_e32 v148, v122, v148
	v_div_scale_f32 v122, vcc, 1.0, v142, 1.0
	v_mul_f32_e32 v139, v122, v148
	v_fma_f32 v146, -v147, v139, v122
	v_pk_add_f32 v[134:135], v[134:135], 1.0 op_sel_hi:[1,0]
	v_fmac_f32_e32 v139, v146, v148
	v_div_scale_f32 v146, s[6:7], v135, v135, v124
	v_fma_f32 v122, -v147, v139, v122
	v_rcp_f32_e32 v147, v146
	v_div_fmas_f32 v122, v122, v148, v139
	v_div_fixup_f32 v142, v122, v142, 1.0
	v_pk_mul_f32 v[126:127], v[142:143], v[126:127]
	v_fma_f32 v122, -v146, v147, 1.0
	v_fmac_f32_e32 v147, v122, v147
	v_div_scale_f32 v122, vcc, v124, v135, v124
	v_mul_f32_e32 v139, v122, v147
	v_fma_f32 v142, -v146, v139, v122
	v_fmac_f32_e32 v139, v142, v147
	v_div_scale_f32 v142, s[6:7], v134, v134, v1
	v_rcp_f32_e32 v143, v142
	v_fma_f32 v122, -v146, v139, v122
	v_div_fmas_f32 v122, v122, v147, v139
	v_div_fixup_f32 v135, v122, v135, v124
	v_fma_f32 v122, -v142, v143, 1.0
	v_fmac_f32_e32 v143, v122, v143
	v_div_scale_f32 v122, vcc, v1, v134, v1
	v_mul_f32_e32 v124, v122, v143
	v_fma_f32 v139, -v142, v124, v122
	v_fmac_f32_e32 v124, v139, v143
	v_fma_f32 v122, -v142, v124, v122
	v_div_fmas_f32 v122, v122, v143, v124
	v_div_fixup_f32 v134, v122, v134, v1
	v_add_f32_e32 v1, v114, v182
	v_mul_f32_e32 v1, 0xbfb8aa3b, v1
	v_exp_f32_e32 v114, v1
	v_add_f32_e32 v1, v115, v183
	v_mul_f32_e32 v1, 0xbfb8aa3b, v1
	v_exp_f32_e32 v115, v1
	v_lshlrev_b32_e32 v1, 16, v125
	v_and_b32_e32 v124, 0xffff0000, v125
	v_pk_mul_f32 v[126:127], v[134:135], v[126:127]
	v_pk_add_f32 v[114:115], v[114:115], 1.0 op_sel_hi:[1,0]
	v_mul_f32_e32 v118, 0xbfb8aa3b, v1
	v_div_scale_f32 v119, s[6:7], v115, v115, 1.0
	v_rcp_f32_e32 v125, v119
	v_exp_f32_e32 v118, v118
	v_lshlrev_b32_e32 v122, 16, v123
	v_and_b32_e32 v123, 0xffff0000, v123
	v_fma_f32 v134, -v119, v125, 1.0
	v_fmac_f32_e32 v125, v134, v125
	v_div_scale_f32 v134, vcc, 1.0, v115, 1.0
	v_mul_f32_e32 v135, v134, v125
	v_fma_f32 v139, -v119, v135, v134
	v_fmac_f32_e32 v135, v139, v125
	v_fma_f32 v119, -v119, v135, v134
	v_div_scale_f32 v134, s[6:7], v114, v114, 1.0
	v_rcp_f32_e32 v139, v134
	v_div_fmas_f32 v119, v119, v125, v135
	v_div_fixup_f32 v115, v119, v115, 1.0
	v_div_scale_f32 v125, vcc, 1.0, v114, 1.0
	v_fma_f32 v119, -v134, v139, 1.0
	v_fmac_f32_e32 v139, v119, v139
	v_mul_f32_e32 v119, 0xbfb8aa3b, v124
	v_exp_f32_e32 v119, v119
	v_mul_f32_e32 v135, v125, v139
	v_fma_f32 v142, -v134, v135, v125
	v_fmac_f32_e32 v135, v142, v139
	v_pk_add_f32 v[118:119], v[118:119], 1.0 op_sel_hi:[1,0]
	v_fma_f32 v125, -v134, v135, v125
	v_div_scale_f32 v134, s[6:7], v119, v119, v124
	v_rcp_f32_e32 v142, v134
	v_div_fmas_f32 v125, v125, v139, v135
	v_div_fixup_f32 v114, v125, v114, 1.0
	v_pk_mul_f32 v[114:115], v[114:115], v[122:123]
	v_fma_f32 v122, -v134, v142, 1.0
	v_fmac_f32_e32 v142, v122, v142
	v_div_scale_f32 v122, vcc, v124, v119, v124
	v_mul_f32_e32 v123, v122, v142
	v_fma_f32 v125, -v134, v123, v122
	v_fmac_f32_e32 v123, v125, v142
	v_div_scale_f32 v125, s[6:7], v118, v118, v1
	v_fma_f32 v122, -v134, v123, v122
	v_rcp_f32_e32 v134, v125
	v_div_fmas_f32 v122, v122, v142, v123
	v_div_fixup_f32 v119, v122, v119, v124
	v_fma_f32 v122, -v125, v134, 1.0
	v_fmac_f32_e32 v134, v122, v134
	v_div_scale_f32 v122, vcc, v1, v118, v1
	v_mul_f32_e32 v123, v122, v134
	v_fma_f32 v124, -v125, v123, v122
	v_fmac_f32_e32 v123, v124, v134
	v_fma_f32 v122, -v125, v123, v122
	v_div_fmas_f32 v122, v122, v134, v123
	v_div_fixup_f32 v118, v122, v118, v1
	v_pk_mul_f32 v[114:115], v[118:119], v[114:115]
	v_cvt_pk_bf16_f32 v118, v126, v127
	v_cvt_pk_bf16_f32 v119, v114, v115
	v_lshl_add_u64 v[114:115], s[24:25], 0, v[120:121]
	v_lshl_add_u64 v[114:115], v[114:115], 0, v[136:137]
	global_store_dwordx2 v[114:115], v[118:119], off
	s_waitcnt vmcnt(3)
	v_lshlrev_b32_e32 v122, 16, v144
	v_and_b32_e32 v123, 0xffff0000, v144
	s_waitcnt vmcnt(1)
	v_add_f32_e32 v1, v108, v184
	v_mul_f32_e32 v1, 0xbfb8aa3b, v1
	v_exp_f32_e32 v108, v1
	v_add_f32_e32 v1, v109, v185
	v_mul_f32_e32 v1, 0xbfb8aa3b, v1
	v_exp_f32_e32 v109, v1
	v_lshlrev_b32_e32 v1, 16, v112
	v_and_b32_e32 v112, 0xffff0000, v112
	v_mul_f32_e32 v118, 0xbfb8aa3b, v1
	v_pk_add_f32 v[108:109], v[108:109], 1.0 op_sel_hi:[1,0]
	v_exp_f32_e32 v118, v118
	v_div_scale_f32 v119, s[6:7], v109, v109, 1.0
	v_rcp_f32_e32 v124, v119
	s_nop 0
	v_fma_f32 v125, -v119, v124, 1.0
	v_fmac_f32_e32 v124, v125, v124
	v_div_scale_f32 v125, vcc, 1.0, v109, 1.0
	v_mul_f32_e32 v126, v125, v124
	v_fma_f32 v127, -v119, v126, v125
	v_fmac_f32_e32 v126, v127, v124
	v_fma_f32 v119, -v119, v126, v125
	v_div_scale_f32 v125, s[6:7], v108, v108, 1.0
	v_rcp_f32_e32 v127, v125
	v_div_fmas_f32 v119, v119, v124, v126
	v_div_fixup_f32 v109, v119, v109, 1.0
	v_div_scale_f32 v124, vcc, 1.0, v108, 1.0
	v_fma_f32 v119, -v125, v127, 1.0
	v_fmac_f32_e32 v127, v119, v127
	v_mul_f32_e32 v119, 0xbfb8aa3b, v112
	v_exp_f32_e32 v119, v119
	v_mul_f32_e32 v126, v124, v127
	v_fma_f32 v134, -v125, v126, v124
	v_fmac_f32_e32 v126, v134, v127
	v_pk_add_f32 v[118:119], v[118:119], 1.0 op_sel_hi:[1,0]
	v_fma_f32 v124, -v125, v126, v124
	v_div_scale_f32 v125, s[6:7], v119, v119, v112
	v_rcp_f32_e32 v134, v125
	v_div_fmas_f32 v124, v124, v127, v126
	v_div_fixup_f32 v108, v124, v108, 1.0
	v_pk_mul_f32 v[108:109], v[108:109], v[122:123]
	v_fma_f32 v122, -v125, v134, 1.0
	v_fmac_f32_e32 v134, v122, v134
	v_div_scale_f32 v122, vcc, v112, v119, v112
	v_mul_f32_e32 v123, v122, v134
	v_fma_f32 v124, -v125, v123, v122
	v_fmac_f32_e32 v123, v124, v134
	v_div_scale_f32 v124, s[6:7], v118, v118, v1
	v_fma_f32 v122, -v125, v123, v122
	v_rcp_f32_e32 v125, v124
	v_div_fmas_f32 v122, v122, v134, v123
	v_div_fixup_f32 v119, v122, v119, v112
	v_fma_f32 v112, -v124, v125, 1.0
	v_fmac_f32_e32 v125, v112, v125
	v_div_scale_f32 v112, vcc, v1, v118, v1
	v_mul_f32_e32 v122, v112, v125
	v_fma_f32 v123, -v124, v122, v112
	v_fmac_f32_e32 v122, v123, v125
	v_fma_f32 v112, -v124, v122, v112
	v_div_fmas_f32 v112, v112, v125, v122
	v_div_fixup_f32 v118, v112, v118, v1
	v_add_f32_e32 v1, v110, v186
	v_mul_f32_e32 v1, 0xbfb8aa3b, v1
	v_exp_f32_e32 v110, v1
	v_add_f32_e32 v1, v111, v187
	v_mul_f32_e32 v1, 0xbfb8aa3b, v1
	v_exp_f32_e32 v111, v1
	v_lshlrev_b32_e32 v1, 16, v113
	v_and_b32_e32 v120, 0xffff0000, v113
	v_mul_f32_e32 v112, 0xbfb8aa3b, v1
	v_pk_add_f32 v[110:111], v[110:111], 1.0 op_sel_hi:[1,0]
	v_exp_f32_e32 v112, v112
	v_div_scale_f32 v113, s[6:7], v111, v111, 1.0
	v_rcp_f32_e32 v121, v113
	v_pk_mul_f32 v[108:109], v[118:119], v[108:109]
	v_lshlrev_b32_e32 v118, 16, v145
	v_and_b32_e32 v119, 0xffff0000, v145
	v_fma_f32 v122, -v113, v121, 1.0
	v_fmac_f32_e32 v121, v122, v121
	v_div_scale_f32 v122, vcc, 1.0, v111, 1.0
	v_mul_f32_e32 v123, v122, v121
	v_fma_f32 v124, -v113, v123, v122
	v_fmac_f32_e32 v123, v124, v121
	v_fma_f32 v113, -v113, v123, v122
	v_div_scale_f32 v122, s[6:7], v110, v110, 1.0
	v_rcp_f32_e32 v124, v122
	v_div_fmas_f32 v113, v113, v121, v123
	v_div_fixup_f32 v111, v113, v111, 1.0
	v_div_scale_f32 v121, vcc, 1.0, v110, 1.0
	v_fma_f32 v113, -v122, v124, 1.0
	v_fmac_f32_e32 v124, v113, v124
	v_mul_f32_e32 v113, 0xbfb8aa3b, v120
	v_exp_f32_e32 v113, v113
	v_mul_f32_e32 v123, v121, v124
	v_fma_f32 v125, -v122, v123, v121
	v_fmac_f32_e32 v123, v125, v124
	v_pk_add_f32 v[112:113], v[112:113], 1.0 op_sel_hi:[1,0]
	v_fma_f32 v121, -v122, v123, v121
	v_div_scale_f32 v122, s[6:7], v113, v113, v120
	v_rcp_f32_e32 v125, v122
	v_div_fmas_f32 v121, v121, v124, v123
	v_div_fixup_f32 v110, v121, v110, 1.0
	v_pk_mul_f32 v[110:111], v[110:111], v[118:119]
	v_fma_f32 v118, -v122, v125, 1.0
	v_fmac_f32_e32 v125, v118, v125
	v_div_scale_f32 v118, vcc, v120, v113, v120
	v_mul_f32_e32 v119, v118, v125
	v_fma_f32 v121, -v122, v119, v118
	v_fmac_f32_e32 v119, v121, v125
	v_div_scale_f32 v121, s[6:7], v112, v112, v1
	v_fma_f32 v118, -v122, v119, v118
	v_rcp_f32_e32 v122, v121
	v_div_fmas_f32 v118, v118, v125, v119
	v_div_fixup_f32 v113, v118, v113, v120
	v_cvt_pk_bf16_f32 v108, v108, v109
	v_fma_f32 v118, -v121, v122, 1.0
	v_fmac_f32_e32 v122, v118, v122
	v_div_scale_f32 v118, vcc, v1, v112, v1
	v_mul_f32_e32 v119, v118, v122
	v_fma_f32 v120, -v121, v119, v118
	v_fmac_f32_e32 v119, v120, v122
	v_fma_f32 v118, -v121, v119, v118
	v_div_fmas_f32 v118, v118, v122, v119
	v_div_fixup_f32 v112, v118, v112, v1
	v_pk_mul_f32 v[110:111], v[112:113], v[110:111]
	v_and_b32_e32 v118, 0xffff0000, v130
	v_cvt_pk_bf16_f32 v109, v110, v111
	global_store_dwordx2 v[114:115], v[108:109], off offset:32
	v_lshlrev_b32_e32 v112, 16, v132
	v_and_b32_e32 v113, 0xffff0000, v132
	s_waitcnt vmcnt(2)
	v_add_f32_e32 v1, v104, v188
	v_mul_f32_e32 v1, 0xbfb8aa3b, v1
	v_exp_f32_e32 v104, v1
	v_add_f32_e32 v1, v105, v189
	v_mul_f32_e32 v1, 0xbfb8aa3b, v1
	v_exp_f32_e32 v105, v1
	v_lshlrev_b32_e32 v1, 16, v130
	v_mul_f32_e32 v108, 0xbfb8aa3b, v1
	v_exp_f32_e32 v108, v108
	v_pk_add_f32 v[104:105], v[104:105], 1.0 op_sel_hi:[1,0]
	s_nop 0
	v_div_scale_f32 v109, s[6:7], v105, v105, 1.0
	v_rcp_f32_e32 v119, v109
	s_nop 0
	v_fma_f32 v120, -v109, v119, 1.0
	v_fmac_f32_e32 v119, v120, v119
	v_div_scale_f32 v120, vcc, 1.0, v105, 1.0
	v_mul_f32_e32 v121, v120, v119
	v_fma_f32 v122, -v109, v121, v120
	v_fmac_f32_e32 v121, v122, v119
	v_fma_f32 v109, -v109, v121, v120
	v_div_scale_f32 v120, s[6:7], v104, v104, 1.0
	v_rcp_f32_e32 v122, v120
	v_div_fmas_f32 v109, v109, v119, v121
	v_div_fixup_f32 v105, v109, v105, 1.0
	v_div_scale_f32 v119, vcc, 1.0, v104, 1.0
	v_fma_f32 v109, -v120, v122, 1.0
	v_fmac_f32_e32 v122, v109, v122
	v_mul_f32_e32 v109, 0xbfb8aa3b, v118
	v_exp_f32_e32 v109, v109
	v_mul_f32_e32 v121, v119, v122
	v_fma_f32 v123, -v120, v121, v119
	v_fmac_f32_e32 v121, v123, v122
	v_pk_add_f32 v[108:109], v[108:109], 1.0 op_sel_hi:[1,0]
	v_fma_f32 v119, -v120, v121, v119
	v_div_scale_f32 v120, s[6:7], v109, v109, v118
	v_rcp_f32_e32 v123, v120
	v_div_fmas_f32 v119, v119, v122, v121
	v_div_fixup_f32 v104, v119, v104, 1.0
	v_pk_mul_f32 v[104:105], v[104:105], v[112:113]
	v_fma_f32 v112, -v120, v123, 1.0
	v_fmac_f32_e32 v123, v112, v123
	v_div_scale_f32 v112, vcc, v118, v109, v118
	v_mul_f32_e32 v113, v112, v123
	v_fma_f32 v119, -v120, v113, v112
	v_fmac_f32_e32 v113, v119, v123
	v_div_scale_f32 v119, s[6:7], v108, v108, v1
	v_fma_f32 v112, -v120, v113, v112
	v_rcp_f32_e32 v120, v119
	v_div_fmas_f32 v112, v112, v123, v113
	v_div_fixup_f32 v109, v112, v109, v118
	v_fma_f32 v112, -v119, v120, 1.0
	v_fmac_f32_e32 v120, v112, v120
	v_div_scale_f32 v112, vcc, v1, v108, v1
	v_mul_f32_e32 v113, v112, v120
	v_fma_f32 v118, -v119, v113, v112
	v_fmac_f32_e32 v113, v118, v120
	v_fma_f32 v112, -v119, v113, v112
	v_div_fmas_f32 v112, v112, v120, v113
	v_div_fixup_f32 v108, v112, v108, v1
	v_add_f32_e32 v1, v106, v190
	v_mul_f32_e32 v1, 0xbfb8aa3b, v1
	v_exp_f32_e32 v106, v1
	v_add_f32_e32 v1, v107, v191
	v_mul_f32_e32 v1, 0xbfb8aa3b, v1
	v_exp_f32_e32 v107, v1
	v_pk_mul_f32 v[104:105], v[108:109], v[104:105]
	v_lshlrev_b32_e32 v1, 16, v131
	v_and_b32_e32 v112, 0xffff0000, v131
	v_pk_add_f32 v[106:107], v[106:107], 1.0 op_sel_hi:[1,0]
	v_mul_f32_e32 v108, 0xbfb8aa3b, v1
	v_div_scale_f32 v109, s[6:7], v107, v107, 1.0
	v_rcp_f32_e32 v113, v109
	v_exp_f32_e32 v108, v108
	v_lshlrev_b32_e32 v110, 16, v133
	v_and_b32_e32 v111, 0xffff0000, v133
	v_fma_f32 v118, -v109, v113, 1.0
	v_fmac_f32_e32 v113, v118, v113
	v_div_scale_f32 v118, vcc, 1.0, v107, 1.0
	v_mul_f32_e32 v119, v118, v113
	v_fma_f32 v120, -v109, v119, v118
	v_fmac_f32_e32 v119, v120, v113
	v_fma_f32 v109, -v109, v119, v118
	v_div_scale_f32 v118, s[6:7], v106, v106, 1.0
	v_rcp_f32_e32 v120, v118
	v_div_fmas_f32 v109, v109, v113, v119
	v_div_fixup_f32 v107, v109, v107, 1.0
	v_div_scale_f32 v113, vcc, 1.0, v106, 1.0
	v_fma_f32 v109, -v118, v120, 1.0
	v_fmac_f32_e32 v120, v109, v120
	v_mul_f32_e32 v109, 0xbfb8aa3b, v112
	v_exp_f32_e32 v109, v109
	v_mul_f32_e32 v119, v113, v120
	v_fma_f32 v121, -v118, v119, v113
	v_fmac_f32_e32 v119, v121, v120
	v_pk_add_f32 v[108:109], v[108:109], 1.0 op_sel_hi:[1,0]
	v_fma_f32 v113, -v118, v119, v113
	v_div_scale_f32 v118, s[6:7], v109, v109, v112
	v_rcp_f32_e32 v121, v118
	v_div_fmas_f32 v113, v113, v120, v119
	v_div_fixup_f32 v106, v113, v106, 1.0
	v_pk_mul_f32 v[106:107], v[106:107], v[110:111]
	v_fma_f32 v110, -v118, v121, 1.0
	v_fmac_f32_e32 v121, v110, v121
	v_div_scale_f32 v110, vcc, v112, v109, v112
	v_mul_f32_e32 v111, v110, v121
	v_fma_f32 v113, -v118, v111, v110
	v_fmac_f32_e32 v111, v113, v121
	v_div_scale_f32 v113, s[6:7], v108, v108, v1
	v_fma_f32 v110, -v118, v111, v110
	v_rcp_f32_e32 v118, v113
	v_div_fmas_f32 v110, v110, v121, v111
	v_div_fixup_f32 v109, v110, v109, v112
	v_cvt_pk_bf16_f32 v104, v104, v105
	v_fma_f32 v110, -v113, v118, 1.0
	v_fmac_f32_e32 v118, v110, v118
	v_div_scale_f32 v110, vcc, v1, v108, v1
	v_mul_f32_e32 v111, v110, v118
	v_fma_f32 v112, -v113, v111, v110
	v_fmac_f32_e32 v111, v112, v118
	v_fma_f32 v110, -v113, v111, v110
	v_div_fmas_f32 v110, v110, v118, v111
	v_div_fixup_f32 v108, v110, v108, v1
	v_pk_mul_f32 v[106:107], v[108:109], v[106:107]
	v_lshlrev_b32_e32 v108, 16, v116
	v_cvt_pk_bf16_f32 v105, v106, v107
	global_store_dwordx2 v[114:115], v[104:105], off offset:256
	v_and_b32_e32 v109, 0xffff0000, v116
	v_and_b32_e32 v110, 0xffff0000, v128
	s_waitcnt vmcnt(3)
	v_add_f32_e32 v1, v100, v192
	v_mul_f32_e32 v1, 0xbfb8aa3b, v1
	v_exp_f32_e32 v100, v1
	v_add_f32_e32 v1, v101, v193
	v_mul_f32_e32 v1, 0xbfb8aa3b, v1
	v_exp_f32_e32 v101, v1
	v_lshlrev_b32_e32 v1, 16, v128
	v_mul_f32_e32 v104, 0xbfb8aa3b, v1
	v_exp_f32_e32 v104, v104
	v_pk_add_f32 v[100:101], v[100:101], 1.0 op_sel_hi:[1,0]
	s_nop 0
	v_div_scale_f32 v105, s[6:7], v101, v101, 1.0
	v_rcp_f32_e32 v111, v105
	s_nop 0
	v_fma_f32 v112, -v105, v111, 1.0
	v_fmac_f32_e32 v111, v112, v111
	v_div_scale_f32 v112, vcc, 1.0, v101, 1.0
	v_mul_f32_e32 v113, v112, v111
	v_fma_f32 v116, -v105, v113, v112
	v_fmac_f32_e32 v113, v116, v111
	v_fma_f32 v105, -v105, v113, v112
	v_div_scale_f32 v112, s[6:7], v100, v100, 1.0
	v_rcp_f32_e32 v116, v112
	v_div_fmas_f32 v105, v105, v111, v113
	v_div_fixup_f32 v101, v105, v101, 1.0
	v_div_scale_f32 v111, vcc, 1.0, v100, 1.0
	v_fma_f32 v105, -v112, v116, 1.0
	v_fmac_f32_e32 v116, v105, v116
	v_mul_f32_e32 v105, 0xbfb8aa3b, v110
	v_exp_f32_e32 v105, v105
	v_mul_f32_e32 v113, v111, v116
	v_fma_f32 v118, -v112, v113, v111
	v_fmac_f32_e32 v113, v118, v116
	v_pk_add_f32 v[104:105], v[104:105], 1.0 op_sel_hi:[1,0]
	v_fma_f32 v111, -v112, v113, v111
	v_div_scale_f32 v112, s[6:7], v105, v105, v110
	v_rcp_f32_e32 v118, v112
	v_div_fmas_f32 v111, v111, v116, v113
	v_div_fixup_f32 v100, v111, v100, 1.0
	v_pk_mul_f32 v[100:101], v[100:101], v[108:109]
	v_fma_f32 v108, -v112, v118, 1.0
	v_fmac_f32_e32 v118, v108, v118
	v_div_scale_f32 v108, vcc, v110, v105, v110
	v_mul_f32_e32 v109, v108, v118
	v_fma_f32 v111, -v112, v109, v108
	v_fmac_f32_e32 v109, v111, v118
	v_div_scale_f32 v111, s[6:7], v104, v104, v1
	v_fma_f32 v108, -v112, v109, v108
	v_rcp_f32_e32 v112, v111
	v_div_fmas_f32 v108, v108, v118, v109
	v_div_fixup_f32 v105, v108, v105, v110
	v_fma_f32 v108, -v111, v112, 1.0
	v_fmac_f32_e32 v112, v108, v112
	v_div_scale_f32 v108, vcc, v1, v104, v1
	v_mul_f32_e32 v109, v108, v112
	v_fma_f32 v110, -v111, v109, v108
	v_fmac_f32_e32 v109, v110, v112
	v_fma_f32 v108, -v111, v109, v108
	v_div_fmas_f32 v108, v108, v112, v109
	v_div_fixup_f32 v104, v108, v104, v1
	v_add_f32_e32 v1, v102, v194
	v_mul_f32_e32 v1, 0xbfb8aa3b, v1
	v_exp_f32_e32 v102, v1
	v_add_f32_e32 v1, v103, v195
	v_mul_f32_e32 v1, 0xbfb8aa3b, v1
	v_exp_f32_e32 v103, v1
	v_pk_mul_f32 v[100:101], v[104:105], v[100:101]
	v_lshlrev_b32_e32 v1, 16, v129
	v_and_b32_e32 v108, 0xffff0000, v129
	v_pk_add_f32 v[102:103], v[102:103], 1.0 op_sel_hi:[1,0]
	v_mul_f32_e32 v104, 0xbfb8aa3b, v1
	v_div_scale_f32 v105, s[6:7], v103, v103, 1.0
	v_rcp_f32_e32 v109, v105
	v_exp_f32_e32 v104, v104
	v_lshlrev_b32_e32 v106, 16, v117
	v_and_b32_e32 v107, 0xffff0000, v117
	v_fma_f32 v110, -v105, v109, 1.0
	v_fmac_f32_e32 v109, v110, v109
	v_div_scale_f32 v110, vcc, 1.0, v103, 1.0
	v_mul_f32_e32 v111, v110, v109
	v_fma_f32 v112, -v105, v111, v110
	v_fmac_f32_e32 v111, v112, v109
	v_fma_f32 v105, -v105, v111, v110
	v_div_scale_f32 v110, s[6:7], v102, v102, 1.0
	v_rcp_f32_e32 v112, v110
	v_div_fmas_f32 v105, v105, v109, v111
	v_div_fixup_f32 v103, v105, v103, 1.0
	v_div_scale_f32 v109, vcc, 1.0, v102, 1.0
	v_fma_f32 v105, -v110, v112, 1.0
	v_fmac_f32_e32 v112, v105, v112
	v_mul_f32_e32 v105, 0xbfb8aa3b, v108
	v_exp_f32_e32 v105, v105
	v_mul_f32_e32 v111, v109, v112
	v_fma_f32 v113, -v110, v111, v109
	v_fmac_f32_e32 v111, v113, v112
	v_pk_add_f32 v[104:105], v[104:105], 1.0 op_sel_hi:[1,0]
	v_fma_f32 v109, -v110, v111, v109
	v_div_scale_f32 v110, s[6:7], v105, v105, v108
	v_rcp_f32_e32 v113, v110
	v_div_fmas_f32 v109, v109, v112, v111
	v_div_fixup_f32 v102, v109, v102, 1.0
	v_pk_mul_f32 v[102:103], v[102:103], v[106:107]
	v_fma_f32 v106, -v110, v113, 1.0
	v_fmac_f32_e32 v113, v106, v113
	v_div_scale_f32 v106, vcc, v108, v105, v108
	v_mul_f32_e32 v107, v106, v113
	v_fma_f32 v109, -v110, v107, v106
	v_fmac_f32_e32 v107, v109, v113
	v_div_scale_f32 v109, s[6:7], v104, v104, v1
	v_fma_f32 v106, -v110, v107, v106
	v_rcp_f32_e32 v110, v109
	v_div_fmas_f32 v106, v106, v113, v107
	v_div_fixup_f32 v105, v106, v105, v108
	v_cvt_pk_bf16_f32 v100, v100, v101
	v_fma_f32 v106, -v109, v110, 1.0
	v_fmac_f32_e32 v110, v106, v110
	v_div_scale_f32 v106, vcc, v1, v104, v1
	v_mul_f32_e32 v107, v106, v110
	v_fma_f32 v108, -v109, v107, v106
	v_fmac_f32_e32 v107, v108, v110
	v_fma_f32 v106, -v109, v107, v106
	v_div_fmas_f32 v106, v106, v110, v107
	v_div_fixup_f32 v104, v106, v104, v1
	v_pk_mul_f32 v[102:103], v[104:105], v[102:103]
	v_or_b32_e32 v104, 32, v138
	v_cvt_pk_bf16_f32 v101, v102, v103
	global_store_dwordx2 v[114:115], v[100:101], off offset:288
	v_ashrrev_i32_e32 v105, 31, v104
	v_lshlrev_b64 v[106:107], 13, v[104:105]
	v_lshl_add_u64 v[106:107], s[26:27], 0, v[106:107]
	v_lshl_add_u64 v[112:113], v[106:107], 0, v[136:137]
	global_load_dwordx2 v[108:109], v[112:113], off offset:3072
	v_mad_i64_i32 v[106:107], s[6:7], v104, s81, v[140:141]
	v_lshl_add_u64 v[110:111], v[106:107], 0, v[136:137]
	global_load_dwordx2 v[106:107], v[110:111], off
	v_lshlrev_b64 v[104:105], 12, v[104:105]
	s_waitcnt vmcnt(6)
	v_add_f32_e32 v1, v96, v180
	v_mul_f32_e32 v1, 0xbfb8aa3b, v1
	v_exp_f32_e32 v100, v1
	v_add_f32_e32 v1, v97, v181
	v_mul_f32_e32 v1, 0xbfb8aa3b, v1
	v_exp_f32_e32 v101, v1
	s_waitcnt vmcnt(1)
	v_lshlrev_b32_e32 v1, 16, v108
	v_mul_f32_e32 v116, 0xbfb8aa3b, v1
	global_load_dwordx2 v[96:97], v[112:113], off offset:3104
	global_load_dwordx2 v[114:115], v[112:113], off offset:3328
	s_nop 0
	global_load_dwordx2 v[112:113], v[112:113], off offset:3360
	v_pk_add_f32 v[120:121], v[100:101], 1.0 op_sel_hi:[1,0]
	v_exp_f32_e32 v118, v116
	v_div_scale_f32 v119, s[6:7], v121, v121, 1.0
	v_rcp_f32_e32 v124, v119
	global_load_dwordx2 v[122:123], v[110:111], off offset:32
	global_load_dwordx2 v[116:117], v[110:111], off offset:256
	global_load_dwordx2 v[100:101], v[110:111], off offset:288
	s_waitcnt vmcnt(6)
	v_lshlrev_b32_e32 v110, 16, v106
	v_and_b32_e32 v111, 0xffff0000, v106
	v_fma_f32 v106, -v119, v124, 1.0
	v_fmac_f32_e32 v124, v106, v124
	v_div_scale_f32 v106, vcc, 1.0, v121, 1.0
	v_mul_f32_e32 v125, v106, v124
	v_fma_f32 v126, -v119, v125, v106
	v_fmac_f32_e32 v125, v126, v124
	v_div_scale_f32 v126, s[6:7], v120, v120, 1.0
	v_rcp_f32_e32 v127, v126
	v_and_b32_e32 v108, 0xffff0000, v108
	v_fma_f32 v106, -v119, v125, v106
	v_mul_f32_e32 v119, 0xbfb8aa3b, v108
	v_div_fmas_f32 v106, v106, v124, v125
	v_exp_f32_e32 v119, v119
	v_div_fixup_f32 v121, v106, v121, 1.0
	v_fma_f32 v106, -v126, v127, 1.0
	v_fmac_f32_e32 v127, v106, v127
	v_div_scale_f32 v106, vcc, 1.0, v120, 1.0
	v_mul_f32_e32 v124, v106, v127
	v_fma_f32 v125, -v126, v124, v106
	v_pk_add_f32 v[118:119], v[118:119], 1.0 op_sel_hi:[1,0]
	v_fmac_f32_e32 v124, v125, v127
	v_div_scale_f32 v125, s[6:7], v119, v119, v108
	v_fma_f32 v106, -v126, v124, v106
	v_rcp_f32_e32 v126, v125
	v_div_fmas_f32 v106, v106, v127, v124
	v_div_fixup_f32 v120, v106, v120, 1.0
	v_pk_mul_f32 v[110:111], v[120:121], v[110:111]
	v_fma_f32 v106, -v125, v126, 1.0
	v_fmac_f32_e32 v126, v106, v126
	v_div_scale_f32 v106, vcc, v108, v119, v108
	v_mul_f32_e32 v120, v106, v126
	v_fma_f32 v121, -v125, v120, v106
	v_fmac_f32_e32 v120, v121, v126
	v_div_scale_f32 v121, s[6:7], v118, v118, v1
	v_rcp_f32_e32 v124, v121
	v_fma_f32 v106, -v125, v120, v106
	v_div_fmas_f32 v106, v106, v126, v120
	v_div_fixup_f32 v119, v106, v119, v108
	v_fma_f32 v106, -v121, v124, 1.0
	v_fmac_f32_e32 v124, v106, v124
	v_div_scale_f32 v106, vcc, v1, v118, v1
	v_mul_f32_e32 v108, v106, v124
	v_fma_f32 v120, -v121, v108, v106
	v_fmac_f32_e32 v108, v120, v124
	v_fma_f32 v106, -v121, v108, v106
	v_div_fmas_f32 v106, v106, v124, v108
	v_div_fixup_f32 v118, v106, v118, v1
	v_add_f32_e32 v1, v98, v182
	v_mul_f32_e32 v1, 0xbfb8aa3b, v1
	v_exp_f32_e32 v98, v1
	v_add_f32_e32 v1, v99, v183
	v_mul_f32_e32 v1, 0xbfb8aa3b, v1
	v_exp_f32_e32 v99, v1
	v_lshlrev_b32_e32 v1, 16, v109
	v_and_b32_e32 v108, 0xffff0000, v109
	v_pk_mul_f32 v[110:111], v[118:119], v[110:111]
	v_pk_add_f32 v[98:99], v[98:99], 1.0 op_sel_hi:[1,0]
	v_mul_f32_e32 v102, 0xbfb8aa3b, v1
	v_div_scale_f32 v103, s[6:7], v99, v99, 1.0
	v_rcp_f32_e32 v109, v103
	v_exp_f32_e32 v102, v102
	v_lshlrev_b32_e32 v106, 16, v107
	v_and_b32_e32 v107, 0xffff0000, v107
	v_fma_f32 v118, -v103, v109, 1.0
	v_fmac_f32_e32 v109, v118, v109
	v_div_scale_f32 v118, vcc, 1.0, v99, 1.0
	v_mul_f32_e32 v119, v118, v109
	v_fma_f32 v120, -v103, v119, v118
	v_fmac_f32_e32 v119, v120, v109
	v_fma_f32 v103, -v103, v119, v118
	v_div_scale_f32 v118, s[6:7], v98, v98, 1.0
	v_rcp_f32_e32 v120, v118
	v_div_fmas_f32 v103, v103, v109, v119
	v_div_fixup_f32 v99, v103, v99, 1.0
	v_div_scale_f32 v109, vcc, 1.0, v98, 1.0
	v_fma_f32 v103, -v118, v120, 1.0
	v_fmac_f32_e32 v120, v103, v120
	v_mul_f32_e32 v103, 0xbfb8aa3b, v108
	v_exp_f32_e32 v103, v103
	v_mul_f32_e32 v119, v109, v120
	v_fma_f32 v121, -v118, v119, v109
	v_fmac_f32_e32 v119, v121, v120
	v_pk_add_f32 v[102:103], v[102:103], 1.0 op_sel_hi:[1,0]
	v_fma_f32 v109, -v118, v119, v109
	v_div_scale_f32 v118, s[6:7], v103, v103, v108
	v_rcp_f32_e32 v121, v118
	v_div_fmas_f32 v109, v109, v120, v119
	v_div_fixup_f32 v98, v109, v98, 1.0
	v_pk_mul_f32 v[98:99], v[98:99], v[106:107]
	v_fma_f32 v106, -v118, v121, 1.0
	v_fmac_f32_e32 v121, v106, v121
	v_div_scale_f32 v106, vcc, v108, v103, v108
	v_mul_f32_e32 v107, v106, v121
	v_fma_f32 v109, -v118, v107, v106
	v_fmac_f32_e32 v107, v109, v121
	v_div_scale_f32 v109, s[6:7], v102, v102, v1
	v_fma_f32 v106, -v118, v107, v106
	v_rcp_f32_e32 v118, v109
	v_div_fmas_f32 v106, v106, v121, v107
	v_div_fixup_f32 v103, v106, v103, v108
	v_fma_f32 v106, -v109, v118, 1.0
	v_fmac_f32_e32 v118, v106, v118
	v_div_scale_f32 v106, vcc, v1, v102, v1
	v_mul_f32_e32 v107, v106, v118
	v_fma_f32 v108, -v109, v107, v106
	v_fmac_f32_e32 v107, v108, v118
	v_fma_f32 v106, -v109, v107, v106
	v_div_fmas_f32 v106, v106, v118, v107
	v_div_fixup_f32 v102, v106, v102, v1
	v_pk_mul_f32 v[98:99], v[102:103], v[98:99]
	v_cvt_pk_bf16_f32 v102, v110, v111
	v_cvt_pk_bf16_f32 v103, v98, v99
	v_lshl_add_u64 v[98:99], s[24:25], 0, v[104:105]
	v_lshl_add_u64 v[98:99], v[98:99], 0, v[136:137]
	global_store_dwordx2 v[98:99], v[102:103], off
	s_waitcnt vmcnt(3)
	v_lshlrev_b32_e32 v106, 16, v122
	v_and_b32_e32 v107, 0xffff0000, v122
	s_waitcnt vmcnt(1)
	v_add_f32_e32 v1, v92, v184
	v_mul_f32_e32 v1, 0xbfb8aa3b, v1
	v_exp_f32_e32 v92, v1
	v_add_f32_e32 v1, v93, v185
	v_mul_f32_e32 v1, 0xbfb8aa3b, v1
	v_exp_f32_e32 v93, v1
	v_lshlrev_b32_e32 v1, 16, v96
	v_and_b32_e32 v96, 0xffff0000, v96
	v_mul_f32_e32 v102, 0xbfb8aa3b, v1
	v_pk_add_f32 v[92:93], v[92:93], 1.0 op_sel_hi:[1,0]
	v_exp_f32_e32 v102, v102
	v_div_scale_f32 v103, s[6:7], v93, v93, 1.0
	v_rcp_f32_e32 v108, v103
	s_nop 0
	v_fma_f32 v109, -v103, v108, 1.0
	v_fmac_f32_e32 v108, v109, v108
	v_div_scale_f32 v109, vcc, 1.0, v93, 1.0
	v_mul_f32_e32 v110, v109, v108
	v_fma_f32 v111, -v103, v110, v109
	v_fmac_f32_e32 v110, v111, v108
	v_fma_f32 v103, -v103, v110, v109
	v_div_scale_f32 v109, s[6:7], v92, v92, 1.0
	v_rcp_f32_e32 v111, v109
	v_div_fmas_f32 v103, v103, v108, v110
	v_div_fixup_f32 v93, v103, v93, 1.0
	v_div_scale_f32 v108, vcc, 1.0, v92, 1.0
	v_fma_f32 v103, -v109, v111, 1.0
	v_fmac_f32_e32 v111, v103, v111
	v_mul_f32_e32 v103, 0xbfb8aa3b, v96
	v_exp_f32_e32 v103, v103
	v_mul_f32_e32 v110, v108, v111
	v_fma_f32 v118, -v109, v110, v108
	v_fmac_f32_e32 v110, v118, v111
	v_pk_add_f32 v[102:103], v[102:103], 1.0 op_sel_hi:[1,0]
	v_fma_f32 v108, -v109, v110, v108
	v_div_scale_f32 v109, s[6:7], v103, v103, v96
	v_rcp_f32_e32 v118, v109
	v_div_fmas_f32 v108, v108, v111, v110
	v_div_fixup_f32 v92, v108, v92, 1.0
	v_pk_mul_f32 v[92:93], v[92:93], v[106:107]
	v_fma_f32 v106, -v109, v118, 1.0
	v_fmac_f32_e32 v118, v106, v118
	v_div_scale_f32 v106, vcc, v96, v103, v96
	v_mul_f32_e32 v107, v106, v118
	v_fma_f32 v108, -v109, v107, v106
	v_fmac_f32_e32 v107, v108, v118
	v_div_scale_f32 v108, s[6:7], v102, v102, v1
	v_fma_f32 v106, -v109, v107, v106
	v_rcp_f32_e32 v109, v108
	v_div_fmas_f32 v106, v106, v118, v107
	v_div_fixup_f32 v103, v106, v103, v96
	v_fma_f32 v96, -v108, v109, 1.0
	v_fmac_f32_e32 v109, v96, v109
	v_div_scale_f32 v96, vcc, v1, v102, v1
	v_mul_f32_e32 v106, v96, v109
	v_fma_f32 v107, -v108, v106, v96
	v_fmac_f32_e32 v106, v107, v109
	v_fma_f32 v96, -v108, v106, v96
	v_div_fmas_f32 v96, v96, v109, v106
	v_div_fixup_f32 v102, v96, v102, v1
	v_add_f32_e32 v1, v94, v186
	v_mul_f32_e32 v1, 0xbfb8aa3b, v1
	v_exp_f32_e32 v94, v1
	v_add_f32_e32 v1, v95, v187
	v_mul_f32_e32 v1, 0xbfb8aa3b, v1
	v_exp_f32_e32 v95, v1
	v_lshlrev_b32_e32 v1, 16, v97
	v_and_b32_e32 v104, 0xffff0000, v97
	v_mul_f32_e32 v96, 0xbfb8aa3b, v1
	v_pk_add_f32 v[94:95], v[94:95], 1.0 op_sel_hi:[1,0]
	v_exp_f32_e32 v96, v96
	v_div_scale_f32 v97, s[6:7], v95, v95, 1.0
	v_rcp_f32_e32 v105, v97
	v_pk_mul_f32 v[92:93], v[102:103], v[92:93]
	v_lshlrev_b32_e32 v102, 16, v123
	v_and_b32_e32 v103, 0xffff0000, v123
	v_fma_f32 v106, -v97, v105, 1.0
	v_fmac_f32_e32 v105, v106, v105
	v_div_scale_f32 v106, vcc, 1.0, v95, 1.0
	v_mul_f32_e32 v107, v106, v105
	v_fma_f32 v108, -v97, v107, v106
	v_fmac_f32_e32 v107, v108, v105
	v_fma_f32 v97, -v97, v107, v106
	v_div_scale_f32 v106, s[6:7], v94, v94, 1.0
	v_rcp_f32_e32 v108, v106
	v_div_fmas_f32 v97, v97, v105, v107
	v_div_fixup_f32 v95, v97, v95, 1.0
	v_div_scale_f32 v105, vcc, 1.0, v94, 1.0
	v_fma_f32 v97, -v106, v108, 1.0
	v_fmac_f32_e32 v108, v97, v108
	v_mul_f32_e32 v97, 0xbfb8aa3b, v104
	v_exp_f32_e32 v97, v97
	v_mul_f32_e32 v107, v105, v108
	v_fma_f32 v109, -v106, v107, v105
	v_fmac_f32_e32 v107, v109, v108
	v_pk_add_f32 v[96:97], v[96:97], 1.0 op_sel_hi:[1,0]
	v_fma_f32 v105, -v106, v107, v105
	v_div_scale_f32 v106, s[6:7], v97, v97, v104
	v_rcp_f32_e32 v109, v106
	v_div_fmas_f32 v105, v105, v108, v107
	v_div_fixup_f32 v94, v105, v94, 1.0
	v_pk_mul_f32 v[94:95], v[94:95], v[102:103]
	v_fma_f32 v102, -v106, v109, 1.0
	v_fmac_f32_e32 v109, v102, v109
	v_div_scale_f32 v102, vcc, v104, v97, v104
	v_mul_f32_e32 v103, v102, v109
	v_fma_f32 v105, -v106, v103, v102
	v_fmac_f32_e32 v103, v105, v109
	v_div_scale_f32 v105, s[6:7], v96, v96, v1
	v_fma_f32 v102, -v106, v103, v102
	v_rcp_f32_e32 v106, v105
	v_div_fmas_f32 v102, v102, v109, v103
	v_div_fixup_f32 v97, v102, v97, v104
	v_cvt_pk_bf16_f32 v92, v92, v93
	v_fma_f32 v102, -v105, v106, 1.0
	v_fmac_f32_e32 v106, v102, v106
	v_div_scale_f32 v102, vcc, v1, v96, v1
	v_mul_f32_e32 v103, v102, v106
	v_fma_f32 v104, -v105, v103, v102
	v_fmac_f32_e32 v103, v104, v106
	v_fma_f32 v102, -v105, v103, v102
	v_div_fmas_f32 v102, v102, v106, v103
	v_div_fixup_f32 v96, v102, v96, v1
	v_pk_mul_f32 v[94:95], v[96:97], v[94:95]
	v_and_b32_e32 v102, 0xffff0000, v114
	v_cvt_pk_bf16_f32 v93, v94, v95
	global_store_dwordx2 v[98:99], v[92:93], off offset:32
	v_lshlrev_b32_e32 v96, 16, v116
	v_and_b32_e32 v97, 0xffff0000, v116
	s_waitcnt vmcnt(2)
	v_add_f32_e32 v1, v88, v188
	v_mul_f32_e32 v1, 0xbfb8aa3b, v1
	v_exp_f32_e32 v88, v1
	v_add_f32_e32 v1, v89, v189
	v_mul_f32_e32 v1, 0xbfb8aa3b, v1
	v_exp_f32_e32 v89, v1
	v_lshlrev_b32_e32 v1, 16, v114
	v_mul_f32_e32 v92, 0xbfb8aa3b, v1
	v_exp_f32_e32 v92, v92
	v_pk_add_f32 v[88:89], v[88:89], 1.0 op_sel_hi:[1,0]
	s_nop 0
	v_div_scale_f32 v93, s[6:7], v89, v89, 1.0
	v_rcp_f32_e32 v103, v93
	s_nop 0
	v_fma_f32 v104, -v93, v103, 1.0
	v_fmac_f32_e32 v103, v104, v103
	v_div_scale_f32 v104, vcc, 1.0, v89, 1.0
	v_mul_f32_e32 v105, v104, v103
	v_fma_f32 v106, -v93, v105, v104
	v_fmac_f32_e32 v105, v106, v103
	v_fma_f32 v93, -v93, v105, v104
	v_div_scale_f32 v104, s[6:7], v88, v88, 1.0
	v_rcp_f32_e32 v106, v104
	v_div_fmas_f32 v93, v93, v103, v105
	v_div_fixup_f32 v89, v93, v89, 1.0
	v_div_scale_f32 v103, vcc, 1.0, v88, 1.0
	v_fma_f32 v93, -v104, v106, 1.0
	v_fmac_f32_e32 v106, v93, v106
	v_mul_f32_e32 v93, 0xbfb8aa3b, v102
	v_exp_f32_e32 v93, v93
	v_mul_f32_e32 v105, v103, v106
	v_fma_f32 v107, -v104, v105, v103
	v_fmac_f32_e32 v105, v107, v106
	v_pk_add_f32 v[92:93], v[92:93], 1.0 op_sel_hi:[1,0]
	v_fma_f32 v103, -v104, v105, v103
	v_div_scale_f32 v104, s[6:7], v93, v93, v102
	v_rcp_f32_e32 v107, v104
	v_div_fmas_f32 v103, v103, v106, v105
	v_div_fixup_f32 v88, v103, v88, 1.0
	v_pk_mul_f32 v[88:89], v[88:89], v[96:97]
	v_fma_f32 v96, -v104, v107, 1.0
	v_fmac_f32_e32 v107, v96, v107
	v_div_scale_f32 v96, vcc, v102, v93, v102
	v_mul_f32_e32 v97, v96, v107
	v_fma_f32 v103, -v104, v97, v96
	v_fmac_f32_e32 v97, v103, v107
	v_div_scale_f32 v103, s[6:7], v92, v92, v1
	v_fma_f32 v96, -v104, v97, v96
	v_rcp_f32_e32 v104, v103
	v_div_fmas_f32 v96, v96, v107, v97
	v_div_fixup_f32 v93, v96, v93, v102
	v_fma_f32 v96, -v103, v104, 1.0
	v_fmac_f32_e32 v104, v96, v104
	v_div_scale_f32 v96, vcc, v1, v92, v1
	v_mul_f32_e32 v97, v96, v104
	v_fma_f32 v102, -v103, v97, v96
	v_fmac_f32_e32 v97, v102, v104
	v_fma_f32 v96, -v103, v97, v96
	v_div_fmas_f32 v96, v96, v104, v97
	v_div_fixup_f32 v92, v96, v92, v1
	v_add_f32_e32 v1, v90, v190
	v_mul_f32_e32 v1, 0xbfb8aa3b, v1
	v_exp_f32_e32 v90, v1
	v_add_f32_e32 v1, v91, v191
	v_mul_f32_e32 v1, 0xbfb8aa3b, v1
	v_exp_f32_e32 v91, v1
	v_pk_mul_f32 v[88:89], v[92:93], v[88:89]
	v_lshlrev_b32_e32 v1, 16, v115
	v_and_b32_e32 v96, 0xffff0000, v115
	v_pk_add_f32 v[90:91], v[90:91], 1.0 op_sel_hi:[1,0]
	v_mul_f32_e32 v92, 0xbfb8aa3b, v1
	v_div_scale_f32 v93, s[6:7], v91, v91, 1.0
	v_rcp_f32_e32 v97, v93
	v_exp_f32_e32 v92, v92
	v_lshlrev_b32_e32 v94, 16, v117
	v_and_b32_e32 v95, 0xffff0000, v117
	v_fma_f32 v102, -v93, v97, 1.0
	v_fmac_f32_e32 v97, v102, v97
	v_div_scale_f32 v102, vcc, 1.0, v91, 1.0
	v_mul_f32_e32 v103, v102, v97
	v_fma_f32 v104, -v93, v103, v102
	v_fmac_f32_e32 v103, v104, v97
	v_fma_f32 v93, -v93, v103, v102
	v_div_scale_f32 v102, s[6:7], v90, v90, 1.0
	v_rcp_f32_e32 v104, v102
	v_div_fmas_f32 v93, v93, v97, v103
	v_div_fixup_f32 v91, v93, v91, 1.0
	v_div_scale_f32 v97, vcc, 1.0, v90, 1.0
	v_fma_f32 v93, -v102, v104, 1.0
	v_fmac_f32_e32 v104, v93, v104
	v_mul_f32_e32 v93, 0xbfb8aa3b, v96
	v_exp_f32_e32 v93, v93
	v_mul_f32_e32 v103, v97, v104
	v_fma_f32 v105, -v102, v103, v97
	v_fmac_f32_e32 v103, v105, v104
	v_pk_add_f32 v[92:93], v[92:93], 1.0 op_sel_hi:[1,0]
	v_fma_f32 v97, -v102, v103, v97
	v_div_scale_f32 v102, s[6:7], v93, v93, v96
	v_rcp_f32_e32 v105, v102
	v_div_fmas_f32 v97, v97, v104, v103
	v_div_fixup_f32 v90, v97, v90, 1.0
	v_pk_mul_f32 v[90:91], v[90:91], v[94:95]
	v_fma_f32 v94, -v102, v105, 1.0
	v_fmac_f32_e32 v105, v94, v105
	v_div_scale_f32 v94, vcc, v96, v93, v96
	v_mul_f32_e32 v95, v94, v105
	v_fma_f32 v97, -v102, v95, v94
	v_fmac_f32_e32 v95, v97, v105
	v_div_scale_f32 v97, s[6:7], v92, v92, v1
	v_fma_f32 v94, -v102, v95, v94
	v_rcp_f32_e32 v102, v97
	v_div_fmas_f32 v94, v94, v105, v95
	v_div_fixup_f32 v93, v94, v93, v96
	v_cvt_pk_bf16_f32 v88, v88, v89
	v_fma_f32 v94, -v97, v102, 1.0
	v_fmac_f32_e32 v102, v94, v102
	v_div_scale_f32 v94, vcc, v1, v92, v1
	v_mul_f32_e32 v95, v94, v102
	v_fma_f32 v96, -v97, v95, v94
	v_fmac_f32_e32 v95, v96, v102
	v_fma_f32 v94, -v97, v95, v94
	v_div_fmas_f32 v94, v94, v102, v95
	v_div_fixup_f32 v92, v94, v92, v1
	v_pk_mul_f32 v[90:91], v[92:93], v[90:91]
	v_lshlrev_b32_e32 v92, 16, v100
	v_cvt_pk_bf16_f32 v89, v90, v91
	global_store_dwordx2 v[98:99], v[88:89], off offset:256
	v_and_b32_e32 v93, 0xffff0000, v100
	v_and_b32_e32 v94, 0xffff0000, v112
	s_waitcnt vmcnt(3)
	v_add_f32_e32 v1, v84, v192
	v_mul_f32_e32 v1, 0xbfb8aa3b, v1
	v_exp_f32_e32 v84, v1
	v_add_f32_e32 v1, v85, v193
	v_mul_f32_e32 v1, 0xbfb8aa3b, v1
	v_exp_f32_e32 v85, v1
	v_lshlrev_b32_e32 v1, 16, v112
	v_mul_f32_e32 v88, 0xbfb8aa3b, v1
	v_exp_f32_e32 v88, v88
	v_pk_add_f32 v[84:85], v[84:85], 1.0 op_sel_hi:[1,0]
	s_nop 0
	v_div_scale_f32 v89, s[6:7], v85, v85, 1.0
	v_rcp_f32_e32 v95, v89
	s_nop 0
	v_fma_f32 v96, -v89, v95, 1.0
	v_fmac_f32_e32 v95, v96, v95
	v_div_scale_f32 v96, vcc, 1.0, v85, 1.0
	v_mul_f32_e32 v97, v96, v95
	v_fma_f32 v100, -v89, v97, v96
	v_fmac_f32_e32 v97, v100, v95
	v_fma_f32 v89, -v89, v97, v96
	v_div_scale_f32 v96, s[6:7], v84, v84, 1.0
	v_rcp_f32_e32 v100, v96
	v_div_fmas_f32 v89, v89, v95, v97
	v_div_fixup_f32 v85, v89, v85, 1.0
	v_div_scale_f32 v95, vcc, 1.0, v84, 1.0
	v_fma_f32 v89, -v96, v100, 1.0
	v_fmac_f32_e32 v100, v89, v100
	v_mul_f32_e32 v89, 0xbfb8aa3b, v94
	v_exp_f32_e32 v89, v89
	v_mul_f32_e32 v97, v95, v100
	v_fma_f32 v102, -v96, v97, v95
	v_fmac_f32_e32 v97, v102, v100
	v_pk_add_f32 v[88:89], v[88:89], 1.0 op_sel_hi:[1,0]
	v_fma_f32 v95, -v96, v97, v95
	v_div_scale_f32 v96, s[6:7], v89, v89, v94
	v_rcp_f32_e32 v102, v96
	v_div_fmas_f32 v95, v95, v100, v97
	v_div_fixup_f32 v84, v95, v84, 1.0
	v_pk_mul_f32 v[84:85], v[84:85], v[92:93]
	v_fma_f32 v92, -v96, v102, 1.0
	v_fmac_f32_e32 v102, v92, v102
	v_div_scale_f32 v92, vcc, v94, v89, v94
	v_mul_f32_e32 v93, v92, v102
	v_fma_f32 v95, -v96, v93, v92
	v_fmac_f32_e32 v93, v95, v102
	v_div_scale_f32 v95, s[6:7], v88, v88, v1
	v_fma_f32 v92, -v96, v93, v92
	v_rcp_f32_e32 v96, v95
	v_div_fmas_f32 v92, v92, v102, v93
	v_div_fixup_f32 v89, v92, v89, v94
	v_fma_f32 v92, -v95, v96, 1.0
	v_fmac_f32_e32 v96, v92, v96
	v_div_scale_f32 v92, vcc, v1, v88, v1
	v_mul_f32_e32 v93, v92, v96
	v_fma_f32 v94, -v95, v93, v92
	v_fmac_f32_e32 v93, v94, v96
	v_fma_f32 v92, -v95, v93, v92
	v_div_fmas_f32 v92, v92, v96, v93
	v_div_fixup_f32 v88, v92, v88, v1
	v_add_f32_e32 v1, v86, v194
	v_mul_f32_e32 v1, 0xbfb8aa3b, v1
	v_exp_f32_e32 v86, v1
	v_add_f32_e32 v1, v87, v195
	v_mul_f32_e32 v1, 0xbfb8aa3b, v1
	v_exp_f32_e32 v87, v1
	v_pk_mul_f32 v[84:85], v[88:89], v[84:85]
	v_lshlrev_b32_e32 v1, 16, v113
	v_and_b32_e32 v92, 0xffff0000, v113
	v_pk_add_f32 v[86:87], v[86:87], 1.0 op_sel_hi:[1,0]
	v_mul_f32_e32 v88, 0xbfb8aa3b, v1
	v_div_scale_f32 v89, s[6:7], v87, v87, 1.0
	v_rcp_f32_e32 v93, v89
	v_exp_f32_e32 v88, v88
	v_lshlrev_b32_e32 v90, 16, v101
	v_and_b32_e32 v91, 0xffff0000, v101
	v_fma_f32 v94, -v89, v93, 1.0
	v_fmac_f32_e32 v93, v94, v93
	v_div_scale_f32 v94, vcc, 1.0, v87, 1.0
	v_mul_f32_e32 v95, v94, v93
	v_fma_f32 v96, -v89, v95, v94
	v_fmac_f32_e32 v95, v96, v93
	v_fma_f32 v89, -v89, v95, v94
	v_div_scale_f32 v94, s[6:7], v86, v86, 1.0
	v_rcp_f32_e32 v96, v94
	v_div_fmas_f32 v89, v89, v93, v95
	v_div_fixup_f32 v87, v89, v87, 1.0
	v_div_scale_f32 v93, vcc, 1.0, v86, 1.0
	v_fma_f32 v89, -v94, v96, 1.0
	v_fmac_f32_e32 v96, v89, v96
	v_mul_f32_e32 v89, 0xbfb8aa3b, v92
	v_exp_f32_e32 v89, v89
	v_mul_f32_e32 v95, v93, v96
	v_fma_f32 v97, -v94, v95, v93
	v_fmac_f32_e32 v95, v97, v96
	v_pk_add_f32 v[88:89], v[88:89], 1.0 op_sel_hi:[1,0]
	v_fma_f32 v93, -v94, v95, v93
	v_div_scale_f32 v94, s[6:7], v89, v89, v92
	v_rcp_f32_e32 v97, v94
	v_div_fmas_f32 v93, v93, v96, v95
	v_div_fixup_f32 v86, v93, v86, 1.0
	v_pk_mul_f32 v[86:87], v[86:87], v[90:91]
	v_fma_f32 v90, -v94, v97, 1.0
	v_fmac_f32_e32 v97, v90, v97
	v_div_scale_f32 v90, vcc, v92, v89, v92
	v_mul_f32_e32 v91, v90, v97
	v_fma_f32 v93, -v94, v91, v90
	v_fmac_f32_e32 v91, v93, v97
	v_div_scale_f32 v93, s[6:7], v88, v88, v1
	v_fma_f32 v90, -v94, v91, v90
	v_rcp_f32_e32 v94, v93
	v_div_fmas_f32 v90, v90, v97, v91
	v_div_fixup_f32 v89, v90, v89, v92
	v_cvt_pk_bf16_f32 v84, v84, v85
	v_fma_f32 v90, -v93, v94, 1.0
	v_fmac_f32_e32 v94, v90, v94
	v_div_scale_f32 v90, vcc, v1, v88, v1
	v_mul_f32_e32 v91, v90, v94
	v_fma_f32 v92, -v93, v91, v90
	v_fmac_f32_e32 v91, v92, v94
	v_fma_f32 v90, -v93, v91, v90
	v_div_fmas_f32 v90, v90, v94, v91
	v_div_fixup_f32 v88, v90, v88, v1
	v_pk_mul_f32 v[86:87], v[88:89], v[86:87]
	v_or_b32_e32 v88, 48, v138
	v_cvt_pk_bf16_f32 v85, v86, v87
	global_store_dwordx2 v[98:99], v[84:85], off offset:288
	v_ashrrev_i32_e32 v89, 31, v88
	v_lshlrev_b64 v[90:91], 13, v[88:89]
	v_lshl_add_u64 v[90:91], s[26:27], 0, v[90:91]
	v_lshl_add_u64 v[96:97], v[90:91], 0, v[136:137]
	global_load_dwordx2 v[92:93], v[96:97], off offset:3072
	v_mad_i64_i32 v[90:91], s[6:7], v88, s81, v[140:141]
	v_lshl_add_u64 v[94:95], v[90:91], 0, v[136:137]
	global_load_dwordx2 v[90:91], v[94:95], off
	v_lshlrev_b64 v[88:89], 12, v[88:89]
	s_waitcnt vmcnt(6)
	v_add_f32_e32 v1, v80, v180
	v_mul_f32_e32 v1, 0xbfb8aa3b, v1
	v_exp_f32_e32 v84, v1
	v_add_f32_e32 v1, v81, v181
	v_mul_f32_e32 v1, 0xbfb8aa3b, v1
	v_exp_f32_e32 v85, v1
	s_waitcnt vmcnt(1)
	v_lshlrev_b32_e32 v1, 16, v92
	v_mul_f32_e32 v100, 0xbfb8aa3b, v1
	global_load_dwordx2 v[80:81], v[96:97], off offset:3104
	global_load_dwordx2 v[98:99], v[96:97], off offset:3328
	s_nop 0
	global_load_dwordx2 v[96:97], v[96:97], off offset:3360
	v_pk_add_f32 v[104:105], v[84:85], 1.0 op_sel_hi:[1,0]
	v_exp_f32_e32 v102, v100
	v_div_scale_f32 v103, s[6:7], v105, v105, 1.0
	v_rcp_f32_e32 v108, v103
	global_load_dwordx2 v[106:107], v[94:95], off offset:32
	global_load_dwordx2 v[100:101], v[94:95], off offset:256
	global_load_dwordx2 v[84:85], v[94:95], off offset:288
	s_waitcnt vmcnt(6)
	v_lshlrev_b32_e32 v94, 16, v90
	v_and_b32_e32 v95, 0xffff0000, v90
	v_fma_f32 v90, -v103, v108, 1.0
	v_fmac_f32_e32 v108, v90, v108
	v_div_scale_f32 v90, vcc, 1.0, v105, 1.0
	v_mul_f32_e32 v109, v90, v108
	v_fma_f32 v110, -v103, v109, v90
	v_fmac_f32_e32 v109, v110, v108
	v_div_scale_f32 v110, s[6:7], v104, v104, 1.0
	v_rcp_f32_e32 v111, v110
	v_and_b32_e32 v92, 0xffff0000, v92
	v_fma_f32 v90, -v103, v109, v90
	v_mul_f32_e32 v103, 0xbfb8aa3b, v92
	v_div_fmas_f32 v90, v90, v108, v109
	v_exp_f32_e32 v103, v103
	v_div_fixup_f32 v105, v90, v105, 1.0
	v_fma_f32 v90, -v110, v111, 1.0
	v_fmac_f32_e32 v111, v90, v111
	v_div_scale_f32 v90, vcc, 1.0, v104, 1.0
	v_mul_f32_e32 v108, v90, v111
	v_fma_f32 v109, -v110, v108, v90
	v_pk_add_f32 v[102:103], v[102:103], 1.0 op_sel_hi:[1,0]
	v_fmac_f32_e32 v108, v109, v111
	v_div_scale_f32 v109, s[6:7], v103, v103, v92
	v_fma_f32 v90, -v110, v108, v90
	v_rcp_f32_e32 v110, v109
	v_div_fmas_f32 v90, v90, v111, v108
	v_div_fixup_f32 v104, v90, v104, 1.0
	v_pk_mul_f32 v[94:95], v[104:105], v[94:95]
	v_fma_f32 v90, -v109, v110, 1.0
	v_fmac_f32_e32 v110, v90, v110
	v_div_scale_f32 v90, vcc, v92, v103, v92
	v_mul_f32_e32 v104, v90, v110
	v_fma_f32 v105, -v109, v104, v90
	v_fmac_f32_e32 v104, v105, v110
	v_div_scale_f32 v105, s[6:7], v102, v102, v1
	v_rcp_f32_e32 v108, v105
	v_fma_f32 v90, -v109, v104, v90
	v_div_fmas_f32 v90, v90, v110, v104
	v_div_fixup_f32 v103, v90, v103, v92
	v_fma_f32 v90, -v105, v108, 1.0
	v_fmac_f32_e32 v108, v90, v108
	v_div_scale_f32 v90, vcc, v1, v102, v1
	v_mul_f32_e32 v92, v90, v108
	v_fma_f32 v104, -v105, v92, v90
	v_fmac_f32_e32 v92, v104, v108
	v_fma_f32 v90, -v105, v92, v90
	v_div_fmas_f32 v90, v90, v108, v92
	v_div_fixup_f32 v102, v90, v102, v1
	v_add_f32_e32 v1, v82, v182
	v_mul_f32_e32 v1, 0xbfb8aa3b, v1
	v_exp_f32_e32 v82, v1
	v_add_f32_e32 v1, v83, v183
	v_mul_f32_e32 v1, 0xbfb8aa3b, v1
	v_exp_f32_e32 v83, v1
	v_lshlrev_b32_e32 v1, 16, v93
	v_and_b32_e32 v92, 0xffff0000, v93
	v_pk_mul_f32 v[94:95], v[102:103], v[94:95]
	v_pk_add_f32 v[82:83], v[82:83], 1.0 op_sel_hi:[1,0]
	v_mul_f32_e32 v86, 0xbfb8aa3b, v1
	v_div_scale_f32 v87, s[6:7], v83, v83, 1.0
	v_rcp_f32_e32 v93, v87
	v_exp_f32_e32 v86, v86
	v_lshlrev_b32_e32 v90, 16, v91
	v_and_b32_e32 v91, 0xffff0000, v91
	v_fma_f32 v102, -v87, v93, 1.0
	v_fmac_f32_e32 v93, v102, v93
	v_div_scale_f32 v102, vcc, 1.0, v83, 1.0
	v_mul_f32_e32 v103, v102, v93
	v_fma_f32 v104, -v87, v103, v102
	v_fmac_f32_e32 v103, v104, v93
	v_fma_f32 v87, -v87, v103, v102
	v_div_scale_f32 v102, s[6:7], v82, v82, 1.0
	v_rcp_f32_e32 v104, v102
	v_div_fmas_f32 v87, v87, v93, v103
	v_div_fixup_f32 v83, v87, v83, 1.0
	v_div_scale_f32 v93, vcc, 1.0, v82, 1.0
	v_fma_f32 v87, -v102, v104, 1.0
	v_fmac_f32_e32 v104, v87, v104
	v_mul_f32_e32 v87, 0xbfb8aa3b, v92
	v_exp_f32_e32 v87, v87
	v_mul_f32_e32 v103, v93, v104
	v_fma_f32 v105, -v102, v103, v93
	v_fmac_f32_e32 v103, v105, v104
	v_pk_add_f32 v[86:87], v[86:87], 1.0 op_sel_hi:[1,0]
	v_fma_f32 v93, -v102, v103, v93
	v_div_scale_f32 v102, s[6:7], v87, v87, v92
	v_rcp_f32_e32 v105, v102
	v_div_fmas_f32 v93, v93, v104, v103
	v_div_fixup_f32 v82, v93, v82, 1.0
	v_pk_mul_f32 v[82:83], v[82:83], v[90:91]
	v_fma_f32 v90, -v102, v105, 1.0
	v_fmac_f32_e32 v105, v90, v105
	v_div_scale_f32 v90, vcc, v92, v87, v92
	v_mul_f32_e32 v91, v90, v105
	v_fma_f32 v93, -v102, v91, v90
	v_fmac_f32_e32 v91, v93, v105
	v_div_scale_f32 v93, s[6:7], v86, v86, v1
	v_fma_f32 v90, -v102, v91, v90
	v_rcp_f32_e32 v102, v93
	v_div_fmas_f32 v90, v90, v105, v91
	v_div_fixup_f32 v87, v90, v87, v92
	v_fma_f32 v90, -v93, v102, 1.0
	v_fmac_f32_e32 v102, v90, v102
	v_div_scale_f32 v90, vcc, v1, v86, v1
	v_mul_f32_e32 v91, v90, v102
	v_fma_f32 v92, -v93, v91, v90
	v_fmac_f32_e32 v91, v92, v102
	v_fma_f32 v90, -v93, v91, v90
	v_div_fmas_f32 v90, v90, v102, v91
	v_div_fixup_f32 v86, v90, v86, v1
	v_pk_mul_f32 v[82:83], v[86:87], v[82:83]
	v_cvt_pk_bf16_f32 v86, v94, v95
	v_cvt_pk_bf16_f32 v87, v82, v83
	v_lshl_add_u64 v[82:83], s[24:25], 0, v[88:89]
	v_lshl_add_u64 v[82:83], v[82:83], 0, v[136:137]
	global_store_dwordx2 v[82:83], v[86:87], off
	s_waitcnt vmcnt(3)
	v_lshlrev_b32_e32 v90, 16, v106
	v_and_b32_e32 v91, 0xffff0000, v106
	s_waitcnt vmcnt(1)
	v_add_f32_e32 v1, v76, v184
	v_mul_f32_e32 v1, 0xbfb8aa3b, v1
	v_exp_f32_e32 v76, v1
	v_add_f32_e32 v1, v77, v185
	v_mul_f32_e32 v1, 0xbfb8aa3b, v1
	v_exp_f32_e32 v77, v1
	v_lshlrev_b32_e32 v1, 16, v80
	v_and_b32_e32 v80, 0xffff0000, v80
	v_mul_f32_e32 v86, 0xbfb8aa3b, v1
	v_pk_add_f32 v[76:77], v[76:77], 1.0 op_sel_hi:[1,0]
	v_exp_f32_e32 v86, v86
	v_div_scale_f32 v87, s[6:7], v77, v77, 1.0
	v_rcp_f32_e32 v92, v87
	s_nop 0
	v_fma_f32 v93, -v87, v92, 1.0
	v_fmac_f32_e32 v92, v93, v92
	v_div_scale_f32 v93, vcc, 1.0, v77, 1.0
	v_mul_f32_e32 v94, v93, v92
	v_fma_f32 v95, -v87, v94, v93
	v_fmac_f32_e32 v94, v95, v92
	v_fma_f32 v87, -v87, v94, v93
	v_div_scale_f32 v93, s[6:7], v76, v76, 1.0
	v_rcp_f32_e32 v95, v93
	v_div_fmas_f32 v87, v87, v92, v94
	v_div_fixup_f32 v77, v87, v77, 1.0
	v_div_scale_f32 v92, vcc, 1.0, v76, 1.0
	v_fma_f32 v87, -v93, v95, 1.0
	v_fmac_f32_e32 v95, v87, v95
	v_mul_f32_e32 v87, 0xbfb8aa3b, v80
	v_exp_f32_e32 v87, v87
	v_mul_f32_e32 v94, v92, v95
	v_fma_f32 v102, -v93, v94, v92
	v_fmac_f32_e32 v94, v102, v95
	v_pk_add_f32 v[86:87], v[86:87], 1.0 op_sel_hi:[1,0]
	v_fma_f32 v92, -v93, v94, v92
	v_div_scale_f32 v93, s[6:7], v87, v87, v80
	v_rcp_f32_e32 v102, v93
	v_div_fmas_f32 v92, v92, v95, v94
	v_div_fixup_f32 v76, v92, v76, 1.0
	v_pk_mul_f32 v[76:77], v[76:77], v[90:91]
	v_fma_f32 v90, -v93, v102, 1.0
	v_fmac_f32_e32 v102, v90, v102
	v_div_scale_f32 v90, vcc, v80, v87, v80
	v_mul_f32_e32 v91, v90, v102
	v_fma_f32 v92, -v93, v91, v90
	v_fmac_f32_e32 v91, v92, v102
	v_div_scale_f32 v92, s[6:7], v86, v86, v1
	v_fma_f32 v90, -v93, v91, v90
	v_rcp_f32_e32 v93, v92
	v_div_fmas_f32 v90, v90, v102, v91
	v_div_fixup_f32 v87, v90, v87, v80
	v_fma_f32 v80, -v92, v93, 1.0
	v_fmac_f32_e32 v93, v80, v93
	v_div_scale_f32 v80, vcc, v1, v86, v1
	v_mul_f32_e32 v90, v80, v93
	v_fma_f32 v91, -v92, v90, v80
	v_fmac_f32_e32 v90, v91, v93
	v_fma_f32 v80, -v92, v90, v80
	v_div_fmas_f32 v80, v80, v93, v90
	v_div_fixup_f32 v86, v80, v86, v1
	v_add_f32_e32 v1, v78, v186
	v_mul_f32_e32 v1, 0xbfb8aa3b, v1
	v_exp_f32_e32 v78, v1
	v_add_f32_e32 v1, v79, v187
	v_mul_f32_e32 v1, 0xbfb8aa3b, v1
	v_exp_f32_e32 v79, v1
	v_lshlrev_b32_e32 v1, 16, v81
	v_and_b32_e32 v88, 0xffff0000, v81
	v_mul_f32_e32 v80, 0xbfb8aa3b, v1
	v_pk_add_f32 v[78:79], v[78:79], 1.0 op_sel_hi:[1,0]
	v_exp_f32_e32 v80, v80
	v_div_scale_f32 v81, s[6:7], v79, v79, 1.0
	v_rcp_f32_e32 v89, v81
	v_pk_mul_f32 v[76:77], v[86:87], v[76:77]
	v_lshlrev_b32_e32 v86, 16, v107
	v_and_b32_e32 v87, 0xffff0000, v107
	v_fma_f32 v90, -v81, v89, 1.0
	v_fmac_f32_e32 v89, v90, v89
	v_div_scale_f32 v90, vcc, 1.0, v79, 1.0
	v_mul_f32_e32 v91, v90, v89
	v_fma_f32 v92, -v81, v91, v90
	v_fmac_f32_e32 v91, v92, v89
	v_fma_f32 v81, -v81, v91, v90
	v_div_scale_f32 v90, s[6:7], v78, v78, 1.0
	v_rcp_f32_e32 v92, v90
	v_div_fmas_f32 v81, v81, v89, v91
	v_div_fixup_f32 v79, v81, v79, 1.0
	v_div_scale_f32 v89, vcc, 1.0, v78, 1.0
	v_fma_f32 v81, -v90, v92, 1.0
	v_fmac_f32_e32 v92, v81, v92
	v_mul_f32_e32 v81, 0xbfb8aa3b, v88
	v_exp_f32_e32 v81, v81
	v_mul_f32_e32 v91, v89, v92
	v_fma_f32 v93, -v90, v91, v89
	v_fmac_f32_e32 v91, v93, v92
	v_pk_add_f32 v[80:81], v[80:81], 1.0 op_sel_hi:[1,0]
	v_fma_f32 v89, -v90, v91, v89
	v_div_scale_f32 v90, s[6:7], v81, v81, v88
	v_rcp_f32_e32 v93, v90
	v_div_fmas_f32 v89, v89, v92, v91
	v_div_fixup_f32 v78, v89, v78, 1.0
	v_pk_mul_f32 v[78:79], v[78:79], v[86:87]
	v_fma_f32 v86, -v90, v93, 1.0
	v_fmac_f32_e32 v93, v86, v93
	v_div_scale_f32 v86, vcc, v88, v81, v88
	v_mul_f32_e32 v87, v86, v93
	v_fma_f32 v89, -v90, v87, v86
	v_fmac_f32_e32 v87, v89, v93
	v_div_scale_f32 v89, s[6:7], v80, v80, v1
	v_fma_f32 v86, -v90, v87, v86
	v_rcp_f32_e32 v90, v89
	v_div_fmas_f32 v86, v86, v93, v87
	v_div_fixup_f32 v81, v86, v81, v88
	v_cvt_pk_bf16_f32 v76, v76, v77
	v_fma_f32 v86, -v89, v90, 1.0
	v_fmac_f32_e32 v90, v86, v90
	v_div_scale_f32 v86, vcc, v1, v80, v1
	v_mul_f32_e32 v87, v86, v90
	v_fma_f32 v88, -v89, v87, v86
	v_fmac_f32_e32 v87, v88, v90
	v_fma_f32 v86, -v89, v87, v86
	v_div_fmas_f32 v86, v86, v90, v87
	v_div_fixup_f32 v80, v86, v80, v1
	v_pk_mul_f32 v[78:79], v[80:81], v[78:79]
	v_and_b32_e32 v86, 0xffff0000, v98
	v_cvt_pk_bf16_f32 v77, v78, v79
	global_store_dwordx2 v[82:83], v[76:77], off offset:32
	v_lshlrev_b32_e32 v80, 16, v100
	v_and_b32_e32 v81, 0xffff0000, v100
	s_waitcnt vmcnt(2)
	v_add_f32_e32 v1, v72, v188
	v_mul_f32_e32 v1, 0xbfb8aa3b, v1
	v_exp_f32_e32 v72, v1
	v_add_f32_e32 v1, v73, v189
	v_mul_f32_e32 v1, 0xbfb8aa3b, v1
	v_exp_f32_e32 v73, v1
	v_lshlrev_b32_e32 v1, 16, v98
	v_mul_f32_e32 v76, 0xbfb8aa3b, v1
	v_exp_f32_e32 v76, v76
	v_pk_add_f32 v[72:73], v[72:73], 1.0 op_sel_hi:[1,0]
	s_nop 0
	v_div_scale_f32 v77, s[6:7], v73, v73, 1.0
	v_rcp_f32_e32 v87, v77
	s_nop 0
	v_fma_f32 v88, -v77, v87, 1.0
	v_fmac_f32_e32 v87, v88, v87
	v_div_scale_f32 v88, vcc, 1.0, v73, 1.0
	v_mul_f32_e32 v89, v88, v87
	v_fma_f32 v90, -v77, v89, v88
	v_fmac_f32_e32 v89, v90, v87
	v_fma_f32 v77, -v77, v89, v88
	v_div_scale_f32 v88, s[6:7], v72, v72, 1.0
	v_rcp_f32_e32 v90, v88
	v_div_fmas_f32 v77, v77, v87, v89
	v_div_fixup_f32 v73, v77, v73, 1.0
	v_div_scale_f32 v87, vcc, 1.0, v72, 1.0
	v_fma_f32 v77, -v88, v90, 1.0
	v_fmac_f32_e32 v90, v77, v90
	v_mul_f32_e32 v77, 0xbfb8aa3b, v86
	v_exp_f32_e32 v77, v77
	v_mul_f32_e32 v89, v87, v90
	v_fma_f32 v91, -v88, v89, v87
	v_fmac_f32_e32 v89, v91, v90
	v_pk_add_f32 v[76:77], v[76:77], 1.0 op_sel_hi:[1,0]
	v_fma_f32 v87, -v88, v89, v87
	v_div_scale_f32 v88, s[6:7], v77, v77, v86
	v_rcp_f32_e32 v91, v88
	v_div_fmas_f32 v87, v87, v90, v89
	v_div_fixup_f32 v72, v87, v72, 1.0
	v_pk_mul_f32 v[72:73], v[72:73], v[80:81]
	v_fma_f32 v80, -v88, v91, 1.0
	v_fmac_f32_e32 v91, v80, v91
	v_div_scale_f32 v80, vcc, v86, v77, v86
	v_mul_f32_e32 v81, v80, v91
	v_fma_f32 v87, -v88, v81, v80
	v_fmac_f32_e32 v81, v87, v91
	v_div_scale_f32 v87, s[6:7], v76, v76, v1
	v_fma_f32 v80, -v88, v81, v80
	v_rcp_f32_e32 v88, v87
	v_div_fmas_f32 v80, v80, v91, v81
	v_div_fixup_f32 v77, v80, v77, v86
	v_fma_f32 v80, -v87, v88, 1.0
	v_fmac_f32_e32 v88, v80, v88
	v_div_scale_f32 v80, vcc, v1, v76, v1
	v_mul_f32_e32 v81, v80, v88
	v_fma_f32 v86, -v87, v81, v80
	v_fmac_f32_e32 v81, v86, v88
	v_fma_f32 v80, -v87, v81, v80
	v_div_fmas_f32 v80, v80, v88, v81
	v_div_fixup_f32 v76, v80, v76, v1
	v_add_f32_e32 v1, v74, v190
	v_mul_f32_e32 v1, 0xbfb8aa3b, v1
	v_exp_f32_e32 v74, v1
	v_add_f32_e32 v1, v75, v191
	v_mul_f32_e32 v1, 0xbfb8aa3b, v1
	v_exp_f32_e32 v75, v1
	v_pk_mul_f32 v[72:73], v[76:77], v[72:73]
	v_lshlrev_b32_e32 v1, 16, v99
	v_and_b32_e32 v80, 0xffff0000, v99
	v_pk_add_f32 v[74:75], v[74:75], 1.0 op_sel_hi:[1,0]
	v_mul_f32_e32 v76, 0xbfb8aa3b, v1
	v_div_scale_f32 v77, s[6:7], v75, v75, 1.0
	v_rcp_f32_e32 v81, v77
	v_exp_f32_e32 v76, v76
	v_lshlrev_b32_e32 v78, 16, v101
	v_and_b32_e32 v79, 0xffff0000, v101
	v_fma_f32 v86, -v77, v81, 1.0
	v_fmac_f32_e32 v81, v86, v81
	v_div_scale_f32 v86, vcc, 1.0, v75, 1.0
	v_mul_f32_e32 v87, v86, v81
	v_fma_f32 v88, -v77, v87, v86
	v_fmac_f32_e32 v87, v88, v81
	v_fma_f32 v77, -v77, v87, v86
	v_div_scale_f32 v86, s[6:7], v74, v74, 1.0
	v_rcp_f32_e32 v88, v86
	v_div_fmas_f32 v77, v77, v81, v87
	v_div_fixup_f32 v75, v77, v75, 1.0
	v_div_scale_f32 v81, vcc, 1.0, v74, 1.0
	v_fma_f32 v77, -v86, v88, 1.0
	v_fmac_f32_e32 v88, v77, v88
	v_mul_f32_e32 v77, 0xbfb8aa3b, v80
	v_exp_f32_e32 v77, v77
	v_mul_f32_e32 v87, v81, v88
	v_fma_f32 v89, -v86, v87, v81
	v_fmac_f32_e32 v87, v89, v88
	v_pk_add_f32 v[76:77], v[76:77], 1.0 op_sel_hi:[1,0]
	v_fma_f32 v81, -v86, v87, v81
	v_div_scale_f32 v86, s[6:7], v77, v77, v80
	v_rcp_f32_e32 v89, v86
	v_div_fmas_f32 v81, v81, v88, v87
	v_div_fixup_f32 v74, v81, v74, 1.0
	v_pk_mul_f32 v[74:75], v[74:75], v[78:79]
	v_fma_f32 v78, -v86, v89, 1.0
	v_fmac_f32_e32 v89, v78, v89
	v_div_scale_f32 v78, vcc, v80, v77, v80
	v_mul_f32_e32 v79, v78, v89
	v_fma_f32 v81, -v86, v79, v78
	v_fmac_f32_e32 v79, v81, v89
	v_div_scale_f32 v81, s[6:7], v76, v76, v1
	v_fma_f32 v78, -v86, v79, v78
	v_rcp_f32_e32 v86, v81
	v_div_fmas_f32 v78, v78, v89, v79
	v_div_fixup_f32 v77, v78, v77, v80
	v_cvt_pk_bf16_f32 v72, v72, v73
	v_fma_f32 v78, -v81, v86, 1.0
	v_fmac_f32_e32 v86, v78, v86
	v_div_scale_f32 v78, vcc, v1, v76, v1
	v_mul_f32_e32 v79, v78, v86
	v_fma_f32 v80, -v81, v79, v78
	v_fmac_f32_e32 v79, v80, v86
	v_fma_f32 v78, -v81, v79, v78
	v_div_fmas_f32 v78, v78, v86, v79
	v_div_fixup_f32 v76, v78, v76, v1
	v_pk_mul_f32 v[74:75], v[76:77], v[74:75]
	v_lshlrev_b32_e32 v76, 16, v84
	v_cvt_pk_bf16_f32 v73, v74, v75
	global_store_dwordx2 v[82:83], v[72:73], off offset:256
	v_and_b32_e32 v77, 0xffff0000, v84
	v_and_b32_e32 v78, 0xffff0000, v96
	s_waitcnt vmcnt(3)
	v_add_f32_e32 v1, v68, v192
	v_mul_f32_e32 v1, 0xbfb8aa3b, v1
	v_exp_f32_e32 v68, v1
	v_add_f32_e32 v1, v69, v193
	v_mul_f32_e32 v1, 0xbfb8aa3b, v1
	v_exp_f32_e32 v69, v1
	v_lshlrev_b32_e32 v1, 16, v96
	v_mul_f32_e32 v72, 0xbfb8aa3b, v1
	v_exp_f32_e32 v72, v72
	v_pk_add_f32 v[68:69], v[68:69], 1.0 op_sel_hi:[1,0]
	s_nop 0
	v_div_scale_f32 v73, s[6:7], v69, v69, 1.0
	v_rcp_f32_e32 v79, v73
	s_nop 0
	v_fma_f32 v80, -v73, v79, 1.0
	v_fmac_f32_e32 v79, v80, v79
	v_div_scale_f32 v80, vcc, 1.0, v69, 1.0
	v_mul_f32_e32 v81, v80, v79
	v_fma_f32 v84, -v73, v81, v80
	v_fmac_f32_e32 v81, v84, v79
	v_fma_f32 v73, -v73, v81, v80
	v_div_scale_f32 v80, s[6:7], v68, v68, 1.0
	v_rcp_f32_e32 v84, v80
	v_div_fmas_f32 v73, v73, v79, v81
	v_div_fixup_f32 v69, v73, v69, 1.0
	v_div_scale_f32 v79, vcc, 1.0, v68, 1.0
	v_fma_f32 v73, -v80, v84, 1.0
	v_fmac_f32_e32 v84, v73, v84
	v_mul_f32_e32 v73, 0xbfb8aa3b, v78
	v_exp_f32_e32 v73, v73
	v_mul_f32_e32 v81, v79, v84
	v_fma_f32 v86, -v80, v81, v79
	v_fmac_f32_e32 v81, v86, v84
	v_pk_add_f32 v[72:73], v[72:73], 1.0 op_sel_hi:[1,0]
	v_fma_f32 v79, -v80, v81, v79
	v_div_scale_f32 v80, s[6:7], v73, v73, v78
	v_rcp_f32_e32 v86, v80
	v_div_fmas_f32 v79, v79, v84, v81
	v_div_fixup_f32 v68, v79, v68, 1.0
	v_pk_mul_f32 v[68:69], v[68:69], v[76:77]
	v_fma_f32 v76, -v80, v86, 1.0
	v_fmac_f32_e32 v86, v76, v86
	v_div_scale_f32 v76, vcc, v78, v73, v78
	v_mul_f32_e32 v77, v76, v86
	v_fma_f32 v79, -v80, v77, v76
	v_fmac_f32_e32 v77, v79, v86
	v_div_scale_f32 v79, s[6:7], v72, v72, v1
	v_fma_f32 v76, -v80, v77, v76
	v_rcp_f32_e32 v80, v79
	v_div_fmas_f32 v76, v76, v86, v77
	v_div_fixup_f32 v73, v76, v73, v78
	v_fma_f32 v76, -v79, v80, 1.0
	v_fmac_f32_e32 v80, v76, v80
	v_div_scale_f32 v76, vcc, v1, v72, v1
	v_mul_f32_e32 v77, v76, v80
	v_fma_f32 v78, -v79, v77, v76
	v_fmac_f32_e32 v77, v78, v80
	v_fma_f32 v76, -v79, v77, v76
	v_div_fmas_f32 v76, v76, v80, v77
	v_div_fixup_f32 v72, v76, v72, v1
	v_add_f32_e32 v1, v70, v194
	v_mul_f32_e32 v1, 0xbfb8aa3b, v1
	v_exp_f32_e32 v70, v1
	v_add_f32_e32 v1, v71, v195
	v_mul_f32_e32 v1, 0xbfb8aa3b, v1
	v_exp_f32_e32 v71, v1
	v_pk_mul_f32 v[68:69], v[72:73], v[68:69]
	v_lshlrev_b32_e32 v1, 16, v97
	v_and_b32_e32 v76, 0xffff0000, v97
	v_pk_add_f32 v[70:71], v[70:71], 1.0 op_sel_hi:[1,0]
	v_mul_f32_e32 v72, 0xbfb8aa3b, v1
	v_div_scale_f32 v73, s[6:7], v71, v71, 1.0
	v_rcp_f32_e32 v77, v73
	v_exp_f32_e32 v72, v72
	v_lshlrev_b32_e32 v74, 16, v85
	v_and_b32_e32 v75, 0xffff0000, v85
	v_fma_f32 v78, -v73, v77, 1.0
	v_fmac_f32_e32 v77, v78, v77
	v_div_scale_f32 v78, vcc, 1.0, v71, 1.0
	v_mul_f32_e32 v79, v78, v77
	v_fma_f32 v80, -v73, v79, v78
	v_fmac_f32_e32 v79, v80, v77
	v_fma_f32 v73, -v73, v79, v78
	v_div_scale_f32 v78, s[6:7], v70, v70, 1.0
	v_rcp_f32_e32 v80, v78
	v_div_fmas_f32 v73, v73, v77, v79
	v_div_fixup_f32 v71, v73, v71, 1.0
	v_div_scale_f32 v77, vcc, 1.0, v70, 1.0
	v_fma_f32 v73, -v78, v80, 1.0
	v_fmac_f32_e32 v80, v73, v80
	v_mul_f32_e32 v73, 0xbfb8aa3b, v76
	v_exp_f32_e32 v73, v73
	v_mul_f32_e32 v79, v77, v80
	v_fma_f32 v81, -v78, v79, v77
	v_fmac_f32_e32 v79, v81, v80
	v_pk_add_f32 v[72:73], v[72:73], 1.0 op_sel_hi:[1,0]
	v_fma_f32 v77, -v78, v79, v77
	v_div_scale_f32 v78, s[6:7], v73, v73, v76
	v_rcp_f32_e32 v81, v78
	v_div_fmas_f32 v77, v77, v80, v79
	v_div_fixup_f32 v70, v77, v70, 1.0
	v_pk_mul_f32 v[70:71], v[70:71], v[74:75]
	v_fma_f32 v74, -v78, v81, 1.0
	v_fmac_f32_e32 v81, v74, v81
	v_div_scale_f32 v74, vcc, v76, v73, v76
	v_mul_f32_e32 v75, v74, v81
	v_fma_f32 v77, -v78, v75, v74
	v_fmac_f32_e32 v75, v77, v81
	v_div_scale_f32 v77, s[6:7], v72, v72, v1
	v_fma_f32 v74, -v78, v75, v74
	v_rcp_f32_e32 v78, v77
	v_div_fmas_f32 v74, v74, v81, v75
	v_div_fixup_f32 v73, v74, v73, v76
	v_cvt_pk_bf16_f32 v68, v68, v69
	v_fma_f32 v74, -v77, v78, 1.0
	v_fmac_f32_e32 v78, v74, v78
	v_div_scale_f32 v74, vcc, v1, v72, v1
	v_mul_f32_e32 v75, v74, v78
	v_fma_f32 v76, -v77, v75, v74
	v_fmac_f32_e32 v75, v76, v78
	v_fma_f32 v74, -v77, v75, v74
	v_div_fmas_f32 v74, v74, v78, v75
	v_div_fixup_f32 v72, v74, v72, v1
	v_pk_mul_f32 v[70:71], v[72:73], v[70:71]
	v_add_u32_e32 v72, 0x80, v138
	v_cvt_pk_bf16_f32 v69, v70, v71
	global_store_dwordx2 v[82:83], v[68:69], off offset:288
	v_ashrrev_i32_e32 v73, 31, v72
	v_lshlrev_b64 v[74:75], 13, v[72:73]
	v_lshl_add_u64 v[74:75], s[26:27], 0, v[74:75]
	v_lshl_add_u64 v[80:81], v[74:75], 0, v[136:137]
	global_load_dwordx2 v[76:77], v[80:81], off offset:3072
	v_mad_i64_i32 v[74:75], s[6:7], v72, s81, v[140:141]
	v_lshl_add_u64 v[78:79], v[74:75], 0, v[136:137]
	global_load_dwordx2 v[74:75], v[78:79], off
	v_lshlrev_b64 v[72:73], 12, v[72:73]
	s_waitcnt vmcnt(6)
	v_add_f32_e32 v1, v64, v180
	v_mul_f32_e32 v1, 0xbfb8aa3b, v1
	v_exp_f32_e32 v68, v1
	v_add_f32_e32 v1, v65, v181
	v_mul_f32_e32 v1, 0xbfb8aa3b, v1
	v_exp_f32_e32 v69, v1
	s_waitcnt vmcnt(1)
	v_lshlrev_b32_e32 v1, 16, v76
	v_mul_f32_e32 v84, 0xbfb8aa3b, v1
	global_load_dwordx2 v[64:65], v[80:81], off offset:3104
	global_load_dwordx2 v[82:83], v[80:81], off offset:3328
	s_nop 0
	global_load_dwordx2 v[80:81], v[80:81], off offset:3360
	v_pk_add_f32 v[88:89], v[68:69], 1.0 op_sel_hi:[1,0]
	v_exp_f32_e32 v86, v84
	v_div_scale_f32 v87, s[6:7], v89, v89, 1.0
	v_rcp_f32_e32 v92, v87
	global_load_dwordx2 v[90:91], v[78:79], off offset:32
	global_load_dwordx2 v[84:85], v[78:79], off offset:256
	global_load_dwordx2 v[68:69], v[78:79], off offset:288
	s_waitcnt vmcnt(6)
	v_lshlrev_b32_e32 v78, 16, v74
	v_and_b32_e32 v79, 0xffff0000, v74
	v_fma_f32 v74, -v87, v92, 1.0
	v_fmac_f32_e32 v92, v74, v92
	v_div_scale_f32 v74, vcc, 1.0, v89, 1.0
	v_mul_f32_e32 v93, v74, v92
	v_fma_f32 v94, -v87, v93, v74
	v_fmac_f32_e32 v93, v94, v92
	v_div_scale_f32 v94, s[6:7], v88, v88, 1.0
	v_rcp_f32_e32 v95, v94
	v_and_b32_e32 v76, 0xffff0000, v76
	v_fma_f32 v74, -v87, v93, v74
	v_mul_f32_e32 v87, 0xbfb8aa3b, v76
	v_div_fmas_f32 v74, v74, v92, v93
	v_exp_f32_e32 v87, v87
	v_div_fixup_f32 v89, v74, v89, 1.0
	v_fma_f32 v74, -v94, v95, 1.0
	v_fmac_f32_e32 v95, v74, v95
	v_div_scale_f32 v74, vcc, 1.0, v88, 1.0
	v_mul_f32_e32 v92, v74, v95
	v_fma_f32 v93, -v94, v92, v74
	v_pk_add_f32 v[86:87], v[86:87], 1.0 op_sel_hi:[1,0]
	v_fmac_f32_e32 v92, v93, v95
	v_div_scale_f32 v93, s[6:7], v87, v87, v76
	v_fma_f32 v74, -v94, v92, v74
	v_rcp_f32_e32 v94, v93
	v_div_fmas_f32 v74, v74, v95, v92
	v_div_fixup_f32 v88, v74, v88, 1.0
	v_pk_mul_f32 v[78:79], v[88:89], v[78:79]
	v_fma_f32 v74, -v93, v94, 1.0
	v_fmac_f32_e32 v94, v74, v94
	v_div_scale_f32 v74, vcc, v76, v87, v76
	v_mul_f32_e32 v88, v74, v94
	v_fma_f32 v89, -v93, v88, v74
	v_fmac_f32_e32 v88, v89, v94
	v_div_scale_f32 v89, s[6:7], v86, v86, v1
	v_rcp_f32_e32 v92, v89
	v_fma_f32 v74, -v93, v88, v74
	v_div_fmas_f32 v74, v74, v94, v88
	v_div_fixup_f32 v87, v74, v87, v76
	v_fma_f32 v74, -v89, v92, 1.0
	v_fmac_f32_e32 v92, v74, v92
	v_div_scale_f32 v74, vcc, v1, v86, v1
	v_mul_f32_e32 v76, v74, v92
	v_fma_f32 v88, -v89, v76, v74
	v_fmac_f32_e32 v76, v88, v92
	v_fma_f32 v74, -v89, v76, v74
	v_div_fmas_f32 v74, v74, v92, v76
	v_div_fixup_f32 v86, v74, v86, v1
	v_add_f32_e32 v1, v66, v182
	v_mul_f32_e32 v1, 0xbfb8aa3b, v1
	v_exp_f32_e32 v66, v1
	v_add_f32_e32 v1, v67, v183
	v_mul_f32_e32 v1, 0xbfb8aa3b, v1
	v_exp_f32_e32 v67, v1
	v_lshlrev_b32_e32 v1, 16, v77
	v_and_b32_e32 v76, 0xffff0000, v77
	v_pk_mul_f32 v[78:79], v[86:87], v[78:79]
	v_pk_add_f32 v[66:67], v[66:67], 1.0 op_sel_hi:[1,0]
	v_mul_f32_e32 v70, 0xbfb8aa3b, v1
	v_div_scale_f32 v71, s[6:7], v67, v67, 1.0
	v_rcp_f32_e32 v77, v71
	v_exp_f32_e32 v70, v70
	v_lshlrev_b32_e32 v74, 16, v75
	v_and_b32_e32 v75, 0xffff0000, v75
	v_fma_f32 v86, -v71, v77, 1.0
	v_fmac_f32_e32 v77, v86, v77
	v_div_scale_f32 v86, vcc, 1.0, v67, 1.0
	v_mul_f32_e32 v87, v86, v77
	v_fma_f32 v88, -v71, v87, v86
	v_fmac_f32_e32 v87, v88, v77
	v_fma_f32 v71, -v71, v87, v86
	v_div_scale_f32 v86, s[6:7], v66, v66, 1.0
	v_rcp_f32_e32 v88, v86
	v_div_fmas_f32 v71, v71, v77, v87
	v_div_fixup_f32 v67, v71, v67, 1.0
	v_div_scale_f32 v77, vcc, 1.0, v66, 1.0
	v_fma_f32 v71, -v86, v88, 1.0
	v_fmac_f32_e32 v88, v71, v88
	v_mul_f32_e32 v71, 0xbfb8aa3b, v76
	v_exp_f32_e32 v71, v71
	v_mul_f32_e32 v87, v77, v88
	v_fma_f32 v89, -v86, v87, v77
	v_fmac_f32_e32 v87, v89, v88
	v_pk_add_f32 v[70:71], v[70:71], 1.0 op_sel_hi:[1,0]
	v_fma_f32 v77, -v86, v87, v77
	v_div_scale_f32 v86, s[6:7], v71, v71, v76
	v_rcp_f32_e32 v89, v86
	v_div_fmas_f32 v77, v77, v88, v87
	v_div_fixup_f32 v66, v77, v66, 1.0
	v_pk_mul_f32 v[66:67], v[66:67], v[74:75]
	v_fma_f32 v74, -v86, v89, 1.0
	v_fmac_f32_e32 v89, v74, v89
	v_div_scale_f32 v74, vcc, v76, v71, v76
	v_mul_f32_e32 v75, v74, v89
	v_fma_f32 v77, -v86, v75, v74
	v_fmac_f32_e32 v75, v77, v89
	v_div_scale_f32 v77, s[6:7], v70, v70, v1
	v_fma_f32 v74, -v86, v75, v74
	v_rcp_f32_e32 v86, v77
	v_div_fmas_f32 v74, v74, v89, v75
	v_div_fixup_f32 v71, v74, v71, v76
	v_fma_f32 v74, -v77, v86, 1.0
	v_fmac_f32_e32 v86, v74, v86
	v_div_scale_f32 v74, vcc, v1, v70, v1
	v_mul_f32_e32 v75, v74, v86
	v_fma_f32 v76, -v77, v75, v74
	v_fmac_f32_e32 v75, v76, v86
	v_fma_f32 v74, -v77, v75, v74
	v_div_fmas_f32 v74, v74, v86, v75
	v_div_fixup_f32 v70, v74, v70, v1
	v_pk_mul_f32 v[66:67], v[70:71], v[66:67]
	v_cvt_pk_bf16_f32 v70, v78, v79
	v_cvt_pk_bf16_f32 v71, v66, v67
	v_lshl_add_u64 v[66:67], s[24:25], 0, v[72:73]
	v_lshl_add_u64 v[66:67], v[66:67], 0, v[136:137]
	global_store_dwordx2 v[66:67], v[70:71], off
	s_waitcnt vmcnt(3)
	v_lshlrev_b32_e32 v74, 16, v90
	v_and_b32_e32 v75, 0xffff0000, v90
	s_waitcnt vmcnt(1)
	v_add_f32_e32 v1, v60, v184
	v_mul_f32_e32 v1, 0xbfb8aa3b, v1
	v_exp_f32_e32 v60, v1
	v_add_f32_e32 v1, v61, v185
	v_mul_f32_e32 v1, 0xbfb8aa3b, v1
	v_exp_f32_e32 v61, v1
	v_lshlrev_b32_e32 v1, 16, v64
	v_and_b32_e32 v64, 0xffff0000, v64
	v_mul_f32_e32 v70, 0xbfb8aa3b, v1
	v_pk_add_f32 v[60:61], v[60:61], 1.0 op_sel_hi:[1,0]
	v_exp_f32_e32 v70, v70
	v_div_scale_f32 v71, s[6:7], v61, v61, 1.0
	v_rcp_f32_e32 v76, v71
	s_nop 0
	v_fma_f32 v77, -v71, v76, 1.0
	v_fmac_f32_e32 v76, v77, v76
	v_div_scale_f32 v77, vcc, 1.0, v61, 1.0
	v_mul_f32_e32 v78, v77, v76
	v_fma_f32 v79, -v71, v78, v77
	v_fmac_f32_e32 v78, v79, v76
	v_fma_f32 v71, -v71, v78, v77
	v_div_scale_f32 v77, s[6:7], v60, v60, 1.0
	v_rcp_f32_e32 v79, v77
	v_div_fmas_f32 v71, v71, v76, v78
	v_div_fixup_f32 v61, v71, v61, 1.0
	v_div_scale_f32 v76, vcc, 1.0, v60, 1.0
	v_fma_f32 v71, -v77, v79, 1.0
	v_fmac_f32_e32 v79, v71, v79
	v_mul_f32_e32 v71, 0xbfb8aa3b, v64
	v_exp_f32_e32 v71, v71
	v_mul_f32_e32 v78, v76, v79
	v_fma_f32 v86, -v77, v78, v76
	v_fmac_f32_e32 v78, v86, v79
	v_pk_add_f32 v[70:71], v[70:71], 1.0 op_sel_hi:[1,0]
	v_fma_f32 v76, -v77, v78, v76
	v_div_scale_f32 v77, s[6:7], v71, v71, v64
	v_rcp_f32_e32 v86, v77
	v_div_fmas_f32 v76, v76, v79, v78
	v_div_fixup_f32 v60, v76, v60, 1.0
	v_pk_mul_f32 v[60:61], v[60:61], v[74:75]
	v_fma_f32 v74, -v77, v86, 1.0
	v_fmac_f32_e32 v86, v74, v86
	v_div_scale_f32 v74, vcc, v64, v71, v64
	v_mul_f32_e32 v75, v74, v86
	v_fma_f32 v76, -v77, v75, v74
	v_fmac_f32_e32 v75, v76, v86
	v_div_scale_f32 v76, s[6:7], v70, v70, v1
	v_fma_f32 v74, -v77, v75, v74
	v_rcp_f32_e32 v77, v76
	v_div_fmas_f32 v74, v74, v86, v75
	v_div_fixup_f32 v71, v74, v71, v64
	v_fma_f32 v64, -v76, v77, 1.0
	v_fmac_f32_e32 v77, v64, v77
	v_div_scale_f32 v64, vcc, v1, v70, v1
	v_mul_f32_e32 v74, v64, v77
	v_fma_f32 v75, -v76, v74, v64
	v_fmac_f32_e32 v74, v75, v77
	v_fma_f32 v64, -v76, v74, v64
	v_div_fmas_f32 v64, v64, v77, v74
	v_div_fixup_f32 v70, v64, v70, v1
	v_add_f32_e32 v1, v62, v186
	v_mul_f32_e32 v1, 0xbfb8aa3b, v1
	v_exp_f32_e32 v62, v1
	v_add_f32_e32 v1, v63, v187
	v_mul_f32_e32 v1, 0xbfb8aa3b, v1
	v_exp_f32_e32 v63, v1
	v_lshlrev_b32_e32 v1, 16, v65
	v_and_b32_e32 v72, 0xffff0000, v65
	v_mul_f32_e32 v64, 0xbfb8aa3b, v1
	v_pk_add_f32 v[62:63], v[62:63], 1.0 op_sel_hi:[1,0]
	v_exp_f32_e32 v64, v64
	v_div_scale_f32 v65, s[6:7], v63, v63, 1.0
	v_rcp_f32_e32 v73, v65
	v_pk_mul_f32 v[60:61], v[70:71], v[60:61]
	v_lshlrev_b32_e32 v70, 16, v91
	v_and_b32_e32 v71, 0xffff0000, v91
	v_fma_f32 v74, -v65, v73, 1.0
	v_fmac_f32_e32 v73, v74, v73
	v_div_scale_f32 v74, vcc, 1.0, v63, 1.0
	v_mul_f32_e32 v75, v74, v73
	v_fma_f32 v76, -v65, v75, v74
	v_fmac_f32_e32 v75, v76, v73
	v_fma_f32 v65, -v65, v75, v74
	v_div_scale_f32 v74, s[6:7], v62, v62, 1.0
	v_rcp_f32_e32 v76, v74
	v_div_fmas_f32 v65, v65, v73, v75
	v_div_fixup_f32 v63, v65, v63, 1.0
	v_div_scale_f32 v73, vcc, 1.0, v62, 1.0
	v_fma_f32 v65, -v74, v76, 1.0
	v_fmac_f32_e32 v76, v65, v76
	v_mul_f32_e32 v65, 0xbfb8aa3b, v72
	v_exp_f32_e32 v65, v65
	v_mul_f32_e32 v75, v73, v76
	v_fma_f32 v77, -v74, v75, v73
	v_fmac_f32_e32 v75, v77, v76
	v_pk_add_f32 v[64:65], v[64:65], 1.0 op_sel_hi:[1,0]
	v_fma_f32 v73, -v74, v75, v73
	v_div_scale_f32 v74, s[6:7], v65, v65, v72
	v_rcp_f32_e32 v77, v74
	v_div_fmas_f32 v73, v73, v76, v75
	v_div_fixup_f32 v62, v73, v62, 1.0
	v_pk_mul_f32 v[62:63], v[62:63], v[70:71]
	v_fma_f32 v70, -v74, v77, 1.0
	v_fmac_f32_e32 v77, v70, v77
	v_div_scale_f32 v70, vcc, v72, v65, v72
	v_mul_f32_e32 v71, v70, v77
	v_fma_f32 v73, -v74, v71, v70
	v_fmac_f32_e32 v71, v73, v77
	v_div_scale_f32 v73, s[6:7], v64, v64, v1
	v_fma_f32 v70, -v74, v71, v70
	v_rcp_f32_e32 v74, v73
	v_div_fmas_f32 v70, v70, v77, v71
	v_div_fixup_f32 v65, v70, v65, v72
	v_cvt_pk_bf16_f32 v60, v60, v61
	v_fma_f32 v70, -v73, v74, 1.0
	v_fmac_f32_e32 v74, v70, v74
	v_div_scale_f32 v70, vcc, v1, v64, v1
	v_mul_f32_e32 v71, v70, v74
	v_fma_f32 v72, -v73, v71, v70
	v_fmac_f32_e32 v71, v72, v74
	v_fma_f32 v70, -v73, v71, v70
	v_div_fmas_f32 v70, v70, v74, v71
	v_div_fixup_f32 v64, v70, v64, v1
	v_pk_mul_f32 v[62:63], v[64:65], v[62:63]
	v_and_b32_e32 v70, 0xffff0000, v82
	v_cvt_pk_bf16_f32 v61, v62, v63
	global_store_dwordx2 v[66:67], v[60:61], off offset:32
	v_lshlrev_b32_e32 v64, 16, v84
	v_and_b32_e32 v65, 0xffff0000, v84
	s_waitcnt vmcnt(2)
	v_add_f32_e32 v1, v56, v188
	v_mul_f32_e32 v1, 0xbfb8aa3b, v1
	v_exp_f32_e32 v56, v1
	v_add_f32_e32 v1, v57, v189
	v_mul_f32_e32 v1, 0xbfb8aa3b, v1
	v_exp_f32_e32 v57, v1
	v_lshlrev_b32_e32 v1, 16, v82
	v_mul_f32_e32 v60, 0xbfb8aa3b, v1
	v_exp_f32_e32 v60, v60
	v_pk_add_f32 v[56:57], v[56:57], 1.0 op_sel_hi:[1,0]
	s_nop 0
	v_div_scale_f32 v61, s[6:7], v57, v57, 1.0
	v_rcp_f32_e32 v71, v61
	s_nop 0
	v_fma_f32 v72, -v61, v71, 1.0
	v_fmac_f32_e32 v71, v72, v71
	v_div_scale_f32 v72, vcc, 1.0, v57, 1.0
	v_mul_f32_e32 v73, v72, v71
	v_fma_f32 v74, -v61, v73, v72
	v_fmac_f32_e32 v73, v74, v71
	v_fma_f32 v61, -v61, v73, v72
	v_div_scale_f32 v72, s[6:7], v56, v56, 1.0
	v_rcp_f32_e32 v74, v72
	v_div_fmas_f32 v61, v61, v71, v73
	v_div_fixup_f32 v57, v61, v57, 1.0
	v_div_scale_f32 v71, vcc, 1.0, v56, 1.0
	v_fma_f32 v61, -v72, v74, 1.0
	v_fmac_f32_e32 v74, v61, v74
	v_mul_f32_e32 v61, 0xbfb8aa3b, v70
	v_exp_f32_e32 v61, v61
	v_mul_f32_e32 v73, v71, v74
	v_fma_f32 v75, -v72, v73, v71
	v_fmac_f32_e32 v73, v75, v74
	v_pk_add_f32 v[60:61], v[60:61], 1.0 op_sel_hi:[1,0]
	v_fma_f32 v71, -v72, v73, v71
	v_div_scale_f32 v72, s[6:7], v61, v61, v70
	v_rcp_f32_e32 v75, v72
	v_div_fmas_f32 v71, v71, v74, v73
	v_div_fixup_f32 v56, v71, v56, 1.0
	v_pk_mul_f32 v[56:57], v[56:57], v[64:65]
	v_fma_f32 v64, -v72, v75, 1.0
	v_fmac_f32_e32 v75, v64, v75
	v_div_scale_f32 v64, vcc, v70, v61, v70
	v_mul_f32_e32 v65, v64, v75
	v_fma_f32 v71, -v72, v65, v64
	v_fmac_f32_e32 v65, v71, v75
	v_div_scale_f32 v71, s[6:7], v60, v60, v1
	v_fma_f32 v64, -v72, v65, v64
	v_rcp_f32_e32 v72, v71
	v_div_fmas_f32 v64, v64, v75, v65
	v_div_fixup_f32 v61, v64, v61, v70
	v_fma_f32 v64, -v71, v72, 1.0
	v_fmac_f32_e32 v72, v64, v72
	v_div_scale_f32 v64, vcc, v1, v60, v1
	v_mul_f32_e32 v65, v64, v72
	v_fma_f32 v70, -v71, v65, v64
	v_fmac_f32_e32 v65, v70, v72
	v_fma_f32 v64, -v71, v65, v64
	v_div_fmas_f32 v64, v64, v72, v65
	v_div_fixup_f32 v60, v64, v60, v1
	v_add_f32_e32 v1, v58, v190
	v_mul_f32_e32 v1, 0xbfb8aa3b, v1
	v_exp_f32_e32 v58, v1
	v_add_f32_e32 v1, v59, v191
	v_mul_f32_e32 v1, 0xbfb8aa3b, v1
	v_exp_f32_e32 v59, v1
	v_pk_mul_f32 v[56:57], v[60:61], v[56:57]
	v_lshlrev_b32_e32 v1, 16, v83
	v_and_b32_e32 v64, 0xffff0000, v83
	v_pk_add_f32 v[58:59], v[58:59], 1.0 op_sel_hi:[1,0]
	v_mul_f32_e32 v60, 0xbfb8aa3b, v1
	v_div_scale_f32 v61, s[6:7], v59, v59, 1.0
	v_rcp_f32_e32 v65, v61
	v_exp_f32_e32 v60, v60
	v_lshlrev_b32_e32 v62, 16, v85
	v_and_b32_e32 v63, 0xffff0000, v85
	v_fma_f32 v70, -v61, v65, 1.0
	v_fmac_f32_e32 v65, v70, v65
	v_div_scale_f32 v70, vcc, 1.0, v59, 1.0
	v_mul_f32_e32 v71, v70, v65
	v_fma_f32 v72, -v61, v71, v70
	v_fmac_f32_e32 v71, v72, v65
	v_fma_f32 v61, -v61, v71, v70
	v_div_scale_f32 v70, s[6:7], v58, v58, 1.0
	v_rcp_f32_e32 v72, v70
	v_div_fmas_f32 v61, v61, v65, v71
	v_div_fixup_f32 v59, v61, v59, 1.0
	v_div_scale_f32 v65, vcc, 1.0, v58, 1.0
	v_fma_f32 v61, -v70, v72, 1.0
	v_fmac_f32_e32 v72, v61, v72
	v_mul_f32_e32 v61, 0xbfb8aa3b, v64
	v_exp_f32_e32 v61, v61
	v_mul_f32_e32 v71, v65, v72
	v_fma_f32 v73, -v70, v71, v65
	v_fmac_f32_e32 v71, v73, v72
	v_pk_add_f32 v[60:61], v[60:61], 1.0 op_sel_hi:[1,0]
	v_fma_f32 v65, -v70, v71, v65
	v_div_scale_f32 v70, s[6:7], v61, v61, v64
	v_rcp_f32_e32 v73, v70
	v_div_fmas_f32 v65, v65, v72, v71
	v_div_fixup_f32 v58, v65, v58, 1.0
	v_pk_mul_f32 v[58:59], v[58:59], v[62:63]
	v_fma_f32 v62, -v70, v73, 1.0
	v_fmac_f32_e32 v73, v62, v73
	v_div_scale_f32 v62, vcc, v64, v61, v64
	v_mul_f32_e32 v63, v62, v73
	v_fma_f32 v65, -v70, v63, v62
	v_fmac_f32_e32 v63, v65, v73
	v_div_scale_f32 v65, s[6:7], v60, v60, v1
	v_fma_f32 v62, -v70, v63, v62
	v_rcp_f32_e32 v70, v65
	v_div_fmas_f32 v62, v62, v73, v63
	v_div_fixup_f32 v61, v62, v61, v64
	v_cvt_pk_bf16_f32 v56, v56, v57
	v_fma_f32 v62, -v65, v70, 1.0
	v_fmac_f32_e32 v70, v62, v70
	v_div_scale_f32 v62, vcc, v1, v60, v1
	v_mul_f32_e32 v63, v62, v70
	v_fma_f32 v64, -v65, v63, v62
	v_fmac_f32_e32 v63, v64, v70
	v_fma_f32 v62, -v65, v63, v62
	v_div_fmas_f32 v62, v62, v70, v63
	v_div_fixup_f32 v60, v62, v60, v1
	v_pk_mul_f32 v[58:59], v[60:61], v[58:59]
	v_lshlrev_b32_e32 v60, 16, v68
	v_cvt_pk_bf16_f32 v57, v58, v59
	global_store_dwordx2 v[66:67], v[56:57], off offset:256
	v_and_b32_e32 v61, 0xffff0000, v68
	v_and_b32_e32 v62, 0xffff0000, v80
	s_waitcnt vmcnt(3)
	v_add_f32_e32 v1, v52, v192
	v_mul_f32_e32 v1, 0xbfb8aa3b, v1
	v_exp_f32_e32 v52, v1
	v_add_f32_e32 v1, v53, v193
	v_mul_f32_e32 v1, 0xbfb8aa3b, v1
	v_exp_f32_e32 v53, v1
	v_lshlrev_b32_e32 v1, 16, v80
	v_mul_f32_e32 v56, 0xbfb8aa3b, v1
	v_exp_f32_e32 v56, v56
	v_pk_add_f32 v[52:53], v[52:53], 1.0 op_sel_hi:[1,0]
	s_nop 0
	v_div_scale_f32 v57, s[6:7], v53, v53, 1.0
	v_rcp_f32_e32 v63, v57
	s_nop 0
	v_fma_f32 v64, -v57, v63, 1.0
	v_fmac_f32_e32 v63, v64, v63
	v_div_scale_f32 v64, vcc, 1.0, v53, 1.0
	v_mul_f32_e32 v65, v64, v63
	v_fma_f32 v68, -v57, v65, v64
	v_fmac_f32_e32 v65, v68, v63
	v_fma_f32 v57, -v57, v65, v64
	v_div_scale_f32 v64, s[6:7], v52, v52, 1.0
	v_rcp_f32_e32 v68, v64
	v_div_fmas_f32 v57, v57, v63, v65
	v_div_fixup_f32 v53, v57, v53, 1.0
	v_div_scale_f32 v63, vcc, 1.0, v52, 1.0
	v_fma_f32 v57, -v64, v68, 1.0
	v_fmac_f32_e32 v68, v57, v68
	v_mul_f32_e32 v57, 0xbfb8aa3b, v62
	v_exp_f32_e32 v57, v57
	v_mul_f32_e32 v65, v63, v68
	v_fma_f32 v70, -v64, v65, v63
	v_fmac_f32_e32 v65, v70, v68
	v_pk_add_f32 v[56:57], v[56:57], 1.0 op_sel_hi:[1,0]
	v_fma_f32 v63, -v64, v65, v63
	v_div_scale_f32 v64, s[6:7], v57, v57, v62
	v_rcp_f32_e32 v70, v64
	v_div_fmas_f32 v63, v63, v68, v65
	v_div_fixup_f32 v52, v63, v52, 1.0
	v_pk_mul_f32 v[52:53], v[52:53], v[60:61]
	v_fma_f32 v60, -v64, v70, 1.0
	v_fmac_f32_e32 v70, v60, v70
	v_div_scale_f32 v60, vcc, v62, v57, v62
	v_mul_f32_e32 v61, v60, v70
	v_fma_f32 v63, -v64, v61, v60
	v_fmac_f32_e32 v61, v63, v70
	v_div_scale_f32 v63, s[6:7], v56, v56, v1
	v_fma_f32 v60, -v64, v61, v60
	v_rcp_f32_e32 v64, v63
	v_div_fmas_f32 v60, v60, v70, v61
	v_div_fixup_f32 v57, v60, v57, v62
	v_fma_f32 v60, -v63, v64, 1.0
	v_fmac_f32_e32 v64, v60, v64
	v_div_scale_f32 v60, vcc, v1, v56, v1
	v_mul_f32_e32 v61, v60, v64
	v_fma_f32 v62, -v63, v61, v60
	v_fmac_f32_e32 v61, v62, v64
	v_fma_f32 v60, -v63, v61, v60
	v_div_fmas_f32 v60, v60, v64, v61
	v_div_fixup_f32 v56, v60, v56, v1
	v_add_f32_e32 v1, v54, v194
	v_mul_f32_e32 v1, 0xbfb8aa3b, v1
	v_exp_f32_e32 v54, v1
	v_add_f32_e32 v1, v55, v195
	v_mul_f32_e32 v1, 0xbfb8aa3b, v1
	v_exp_f32_e32 v55, v1
	v_pk_mul_f32 v[52:53], v[56:57], v[52:53]
	v_lshlrev_b32_e32 v1, 16, v81
	v_and_b32_e32 v60, 0xffff0000, v81
	v_pk_add_f32 v[54:55], v[54:55], 1.0 op_sel_hi:[1,0]
	v_mul_f32_e32 v56, 0xbfb8aa3b, v1
	v_div_scale_f32 v57, s[6:7], v55, v55, 1.0
	v_rcp_f32_e32 v61, v57
	v_exp_f32_e32 v56, v56
	v_lshlrev_b32_e32 v58, 16, v69
	v_and_b32_e32 v59, 0xffff0000, v69
	v_fma_f32 v62, -v57, v61, 1.0
	v_fmac_f32_e32 v61, v62, v61
	v_div_scale_f32 v62, vcc, 1.0, v55, 1.0
	v_mul_f32_e32 v63, v62, v61
	v_fma_f32 v64, -v57, v63, v62
	v_fmac_f32_e32 v63, v64, v61
	v_fma_f32 v57, -v57, v63, v62
	v_div_scale_f32 v62, s[6:7], v54, v54, 1.0
	v_rcp_f32_e32 v64, v62
	v_div_fmas_f32 v57, v57, v61, v63
	v_div_fixup_f32 v55, v57, v55, 1.0
	v_div_scale_f32 v61, vcc, 1.0, v54, 1.0
	v_fma_f32 v57, -v62, v64, 1.0
	v_fmac_f32_e32 v64, v57, v64
	v_mul_f32_e32 v57, 0xbfb8aa3b, v60
	v_exp_f32_e32 v57, v57
	v_mul_f32_e32 v63, v61, v64
	v_fma_f32 v65, -v62, v63, v61
	v_fmac_f32_e32 v63, v65, v64
	v_pk_add_f32 v[56:57], v[56:57], 1.0 op_sel_hi:[1,0]
	v_fma_f32 v61, -v62, v63, v61
	v_div_scale_f32 v62, s[6:7], v57, v57, v60
	v_rcp_f32_e32 v65, v62
	v_div_fmas_f32 v61, v61, v64, v63
	v_div_fixup_f32 v54, v61, v54, 1.0
	v_pk_mul_f32 v[54:55], v[54:55], v[58:59]
	v_fma_f32 v58, -v62, v65, 1.0
	v_fmac_f32_e32 v65, v58, v65
	v_div_scale_f32 v58, vcc, v60, v57, v60
	v_mul_f32_e32 v59, v58, v65
	v_fma_f32 v61, -v62, v59, v58
	v_fmac_f32_e32 v59, v61, v65
	v_div_scale_f32 v61, s[6:7], v56, v56, v1
	v_fma_f32 v58, -v62, v59, v58
	v_rcp_f32_e32 v62, v61
	v_div_fmas_f32 v58, v58, v65, v59
	v_div_fixup_f32 v57, v58, v57, v60
	v_cvt_pk_bf16_f32 v52, v52, v53
	v_fma_f32 v58, -v61, v62, 1.0
	v_fmac_f32_e32 v62, v58, v62
	v_div_scale_f32 v58, vcc, v1, v56, v1
	v_mul_f32_e32 v59, v58, v62
	v_fma_f32 v60, -v61, v59, v58
	v_fmac_f32_e32 v59, v60, v62
	v_fma_f32 v58, -v61, v59, v58
	v_div_fmas_f32 v58, v58, v62, v59
	v_div_fixup_f32 v56, v58, v56, v1
	v_pk_mul_f32 v[54:55], v[56:57], v[54:55]
	v_add_u32_e32 v56, 0x90, v138
	v_cvt_pk_bf16_f32 v53, v54, v55
	global_store_dwordx2 v[66:67], v[52:53], off offset:288
	v_ashrrev_i32_e32 v57, 31, v56
	v_lshlrev_b64 v[58:59], 13, v[56:57]
	v_lshl_add_u64 v[58:59], s[26:27], 0, v[58:59]
	v_lshl_add_u64 v[64:65], v[58:59], 0, v[136:137]
	global_load_dwordx2 v[60:61], v[64:65], off offset:3072
	v_mad_i64_i32 v[58:59], s[6:7], v56, s81, v[140:141]
	v_lshl_add_u64 v[62:63], v[58:59], 0, v[136:137]
	global_load_dwordx2 v[58:59], v[62:63], off
	v_lshlrev_b64 v[56:57], 12, v[56:57]
	s_waitcnt vmcnt(6)
	v_add_f32_e32 v1, v48, v180
	v_mul_f32_e32 v1, 0xbfb8aa3b, v1
	v_exp_f32_e32 v52, v1
	v_add_f32_e32 v1, v49, v181
	v_mul_f32_e32 v1, 0xbfb8aa3b, v1
	v_exp_f32_e32 v53, v1
	s_waitcnt vmcnt(1)
	v_lshlrev_b32_e32 v1, 16, v60
	v_mul_f32_e32 v68, 0xbfb8aa3b, v1
	global_load_dwordx2 v[48:49], v[64:65], off offset:3104
	global_load_dwordx2 v[66:67], v[64:65], off offset:3328
	s_nop 0
	global_load_dwordx2 v[64:65], v[64:65], off offset:3360
	v_pk_add_f32 v[72:73], v[52:53], 1.0 op_sel_hi:[1,0]
	v_exp_f32_e32 v70, v68
	v_div_scale_f32 v71, s[6:7], v73, v73, 1.0
	v_rcp_f32_e32 v76, v71
	global_load_dwordx2 v[74:75], v[62:63], off offset:32
	global_load_dwordx2 v[68:69], v[62:63], off offset:256
	global_load_dwordx2 v[52:53], v[62:63], off offset:288
	s_waitcnt vmcnt(6)
	v_lshlrev_b32_e32 v62, 16, v58
	v_and_b32_e32 v63, 0xffff0000, v58
	v_fma_f32 v58, -v71, v76, 1.0
	v_fmac_f32_e32 v76, v58, v76
	v_div_scale_f32 v58, vcc, 1.0, v73, 1.0
	v_mul_f32_e32 v77, v58, v76
	v_fma_f32 v78, -v71, v77, v58
	v_fmac_f32_e32 v77, v78, v76
	v_div_scale_f32 v78, s[6:7], v72, v72, 1.0
	v_rcp_f32_e32 v79, v78
	v_and_b32_e32 v60, 0xffff0000, v60
	v_fma_f32 v58, -v71, v77, v58
	v_mul_f32_e32 v71, 0xbfb8aa3b, v60
	v_div_fmas_f32 v58, v58, v76, v77
	v_exp_f32_e32 v71, v71
	v_div_fixup_f32 v73, v58, v73, 1.0
	v_fma_f32 v58, -v78, v79, 1.0
	v_fmac_f32_e32 v79, v58, v79
	v_div_scale_f32 v58, vcc, 1.0, v72, 1.0
	v_mul_f32_e32 v76, v58, v79
	v_fma_f32 v77, -v78, v76, v58
	v_pk_add_f32 v[70:71], v[70:71], 1.0 op_sel_hi:[1,0]
	v_fmac_f32_e32 v76, v77, v79
	v_div_scale_f32 v77, s[6:7], v71, v71, v60
	v_fma_f32 v58, -v78, v76, v58
	v_rcp_f32_e32 v78, v77
	v_div_fmas_f32 v58, v58, v79, v76
	v_div_fixup_f32 v72, v58, v72, 1.0
	v_pk_mul_f32 v[62:63], v[72:73], v[62:63]
	v_fma_f32 v58, -v77, v78, 1.0
	v_fmac_f32_e32 v78, v58, v78
	v_div_scale_f32 v58, vcc, v60, v71, v60
	v_mul_f32_e32 v72, v58, v78
	v_fma_f32 v73, -v77, v72, v58
	v_fmac_f32_e32 v72, v73, v78
	v_div_scale_f32 v73, s[6:7], v70, v70, v1
	v_rcp_f32_e32 v76, v73
	v_fma_f32 v58, -v77, v72, v58
	v_div_fmas_f32 v58, v58, v78, v72
	v_div_fixup_f32 v71, v58, v71, v60
	v_fma_f32 v58, -v73, v76, 1.0
	v_fmac_f32_e32 v76, v58, v76
	v_div_scale_f32 v58, vcc, v1, v70, v1
	v_mul_f32_e32 v60, v58, v76
	v_fma_f32 v72, -v73, v60, v58
	v_fmac_f32_e32 v60, v72, v76
	v_fma_f32 v58, -v73, v60, v58
	v_div_fmas_f32 v58, v58, v76, v60
	v_div_fixup_f32 v70, v58, v70, v1
	v_add_f32_e32 v1, v50, v182
	v_mul_f32_e32 v1, 0xbfb8aa3b, v1
	v_exp_f32_e32 v50, v1
	v_add_f32_e32 v1, v51, v183
	v_mul_f32_e32 v1, 0xbfb8aa3b, v1
	v_exp_f32_e32 v51, v1
	v_lshlrev_b32_e32 v1, 16, v61
	v_and_b32_e32 v60, 0xffff0000, v61
	v_pk_mul_f32 v[62:63], v[70:71], v[62:63]
	v_pk_add_f32 v[50:51], v[50:51], 1.0 op_sel_hi:[1,0]
	v_mul_f32_e32 v54, 0xbfb8aa3b, v1
	v_div_scale_f32 v55, s[6:7], v51, v51, 1.0
	v_rcp_f32_e32 v61, v55
	v_exp_f32_e32 v54, v54
	v_lshlrev_b32_e32 v58, 16, v59
	v_and_b32_e32 v59, 0xffff0000, v59
	v_fma_f32 v70, -v55, v61, 1.0
	v_fmac_f32_e32 v61, v70, v61
	v_div_scale_f32 v70, vcc, 1.0, v51, 1.0
	v_mul_f32_e32 v71, v70, v61
	v_fma_f32 v72, -v55, v71, v70
	v_fmac_f32_e32 v71, v72, v61
	v_fma_f32 v55, -v55, v71, v70
	v_div_scale_f32 v70, s[6:7], v50, v50, 1.0
	v_rcp_f32_e32 v72, v70
	v_div_fmas_f32 v55, v55, v61, v71
	v_div_fixup_f32 v51, v55, v51, 1.0
	v_div_scale_f32 v61, vcc, 1.0, v50, 1.0
	v_fma_f32 v55, -v70, v72, 1.0
	v_fmac_f32_e32 v72, v55, v72
	v_mul_f32_e32 v55, 0xbfb8aa3b, v60
	v_exp_f32_e32 v55, v55
	v_mul_f32_e32 v71, v61, v72
	v_fma_f32 v73, -v70, v71, v61
	v_fmac_f32_e32 v71, v73, v72
	v_pk_add_f32 v[54:55], v[54:55], 1.0 op_sel_hi:[1,0]
	v_fma_f32 v61, -v70, v71, v61
	v_div_scale_f32 v70, s[6:7], v55, v55, v60
	v_rcp_f32_e32 v73, v70
	v_div_fmas_f32 v61, v61, v72, v71
	v_div_fixup_f32 v50, v61, v50, 1.0
	v_pk_mul_f32 v[50:51], v[50:51], v[58:59]
	v_fma_f32 v58, -v70, v73, 1.0
	v_fmac_f32_e32 v73, v58, v73
	v_div_scale_f32 v58, vcc, v60, v55, v60
	v_mul_f32_e32 v59, v58, v73
	v_fma_f32 v61, -v70, v59, v58
	v_fmac_f32_e32 v59, v61, v73
	v_div_scale_f32 v61, s[6:7], v54, v54, v1
	v_fma_f32 v58, -v70, v59, v58
	v_rcp_f32_e32 v70, v61
	v_div_fmas_f32 v58, v58, v73, v59
	v_div_fixup_f32 v55, v58, v55, v60
	v_fma_f32 v58, -v61, v70, 1.0
	v_fmac_f32_e32 v70, v58, v70
	v_div_scale_f32 v58, vcc, v1, v54, v1
	v_mul_f32_e32 v59, v58, v70
	v_fma_f32 v60, -v61, v59, v58
	v_fmac_f32_e32 v59, v60, v70
	v_fma_f32 v58, -v61, v59, v58
	v_div_fmas_f32 v58, v58, v70, v59
	v_div_fixup_f32 v54, v58, v54, v1
	v_pk_mul_f32 v[50:51], v[54:55], v[50:51]
	v_cvt_pk_bf16_f32 v54, v62, v63
	v_cvt_pk_bf16_f32 v55, v50, v51
	v_lshl_add_u64 v[50:51], s[24:25], 0, v[56:57]
	v_lshl_add_u64 v[50:51], v[50:51], 0, v[136:137]
	global_store_dwordx2 v[50:51], v[54:55], off
	s_waitcnt vmcnt(3)
	v_lshlrev_b32_e32 v58, 16, v74
	v_and_b32_e32 v59, 0xffff0000, v74
	s_waitcnt vmcnt(1)
	v_add_f32_e32 v1, v44, v184
	v_mul_f32_e32 v1, 0xbfb8aa3b, v1
	v_exp_f32_e32 v44, v1
	v_add_f32_e32 v1, v45, v185
	v_mul_f32_e32 v1, 0xbfb8aa3b, v1
	v_exp_f32_e32 v45, v1
	v_lshlrev_b32_e32 v1, 16, v48
	v_and_b32_e32 v48, 0xffff0000, v48
	v_mul_f32_e32 v54, 0xbfb8aa3b, v1
	v_pk_add_f32 v[44:45], v[44:45], 1.0 op_sel_hi:[1,0]
	v_exp_f32_e32 v54, v54
	v_div_scale_f32 v55, s[6:7], v45, v45, 1.0
	v_rcp_f32_e32 v60, v55
	s_nop 0
	v_fma_f32 v61, -v55, v60, 1.0
	v_fmac_f32_e32 v60, v61, v60
	v_div_scale_f32 v61, vcc, 1.0, v45, 1.0
	v_mul_f32_e32 v62, v61, v60
	v_fma_f32 v63, -v55, v62, v61
	v_fmac_f32_e32 v62, v63, v60
	v_fma_f32 v55, -v55, v62, v61
	v_div_scale_f32 v61, s[6:7], v44, v44, 1.0
	v_rcp_f32_e32 v63, v61
	v_div_fmas_f32 v55, v55, v60, v62
	v_div_fixup_f32 v45, v55, v45, 1.0
	v_div_scale_f32 v60, vcc, 1.0, v44, 1.0
	v_fma_f32 v55, -v61, v63, 1.0
	v_fmac_f32_e32 v63, v55, v63
	v_mul_f32_e32 v55, 0xbfb8aa3b, v48
	v_exp_f32_e32 v55, v55
	v_mul_f32_e32 v62, v60, v63
	v_fma_f32 v70, -v61, v62, v60
	v_fmac_f32_e32 v62, v70, v63
	v_pk_add_f32 v[54:55], v[54:55], 1.0 op_sel_hi:[1,0]
	v_fma_f32 v60, -v61, v62, v60
	v_div_scale_f32 v61, s[6:7], v55, v55, v48
	v_rcp_f32_e32 v70, v61
	v_div_fmas_f32 v60, v60, v63, v62
	v_div_fixup_f32 v44, v60, v44, 1.0
	v_pk_mul_f32 v[44:45], v[44:45], v[58:59]
	v_fma_f32 v58, -v61, v70, 1.0
	v_fmac_f32_e32 v70, v58, v70
	v_div_scale_f32 v58, vcc, v48, v55, v48
	v_mul_f32_e32 v59, v58, v70
	v_fma_f32 v60, -v61, v59, v58
	v_fmac_f32_e32 v59, v60, v70
	v_div_scale_f32 v60, s[6:7], v54, v54, v1
	v_fma_f32 v58, -v61, v59, v58
	v_rcp_f32_e32 v61, v60
	v_div_fmas_f32 v58, v58, v70, v59
	v_div_fixup_f32 v55, v58, v55, v48
	v_fma_f32 v48, -v60, v61, 1.0
	v_fmac_f32_e32 v61, v48, v61
	v_div_scale_f32 v48, vcc, v1, v54, v1
	v_mul_f32_e32 v58, v48, v61
	v_fma_f32 v59, -v60, v58, v48
	v_fmac_f32_e32 v58, v59, v61
	v_fma_f32 v48, -v60, v58, v48
	v_div_fmas_f32 v48, v48, v61, v58
	v_div_fixup_f32 v54, v48, v54, v1
	v_add_f32_e32 v1, v46, v186
	v_mul_f32_e32 v1, 0xbfb8aa3b, v1
	v_exp_f32_e32 v46, v1
	v_add_f32_e32 v1, v47, v187
	v_mul_f32_e32 v1, 0xbfb8aa3b, v1
	v_exp_f32_e32 v47, v1
	v_lshlrev_b32_e32 v1, 16, v49
	v_and_b32_e32 v56, 0xffff0000, v49
	v_mul_f32_e32 v48, 0xbfb8aa3b, v1
	v_pk_add_f32 v[46:47], v[46:47], 1.0 op_sel_hi:[1,0]
	v_exp_f32_e32 v48, v48
	v_div_scale_f32 v49, s[6:7], v47, v47, 1.0
	v_rcp_f32_e32 v57, v49
	v_pk_mul_f32 v[44:45], v[54:55], v[44:45]
	v_lshlrev_b32_e32 v54, 16, v75
	v_and_b32_e32 v55, 0xffff0000, v75
	v_fma_f32 v58, -v49, v57, 1.0
	v_fmac_f32_e32 v57, v58, v57
	v_div_scale_f32 v58, vcc, 1.0, v47, 1.0
	v_mul_f32_e32 v59, v58, v57
	v_fma_f32 v60, -v49, v59, v58
	v_fmac_f32_e32 v59, v60, v57
	v_fma_f32 v49, -v49, v59, v58
	v_div_scale_f32 v58, s[6:7], v46, v46, 1.0
	v_rcp_f32_e32 v60, v58
	v_div_fmas_f32 v49, v49, v57, v59
	v_div_fixup_f32 v47, v49, v47, 1.0
	v_div_scale_f32 v57, vcc, 1.0, v46, 1.0
	v_fma_f32 v49, -v58, v60, 1.0
	v_fmac_f32_e32 v60, v49, v60
	v_mul_f32_e32 v49, 0xbfb8aa3b, v56
	v_exp_f32_e32 v49, v49
	v_mul_f32_e32 v59, v57, v60
	v_fma_f32 v61, -v58, v59, v57
	v_fmac_f32_e32 v59, v61, v60
	v_pk_add_f32 v[48:49], v[48:49], 1.0 op_sel_hi:[1,0]
	v_fma_f32 v57, -v58, v59, v57
	v_div_scale_f32 v58, s[6:7], v49, v49, v56
	v_rcp_f32_e32 v61, v58
	v_div_fmas_f32 v57, v57, v60, v59
	v_div_fixup_f32 v46, v57, v46, 1.0
	v_pk_mul_f32 v[46:47], v[46:47], v[54:55]
	v_fma_f32 v54, -v58, v61, 1.0
	v_fmac_f32_e32 v61, v54, v61
	v_div_scale_f32 v54, vcc, v56, v49, v56
	v_mul_f32_e32 v55, v54, v61
	v_fma_f32 v57, -v58, v55, v54
	v_fmac_f32_e32 v55, v57, v61
	v_div_scale_f32 v57, s[6:7], v48, v48, v1
	v_fma_f32 v54, -v58, v55, v54
	v_rcp_f32_e32 v58, v57
	v_div_fmas_f32 v54, v54, v61, v55
	v_div_fixup_f32 v49, v54, v49, v56
	v_cvt_pk_bf16_f32 v44, v44, v45
	v_fma_f32 v54, -v57, v58, 1.0
	v_fmac_f32_e32 v58, v54, v58
	v_div_scale_f32 v54, vcc, v1, v48, v1
	v_mul_f32_e32 v55, v54, v58
	v_fma_f32 v56, -v57, v55, v54
	v_fmac_f32_e32 v55, v56, v58
	v_fma_f32 v54, -v57, v55, v54
	v_div_fmas_f32 v54, v54, v58, v55
	v_div_fixup_f32 v48, v54, v48, v1
	v_pk_mul_f32 v[46:47], v[48:49], v[46:47]
	v_and_b32_e32 v54, 0xffff0000, v66
	v_cvt_pk_bf16_f32 v45, v46, v47
	global_store_dwordx2 v[50:51], v[44:45], off offset:32
	v_lshlrev_b32_e32 v48, 16, v68
	v_and_b32_e32 v49, 0xffff0000, v68
	s_waitcnt vmcnt(2)
	v_add_f32_e32 v1, v40, v188
	v_mul_f32_e32 v1, 0xbfb8aa3b, v1
	v_exp_f32_e32 v40, v1
	v_add_f32_e32 v1, v41, v189
	v_mul_f32_e32 v1, 0xbfb8aa3b, v1
	v_exp_f32_e32 v41, v1
	v_lshlrev_b32_e32 v1, 16, v66
	v_mul_f32_e32 v44, 0xbfb8aa3b, v1
	v_exp_f32_e32 v44, v44
	v_pk_add_f32 v[40:41], v[40:41], 1.0 op_sel_hi:[1,0]
	s_nop 0
	v_div_scale_f32 v45, s[6:7], v41, v41, 1.0
	v_rcp_f32_e32 v55, v45
	s_nop 0
	v_fma_f32 v56, -v45, v55, 1.0
	v_fmac_f32_e32 v55, v56, v55
	v_div_scale_f32 v56, vcc, 1.0, v41, 1.0
	v_mul_f32_e32 v57, v56, v55
	v_fma_f32 v58, -v45, v57, v56
	v_fmac_f32_e32 v57, v58, v55
	v_fma_f32 v45, -v45, v57, v56
	v_div_scale_f32 v56, s[6:7], v40, v40, 1.0
	v_rcp_f32_e32 v58, v56
	v_div_fmas_f32 v45, v45, v55, v57
	v_div_fixup_f32 v41, v45, v41, 1.0
	v_div_scale_f32 v55, vcc, 1.0, v40, 1.0
	v_fma_f32 v45, -v56, v58, 1.0
	v_fmac_f32_e32 v58, v45, v58
	v_mul_f32_e32 v45, 0xbfb8aa3b, v54
	v_exp_f32_e32 v45, v45
	v_mul_f32_e32 v57, v55, v58
	v_fma_f32 v59, -v56, v57, v55
	v_fmac_f32_e32 v57, v59, v58
	v_pk_add_f32 v[44:45], v[44:45], 1.0 op_sel_hi:[1,0]
	v_fma_f32 v55, -v56, v57, v55
	v_div_scale_f32 v56, s[6:7], v45, v45, v54
	v_rcp_f32_e32 v59, v56
	v_div_fmas_f32 v55, v55, v58, v57
	v_div_fixup_f32 v40, v55, v40, 1.0
	v_pk_mul_f32 v[40:41], v[40:41], v[48:49]
	v_fma_f32 v48, -v56, v59, 1.0
	v_fmac_f32_e32 v59, v48, v59
	v_div_scale_f32 v48, vcc, v54, v45, v54
	v_mul_f32_e32 v49, v48, v59
	v_fma_f32 v55, -v56, v49, v48
	v_fmac_f32_e32 v49, v55, v59
	v_div_scale_f32 v55, s[6:7], v44, v44, v1
	v_fma_f32 v48, -v56, v49, v48
	v_rcp_f32_e32 v56, v55
	v_div_fmas_f32 v48, v48, v59, v49
	v_div_fixup_f32 v45, v48, v45, v54
	v_fma_f32 v48, -v55, v56, 1.0
	v_fmac_f32_e32 v56, v48, v56
	v_div_scale_f32 v48, vcc, v1, v44, v1
	v_mul_f32_e32 v49, v48, v56
	v_fma_f32 v54, -v55, v49, v48
	v_fmac_f32_e32 v49, v54, v56
	v_fma_f32 v48, -v55, v49, v48
	v_div_fmas_f32 v48, v48, v56, v49
	v_div_fixup_f32 v44, v48, v44, v1
	v_add_f32_e32 v1, v42, v190
	v_mul_f32_e32 v1, 0xbfb8aa3b, v1
	v_exp_f32_e32 v42, v1
	v_add_f32_e32 v1, v43, v191
	v_mul_f32_e32 v1, 0xbfb8aa3b, v1
	v_exp_f32_e32 v43, v1
	v_pk_mul_f32 v[40:41], v[44:45], v[40:41]
	v_lshlrev_b32_e32 v1, 16, v67
	v_and_b32_e32 v48, 0xffff0000, v67
	v_pk_add_f32 v[42:43], v[42:43], 1.0 op_sel_hi:[1,0]
	v_mul_f32_e32 v44, 0xbfb8aa3b, v1
	v_div_scale_f32 v45, s[6:7], v43, v43, 1.0
	v_rcp_f32_e32 v49, v45
	v_exp_f32_e32 v44, v44
	v_lshlrev_b32_e32 v46, 16, v69
	v_and_b32_e32 v47, 0xffff0000, v69
	v_fma_f32 v54, -v45, v49, 1.0
	v_fmac_f32_e32 v49, v54, v49
	v_div_scale_f32 v54, vcc, 1.0, v43, 1.0
	v_mul_f32_e32 v55, v54, v49
	v_fma_f32 v56, -v45, v55, v54
	v_fmac_f32_e32 v55, v56, v49
	v_fma_f32 v45, -v45, v55, v54
	v_div_scale_f32 v54, s[6:7], v42, v42, 1.0
	v_rcp_f32_e32 v56, v54
	v_div_fmas_f32 v45, v45, v49, v55
	v_div_fixup_f32 v43, v45, v43, 1.0
	v_div_scale_f32 v49, vcc, 1.0, v42, 1.0
	v_fma_f32 v45, -v54, v56, 1.0
	v_fmac_f32_e32 v56, v45, v56
	v_mul_f32_e32 v45, 0xbfb8aa3b, v48
	v_exp_f32_e32 v45, v45
	v_mul_f32_e32 v55, v49, v56
	v_fma_f32 v57, -v54, v55, v49
	v_fmac_f32_e32 v55, v57, v56
	v_pk_add_f32 v[44:45], v[44:45], 1.0 op_sel_hi:[1,0]
	v_fma_f32 v49, -v54, v55, v49
	v_div_scale_f32 v54, s[6:7], v45, v45, v48
	v_rcp_f32_e32 v57, v54
	v_div_fmas_f32 v49, v49, v56, v55
	v_div_fixup_f32 v42, v49, v42, 1.0
	v_pk_mul_f32 v[42:43], v[42:43], v[46:47]
	v_fma_f32 v46, -v54, v57, 1.0
	v_fmac_f32_e32 v57, v46, v57
	v_div_scale_f32 v46, vcc, v48, v45, v48
	v_mul_f32_e32 v47, v46, v57
	v_fma_f32 v49, -v54, v47, v46
	v_fmac_f32_e32 v47, v49, v57
	v_div_scale_f32 v49, s[6:7], v44, v44, v1
	v_fma_f32 v46, -v54, v47, v46
	v_rcp_f32_e32 v54, v49
	v_div_fmas_f32 v46, v46, v57, v47
	v_div_fixup_f32 v45, v46, v45, v48
	v_cvt_pk_bf16_f32 v40, v40, v41
	v_fma_f32 v46, -v49, v54, 1.0
	v_fmac_f32_e32 v54, v46, v54
	v_div_scale_f32 v46, vcc, v1, v44, v1
	v_mul_f32_e32 v47, v46, v54
	v_fma_f32 v48, -v49, v47, v46
	v_fmac_f32_e32 v47, v48, v54
	v_fma_f32 v46, -v49, v47, v46
	v_div_fmas_f32 v46, v46, v54, v47
	v_div_fixup_f32 v44, v46, v44, v1
	v_pk_mul_f32 v[42:43], v[44:45], v[42:43]
	v_lshlrev_b32_e32 v44, 16, v52
	v_cvt_pk_bf16_f32 v41, v42, v43
	global_store_dwordx2 v[50:51], v[40:41], off offset:256
	v_and_b32_e32 v45, 0xffff0000, v52
	v_and_b32_e32 v46, 0xffff0000, v64
	s_waitcnt vmcnt(3)
	v_add_f32_e32 v1, v36, v192
	v_mul_f32_e32 v1, 0xbfb8aa3b, v1
	v_exp_f32_e32 v36, v1
	v_add_f32_e32 v1, v37, v193
	v_mul_f32_e32 v1, 0xbfb8aa3b, v1
	v_exp_f32_e32 v37, v1
	v_lshlrev_b32_e32 v1, 16, v64
	v_mul_f32_e32 v40, 0xbfb8aa3b, v1
	v_exp_f32_e32 v40, v40
	v_pk_add_f32 v[36:37], v[36:37], 1.0 op_sel_hi:[1,0]
	s_nop 0
	v_div_scale_f32 v41, s[6:7], v37, v37, 1.0
	v_rcp_f32_e32 v47, v41
	s_nop 0
	v_fma_f32 v48, -v41, v47, 1.0
	v_fmac_f32_e32 v47, v48, v47
	v_div_scale_f32 v48, vcc, 1.0, v37, 1.0
	v_mul_f32_e32 v49, v48, v47
	v_fma_f32 v52, -v41, v49, v48
	v_fmac_f32_e32 v49, v52, v47
	v_fma_f32 v41, -v41, v49, v48
	v_div_scale_f32 v48, s[6:7], v36, v36, 1.0
	v_rcp_f32_e32 v52, v48
	v_div_fmas_f32 v41, v41, v47, v49
	v_div_fixup_f32 v37, v41, v37, 1.0
	v_div_scale_f32 v47, vcc, 1.0, v36, 1.0
	v_fma_f32 v41, -v48, v52, 1.0
	v_fmac_f32_e32 v52, v41, v52
	v_mul_f32_e32 v41, 0xbfb8aa3b, v46
	v_exp_f32_e32 v41, v41
	v_mul_f32_e32 v49, v47, v52
	v_fma_f32 v54, -v48, v49, v47
	v_fmac_f32_e32 v49, v54, v52
	v_pk_add_f32 v[40:41], v[40:41], 1.0 op_sel_hi:[1,0]
	v_fma_f32 v47, -v48, v49, v47
	v_div_scale_f32 v48, s[6:7], v41, v41, v46
	v_rcp_f32_e32 v54, v48
	v_div_fmas_f32 v47, v47, v52, v49
	v_div_fixup_f32 v36, v47, v36, 1.0
	v_pk_mul_f32 v[36:37], v[36:37], v[44:45]
	v_fma_f32 v44, -v48, v54, 1.0
	v_fmac_f32_e32 v54, v44, v54
	v_div_scale_f32 v44, vcc, v46, v41, v46
	v_mul_f32_e32 v45, v44, v54
	v_fma_f32 v47, -v48, v45, v44
	v_fmac_f32_e32 v45, v47, v54
	v_div_scale_f32 v47, s[6:7], v40, v40, v1
	v_fma_f32 v44, -v48, v45, v44
	v_rcp_f32_e32 v48, v47
	v_div_fmas_f32 v44, v44, v54, v45
	v_div_fixup_f32 v41, v44, v41, v46
	v_fma_f32 v44, -v47, v48, 1.0
	v_fmac_f32_e32 v48, v44, v48
	v_div_scale_f32 v44, vcc, v1, v40, v1
	v_mul_f32_e32 v45, v44, v48
	v_fma_f32 v46, -v47, v45, v44
	v_fmac_f32_e32 v45, v46, v48
	v_fma_f32 v44, -v47, v45, v44
	v_div_fmas_f32 v44, v44, v48, v45
	v_div_fixup_f32 v40, v44, v40, v1
	v_add_f32_e32 v1, v38, v194
	v_mul_f32_e32 v1, 0xbfb8aa3b, v1
	v_exp_f32_e32 v38, v1
	v_add_f32_e32 v1, v39, v195
	v_mul_f32_e32 v1, 0xbfb8aa3b, v1
	v_exp_f32_e32 v39, v1
	v_pk_mul_f32 v[36:37], v[40:41], v[36:37]
	v_lshlrev_b32_e32 v1, 16, v65
	v_and_b32_e32 v44, 0xffff0000, v65
	v_pk_add_f32 v[38:39], v[38:39], 1.0 op_sel_hi:[1,0]
	v_mul_f32_e32 v40, 0xbfb8aa3b, v1
	v_div_scale_f32 v41, s[6:7], v39, v39, 1.0
	v_rcp_f32_e32 v45, v41
	v_exp_f32_e32 v40, v40
	v_lshlrev_b32_e32 v42, 16, v53
	v_and_b32_e32 v43, 0xffff0000, v53
	v_fma_f32 v46, -v41, v45, 1.0
	v_fmac_f32_e32 v45, v46, v45
	v_div_scale_f32 v46, vcc, 1.0, v39, 1.0
	v_mul_f32_e32 v47, v46, v45
	v_fma_f32 v48, -v41, v47, v46
	v_fmac_f32_e32 v47, v48, v45
	v_fma_f32 v41, -v41, v47, v46
	v_div_scale_f32 v46, s[6:7], v38, v38, 1.0
	v_rcp_f32_e32 v48, v46
	v_div_fmas_f32 v41, v41, v45, v47
	v_div_fixup_f32 v39, v41, v39, 1.0
	v_div_scale_f32 v45, vcc, 1.0, v38, 1.0
	v_fma_f32 v41, -v46, v48, 1.0
	v_fmac_f32_e32 v48, v41, v48
	v_mul_f32_e32 v41, 0xbfb8aa3b, v44
	v_exp_f32_e32 v41, v41
	v_mul_f32_e32 v47, v45, v48
	v_fma_f32 v49, -v46, v47, v45
	v_fmac_f32_e32 v47, v49, v48
	v_pk_add_f32 v[40:41], v[40:41], 1.0 op_sel_hi:[1,0]
	v_fma_f32 v45, -v46, v47, v45
	v_div_scale_f32 v46, s[6:7], v41, v41, v44
	v_rcp_f32_e32 v49, v46
	v_div_fmas_f32 v45, v45, v48, v47
	v_div_fixup_f32 v38, v45, v38, 1.0
	v_pk_mul_f32 v[38:39], v[38:39], v[42:43]
	v_fma_f32 v42, -v46, v49, 1.0
	v_fmac_f32_e32 v49, v42, v49
	v_div_scale_f32 v42, vcc, v44, v41, v44
	v_mul_f32_e32 v43, v42, v49
	v_fma_f32 v45, -v46, v43, v42
	v_fmac_f32_e32 v43, v45, v49
	v_div_scale_f32 v45, s[6:7], v40, v40, v1
	v_fma_f32 v42, -v46, v43, v42
	v_rcp_f32_e32 v46, v45
	v_div_fmas_f32 v42, v42, v49, v43
	v_div_fixup_f32 v41, v42, v41, v44
	v_cvt_pk_bf16_f32 v36, v36, v37
	v_fma_f32 v42, -v45, v46, 1.0
	v_fmac_f32_e32 v46, v42, v46
	v_div_scale_f32 v42, vcc, v1, v40, v1
	v_mul_f32_e32 v43, v42, v46
	v_fma_f32 v44, -v45, v43, v42
	v_fmac_f32_e32 v43, v44, v46
	v_fma_f32 v42, -v45, v43, v42
	v_div_fmas_f32 v42, v42, v46, v43
	v_div_fixup_f32 v40, v42, v40, v1
	v_pk_mul_f32 v[38:39], v[40:41], v[38:39]
	v_add_u32_e32 v40, 0xa0, v138
	v_cvt_pk_bf16_f32 v37, v38, v39
	global_store_dwordx2 v[50:51], v[36:37], off offset:288
	v_ashrrev_i32_e32 v41, 31, v40
	v_lshlrev_b64 v[42:43], 13, v[40:41]
	v_lshl_add_u64 v[42:43], s[26:27], 0, v[42:43]
	v_lshl_add_u64 v[48:49], v[42:43], 0, v[136:137]
	global_load_dwordx2 v[44:45], v[48:49], off offset:3072
	v_mad_i64_i32 v[42:43], s[6:7], v40, s81, v[140:141]
	v_lshl_add_u64 v[46:47], v[42:43], 0, v[136:137]
	global_load_dwordx2 v[42:43], v[46:47], off
	v_lshlrev_b64 v[40:41], 12, v[40:41]
	s_waitcnt vmcnt(6)
	v_add_f32_e32 v1, v32, v180
	v_mul_f32_e32 v1, 0xbfb8aa3b, v1
	v_exp_f32_e32 v36, v1
	v_add_f32_e32 v1, v33, v181
	v_mul_f32_e32 v1, 0xbfb8aa3b, v1
	v_exp_f32_e32 v37, v1
	s_waitcnt vmcnt(1)
	v_lshlrev_b32_e32 v1, 16, v44
	v_mul_f32_e32 v52, 0xbfb8aa3b, v1
	global_load_dwordx2 v[32:33], v[48:49], off offset:3104
	global_load_dwordx2 v[50:51], v[48:49], off offset:3328
	s_nop 0
	global_load_dwordx2 v[48:49], v[48:49], off offset:3360
	v_pk_add_f32 v[56:57], v[36:37], 1.0 op_sel_hi:[1,0]
	v_exp_f32_e32 v54, v52
	v_div_scale_f32 v55, s[6:7], v57, v57, 1.0
	v_rcp_f32_e32 v60, v55
	global_load_dwordx2 v[58:59], v[46:47], off offset:32
	global_load_dwordx2 v[52:53], v[46:47], off offset:256
	global_load_dwordx2 v[36:37], v[46:47], off offset:288
	s_waitcnt vmcnt(6)
	v_lshlrev_b32_e32 v46, 16, v42
	v_and_b32_e32 v47, 0xffff0000, v42
	v_fma_f32 v42, -v55, v60, 1.0
	v_fmac_f32_e32 v60, v42, v60
	v_div_scale_f32 v42, vcc, 1.0, v57, 1.0
	v_mul_f32_e32 v61, v42, v60
	v_fma_f32 v62, -v55, v61, v42
	v_fmac_f32_e32 v61, v62, v60
	v_div_scale_f32 v62, s[6:7], v56, v56, 1.0
	v_rcp_f32_e32 v63, v62
	v_and_b32_e32 v44, 0xffff0000, v44
	v_fma_f32 v42, -v55, v61, v42
	v_mul_f32_e32 v55, 0xbfb8aa3b, v44
	v_div_fmas_f32 v42, v42, v60, v61
	v_exp_f32_e32 v55, v55
	v_div_fixup_f32 v57, v42, v57, 1.0
	v_fma_f32 v42, -v62, v63, 1.0
	v_fmac_f32_e32 v63, v42, v63
	v_div_scale_f32 v42, vcc, 1.0, v56, 1.0
	v_mul_f32_e32 v60, v42, v63
	v_fma_f32 v61, -v62, v60, v42
	v_pk_add_f32 v[54:55], v[54:55], 1.0 op_sel_hi:[1,0]
	v_fmac_f32_e32 v60, v61, v63
	v_div_scale_f32 v61, s[6:7], v55, v55, v44
	v_fma_f32 v42, -v62, v60, v42
	v_rcp_f32_e32 v62, v61
	v_div_fmas_f32 v42, v42, v63, v60
	v_div_fixup_f32 v56, v42, v56, 1.0
	v_pk_mul_f32 v[46:47], v[56:57], v[46:47]
	v_fma_f32 v42, -v61, v62, 1.0
	v_fmac_f32_e32 v62, v42, v62
	v_div_scale_f32 v42, vcc, v44, v55, v44
	v_mul_f32_e32 v56, v42, v62
	v_fma_f32 v57, -v61, v56, v42
	v_fmac_f32_e32 v56, v57, v62
	v_div_scale_f32 v57, s[6:7], v54, v54, v1
	v_rcp_f32_e32 v60, v57
	v_fma_f32 v42, -v61, v56, v42
	v_div_fmas_f32 v42, v42, v62, v56
	v_div_fixup_f32 v55, v42, v55, v44
	v_fma_f32 v42, -v57, v60, 1.0
	v_fmac_f32_e32 v60, v42, v60
	v_div_scale_f32 v42, vcc, v1, v54, v1
	v_mul_f32_e32 v44, v42, v60
	v_fma_f32 v56, -v57, v44, v42
	v_fmac_f32_e32 v44, v56, v60
	v_fma_f32 v42, -v57, v44, v42
	v_div_fmas_f32 v42, v42, v60, v44
	v_div_fixup_f32 v54, v42, v54, v1
	v_add_f32_e32 v1, v34, v182
	v_mul_f32_e32 v1, 0xbfb8aa3b, v1
	v_exp_f32_e32 v34, v1
	v_add_f32_e32 v1, v35, v183
	v_mul_f32_e32 v1, 0xbfb8aa3b, v1
	v_exp_f32_e32 v35, v1
	v_lshlrev_b32_e32 v1, 16, v45
	v_and_b32_e32 v44, 0xffff0000, v45
	v_pk_mul_f32 v[46:47], v[54:55], v[46:47]
	v_pk_add_f32 v[34:35], v[34:35], 1.0 op_sel_hi:[1,0]
	v_mul_f32_e32 v38, 0xbfb8aa3b, v1
	v_div_scale_f32 v39, s[6:7], v35, v35, 1.0
	v_rcp_f32_e32 v45, v39
	v_exp_f32_e32 v38, v38
	v_lshlrev_b32_e32 v42, 16, v43
	v_and_b32_e32 v43, 0xffff0000, v43
	v_fma_f32 v54, -v39, v45, 1.0
	v_fmac_f32_e32 v45, v54, v45
	v_div_scale_f32 v54, vcc, 1.0, v35, 1.0
	v_mul_f32_e32 v55, v54, v45
	v_fma_f32 v56, -v39, v55, v54
	v_fmac_f32_e32 v55, v56, v45
	v_fma_f32 v39, -v39, v55, v54
	v_div_scale_f32 v54, s[6:7], v34, v34, 1.0
	v_rcp_f32_e32 v56, v54
	v_div_fmas_f32 v39, v39, v45, v55
	v_div_fixup_f32 v35, v39, v35, 1.0
	v_div_scale_f32 v45, vcc, 1.0, v34, 1.0
	v_fma_f32 v39, -v54, v56, 1.0
	v_fmac_f32_e32 v56, v39, v56
	v_mul_f32_e32 v39, 0xbfb8aa3b, v44
	v_exp_f32_e32 v39, v39
	v_mul_f32_e32 v55, v45, v56
	v_fma_f32 v57, -v54, v55, v45
	v_fmac_f32_e32 v55, v57, v56
	v_pk_add_f32 v[38:39], v[38:39], 1.0 op_sel_hi:[1,0]
	v_fma_f32 v45, -v54, v55, v45
	v_div_scale_f32 v54, s[6:7], v39, v39, v44
	v_rcp_f32_e32 v57, v54
	v_div_fmas_f32 v45, v45, v56, v55
	v_div_fixup_f32 v34, v45, v34, 1.0
	v_pk_mul_f32 v[34:35], v[34:35], v[42:43]
	v_fma_f32 v42, -v54, v57, 1.0
	v_fmac_f32_e32 v57, v42, v57
	v_div_scale_f32 v42, vcc, v44, v39, v44
	v_mul_f32_e32 v43, v42, v57
	v_fma_f32 v45, -v54, v43, v42
	v_fmac_f32_e32 v43, v45, v57
	v_div_scale_f32 v45, s[6:7], v38, v38, v1
	v_fma_f32 v42, -v54, v43, v42
	v_rcp_f32_e32 v54, v45
	v_div_fmas_f32 v42, v42, v57, v43
	v_div_fixup_f32 v39, v42, v39, v44
	v_fma_f32 v42, -v45, v54, 1.0
	v_fmac_f32_e32 v54, v42, v54
	v_div_scale_f32 v42, vcc, v1, v38, v1
	v_mul_f32_e32 v43, v42, v54
	v_fma_f32 v44, -v45, v43, v42
	v_fmac_f32_e32 v43, v44, v54
	v_fma_f32 v42, -v45, v43, v42
	v_div_fmas_f32 v42, v42, v54, v43
	v_div_fixup_f32 v38, v42, v38, v1
	v_pk_mul_f32 v[34:35], v[38:39], v[34:35]
	v_cvt_pk_bf16_f32 v38, v46, v47
	v_cvt_pk_bf16_f32 v39, v34, v35
	v_lshl_add_u64 v[34:35], s[24:25], 0, v[40:41]
	v_lshl_add_u64 v[34:35], v[34:35], 0, v[136:137]
	global_store_dwordx2 v[34:35], v[38:39], off
	s_waitcnt vmcnt(3)
	v_lshlrev_b32_e32 v42, 16, v58
	v_and_b32_e32 v43, 0xffff0000, v58
	s_waitcnt vmcnt(1)
	v_add_f32_e32 v1, v28, v184
	v_mul_f32_e32 v1, 0xbfb8aa3b, v1
	v_exp_f32_e32 v28, v1
	v_add_f32_e32 v1, v29, v185
	v_mul_f32_e32 v1, 0xbfb8aa3b, v1
	v_exp_f32_e32 v29, v1
	v_lshlrev_b32_e32 v1, 16, v32
	v_and_b32_e32 v32, 0xffff0000, v32
	v_mul_f32_e32 v38, 0xbfb8aa3b, v1
	v_pk_add_f32 v[28:29], v[28:29], 1.0 op_sel_hi:[1,0]
	v_exp_f32_e32 v38, v38
	v_div_scale_f32 v39, s[6:7], v29, v29, 1.0
	v_rcp_f32_e32 v44, v39
	s_nop 0
	v_fma_f32 v45, -v39, v44, 1.0
	v_fmac_f32_e32 v44, v45, v44
	v_div_scale_f32 v45, vcc, 1.0, v29, 1.0
	v_mul_f32_e32 v46, v45, v44
	v_fma_f32 v47, -v39, v46, v45
	v_fmac_f32_e32 v46, v47, v44
	v_fma_f32 v39, -v39, v46, v45
	v_div_scale_f32 v45, s[6:7], v28, v28, 1.0
	v_rcp_f32_e32 v47, v45
	v_div_fmas_f32 v39, v39, v44, v46
	v_div_fixup_f32 v29, v39, v29, 1.0
	v_div_scale_f32 v44, vcc, 1.0, v28, 1.0
	v_fma_f32 v39, -v45, v47, 1.0
	v_fmac_f32_e32 v47, v39, v47
	v_mul_f32_e32 v39, 0xbfb8aa3b, v32
	v_exp_f32_e32 v39, v39
	v_mul_f32_e32 v46, v44, v47
	v_fma_f32 v54, -v45, v46, v44
	v_fmac_f32_e32 v46, v54, v47
	v_pk_add_f32 v[38:39], v[38:39], 1.0 op_sel_hi:[1,0]
	v_fma_f32 v44, -v45, v46, v44
	v_div_scale_f32 v45, s[6:7], v39, v39, v32
	v_rcp_f32_e32 v54, v45
	v_div_fmas_f32 v44, v44, v47, v46
	v_div_fixup_f32 v28, v44, v28, 1.0
	v_pk_mul_f32 v[28:29], v[28:29], v[42:43]
	v_fma_f32 v42, -v45, v54, 1.0
	v_fmac_f32_e32 v54, v42, v54
	v_div_scale_f32 v42, vcc, v32, v39, v32
	v_mul_f32_e32 v43, v42, v54
	v_fma_f32 v44, -v45, v43, v42
	v_fmac_f32_e32 v43, v44, v54
	v_div_scale_f32 v44, s[6:7], v38, v38, v1
	v_fma_f32 v42, -v45, v43, v42
	v_rcp_f32_e32 v45, v44
	v_div_fmas_f32 v42, v42, v54, v43
	v_div_fixup_f32 v39, v42, v39, v32
	v_fma_f32 v32, -v44, v45, 1.0
	v_fmac_f32_e32 v45, v32, v45
	v_div_scale_f32 v32, vcc, v1, v38, v1
	v_mul_f32_e32 v42, v32, v45
	v_fma_f32 v43, -v44, v42, v32
	v_fmac_f32_e32 v42, v43, v45
	v_fma_f32 v32, -v44, v42, v32
	v_div_fmas_f32 v32, v32, v45, v42
	v_div_fixup_f32 v38, v32, v38, v1
	v_add_f32_e32 v1, v30, v186
	v_mul_f32_e32 v1, 0xbfb8aa3b, v1
	v_exp_f32_e32 v30, v1
	v_add_f32_e32 v1, v31, v187
	v_mul_f32_e32 v1, 0xbfb8aa3b, v1
	v_exp_f32_e32 v31, v1
	v_lshlrev_b32_e32 v1, 16, v33
	v_and_b32_e32 v40, 0xffff0000, v33
	v_mul_f32_e32 v32, 0xbfb8aa3b, v1
	v_pk_add_f32 v[30:31], v[30:31], 1.0 op_sel_hi:[1,0]
	v_exp_f32_e32 v32, v32
	v_div_scale_f32 v33, s[6:7], v31, v31, 1.0
	v_rcp_f32_e32 v41, v33
	v_pk_mul_f32 v[28:29], v[38:39], v[28:29]
	v_lshlrev_b32_e32 v38, 16, v59
	v_and_b32_e32 v39, 0xffff0000, v59
	v_fma_f32 v42, -v33, v41, 1.0
	v_fmac_f32_e32 v41, v42, v41
	v_div_scale_f32 v42, vcc, 1.0, v31, 1.0
	v_mul_f32_e32 v43, v42, v41
	v_fma_f32 v44, -v33, v43, v42
	v_fmac_f32_e32 v43, v44, v41
	v_fma_f32 v33, -v33, v43, v42
	v_div_scale_f32 v42, s[6:7], v30, v30, 1.0
	v_rcp_f32_e32 v44, v42
	v_div_fmas_f32 v33, v33, v41, v43
	v_div_fixup_f32 v31, v33, v31, 1.0
	v_div_scale_f32 v41, vcc, 1.0, v30, 1.0
	v_fma_f32 v33, -v42, v44, 1.0
	v_fmac_f32_e32 v44, v33, v44
	v_mul_f32_e32 v33, 0xbfb8aa3b, v40
	v_exp_f32_e32 v33, v33
	v_mul_f32_e32 v43, v41, v44
	v_fma_f32 v45, -v42, v43, v41
	v_fmac_f32_e32 v43, v45, v44
	v_pk_add_f32 v[32:33], v[32:33], 1.0 op_sel_hi:[1,0]
	v_fma_f32 v41, -v42, v43, v41
	v_div_scale_f32 v42, s[6:7], v33, v33, v40
	v_rcp_f32_e32 v45, v42
	v_div_fmas_f32 v41, v41, v44, v43
	v_div_fixup_f32 v30, v41, v30, 1.0
	v_pk_mul_f32 v[30:31], v[30:31], v[38:39]
	v_fma_f32 v38, -v42, v45, 1.0
	v_fmac_f32_e32 v45, v38, v45
	v_div_scale_f32 v38, vcc, v40, v33, v40
	v_mul_f32_e32 v39, v38, v45
	v_fma_f32 v41, -v42, v39, v38
	v_fmac_f32_e32 v39, v41, v45
	v_div_scale_f32 v41, s[6:7], v32, v32, v1
	v_fma_f32 v38, -v42, v39, v38
	v_rcp_f32_e32 v42, v41
	v_div_fmas_f32 v38, v38, v45, v39
	v_div_fixup_f32 v33, v38, v33, v40
	v_cvt_pk_bf16_f32 v28, v28, v29
	v_fma_f32 v38, -v41, v42, 1.0
	v_fmac_f32_e32 v42, v38, v42
	v_div_scale_f32 v38, vcc, v1, v32, v1
	v_mul_f32_e32 v39, v38, v42
	v_fma_f32 v40, -v41, v39, v38
	v_fmac_f32_e32 v39, v40, v42
	v_fma_f32 v38, -v41, v39, v38
	v_div_fmas_f32 v38, v38, v42, v39
	v_div_fixup_f32 v32, v38, v32, v1
	v_pk_mul_f32 v[30:31], v[32:33], v[30:31]
	v_and_b32_e32 v38, 0xffff0000, v50
	v_cvt_pk_bf16_f32 v29, v30, v31
	global_store_dwordx2 v[34:35], v[28:29], off offset:32
	v_lshlrev_b32_e32 v32, 16, v52
	v_and_b32_e32 v33, 0xffff0000, v52
	s_waitcnt vmcnt(2)
	v_add_f32_e32 v1, v24, v188
	v_mul_f32_e32 v1, 0xbfb8aa3b, v1
	v_exp_f32_e32 v24, v1
	v_add_f32_e32 v1, v25, v189
	v_mul_f32_e32 v1, 0xbfb8aa3b, v1
	v_exp_f32_e32 v25, v1
	v_lshlrev_b32_e32 v1, 16, v50
	v_mul_f32_e32 v28, 0xbfb8aa3b, v1
	v_exp_f32_e32 v28, v28
	v_pk_add_f32 v[24:25], v[24:25], 1.0 op_sel_hi:[1,0]
	s_nop 0
	v_div_scale_f32 v29, s[6:7], v25, v25, 1.0
	v_rcp_f32_e32 v39, v29
	s_nop 0
	v_fma_f32 v40, -v29, v39, 1.0
	v_fmac_f32_e32 v39, v40, v39
	v_div_scale_f32 v40, vcc, 1.0, v25, 1.0
	v_mul_f32_e32 v41, v40, v39
	v_fma_f32 v42, -v29, v41, v40
	v_fmac_f32_e32 v41, v42, v39
	v_fma_f32 v29, -v29, v41, v40
	v_div_scale_f32 v40, s[6:7], v24, v24, 1.0
	v_rcp_f32_e32 v42, v40
	v_div_fmas_f32 v29, v29, v39, v41
	v_div_fixup_f32 v25, v29, v25, 1.0
	v_div_scale_f32 v39, vcc, 1.0, v24, 1.0
	v_fma_f32 v29, -v40, v42, 1.0
	v_fmac_f32_e32 v42, v29, v42
	v_mul_f32_e32 v29, 0xbfb8aa3b, v38
	v_exp_f32_e32 v29, v29
	v_mul_f32_e32 v41, v39, v42
	v_fma_f32 v43, -v40, v41, v39
	v_fmac_f32_e32 v41, v43, v42
	v_pk_add_f32 v[28:29], v[28:29], 1.0 op_sel_hi:[1,0]
	v_fma_f32 v39, -v40, v41, v39
	v_div_scale_f32 v40, s[6:7], v29, v29, v38
	v_rcp_f32_e32 v43, v40
	v_div_fmas_f32 v39, v39, v42, v41
	v_div_fixup_f32 v24, v39, v24, 1.0
	v_pk_mul_f32 v[24:25], v[24:25], v[32:33]
	v_fma_f32 v32, -v40, v43, 1.0
	v_fmac_f32_e32 v43, v32, v43
	v_div_scale_f32 v32, vcc, v38, v29, v38
	v_mul_f32_e32 v33, v32, v43
	v_fma_f32 v39, -v40, v33, v32
	v_fmac_f32_e32 v33, v39, v43
	v_div_scale_f32 v39, s[6:7], v28, v28, v1
	v_fma_f32 v32, -v40, v33, v32
	v_rcp_f32_e32 v40, v39
	v_div_fmas_f32 v32, v32, v43, v33
	v_div_fixup_f32 v29, v32, v29, v38
	v_fma_f32 v32, -v39, v40, 1.0
	v_fmac_f32_e32 v40, v32, v40
	v_div_scale_f32 v32, vcc, v1, v28, v1
	v_mul_f32_e32 v33, v32, v40
	v_fma_f32 v38, -v39, v33, v32
	v_fmac_f32_e32 v33, v38, v40
	v_fma_f32 v32, -v39, v33, v32
	v_div_fmas_f32 v32, v32, v40, v33
	v_div_fixup_f32 v28, v32, v28, v1
	v_add_f32_e32 v1, v26, v190
	v_mul_f32_e32 v1, 0xbfb8aa3b, v1
	v_exp_f32_e32 v26, v1
	v_add_f32_e32 v1, v27, v191
	v_mul_f32_e32 v1, 0xbfb8aa3b, v1
	v_exp_f32_e32 v27, v1
	v_pk_mul_f32 v[24:25], v[28:29], v[24:25]
	v_lshlrev_b32_e32 v1, 16, v51
	v_and_b32_e32 v32, 0xffff0000, v51
	v_pk_add_f32 v[26:27], v[26:27], 1.0 op_sel_hi:[1,0]
	v_mul_f32_e32 v28, 0xbfb8aa3b, v1
	v_div_scale_f32 v29, s[6:7], v27, v27, 1.0
	v_rcp_f32_e32 v33, v29
	v_exp_f32_e32 v28, v28
	v_lshlrev_b32_e32 v30, 16, v53
	v_and_b32_e32 v31, 0xffff0000, v53
	v_fma_f32 v38, -v29, v33, 1.0
	v_fmac_f32_e32 v33, v38, v33
	v_div_scale_f32 v38, vcc, 1.0, v27, 1.0
	v_mul_f32_e32 v39, v38, v33
	v_fma_f32 v40, -v29, v39, v38
	v_fmac_f32_e32 v39, v40, v33
	v_fma_f32 v29, -v29, v39, v38
	v_div_scale_f32 v38, s[6:7], v26, v26, 1.0
	v_rcp_f32_e32 v40, v38
	v_div_fmas_f32 v29, v29, v33, v39
	v_div_fixup_f32 v27, v29, v27, 1.0
	v_div_scale_f32 v33, vcc, 1.0, v26, 1.0
	v_fma_f32 v29, -v38, v40, 1.0
	v_fmac_f32_e32 v40, v29, v40
	v_mul_f32_e32 v29, 0xbfb8aa3b, v32
	v_exp_f32_e32 v29, v29
	v_mul_f32_e32 v39, v33, v40
	v_fma_f32 v41, -v38, v39, v33
	v_fmac_f32_e32 v39, v41, v40
	v_pk_add_f32 v[28:29], v[28:29], 1.0 op_sel_hi:[1,0]
	v_fma_f32 v33, -v38, v39, v33
	v_div_scale_f32 v38, s[6:7], v29, v29, v32
	v_rcp_f32_e32 v41, v38
	v_div_fmas_f32 v33, v33, v40, v39
	v_div_fixup_f32 v26, v33, v26, 1.0
	v_pk_mul_f32 v[26:27], v[26:27], v[30:31]
	v_fma_f32 v30, -v38, v41, 1.0
	v_fmac_f32_e32 v41, v30, v41
	v_div_scale_f32 v30, vcc, v32, v29, v32
	v_mul_f32_e32 v31, v30, v41
	v_fma_f32 v33, -v38, v31, v30
	v_fmac_f32_e32 v31, v33, v41
	v_div_scale_f32 v33, s[6:7], v28, v28, v1
	v_fma_f32 v30, -v38, v31, v30
	v_rcp_f32_e32 v38, v33
	v_div_fmas_f32 v30, v30, v41, v31
	v_div_fixup_f32 v29, v30, v29, v32
	v_cvt_pk_bf16_f32 v24, v24, v25
	v_fma_f32 v30, -v33, v38, 1.0
	v_fmac_f32_e32 v38, v30, v38
	v_div_scale_f32 v30, vcc, v1, v28, v1
	v_mul_f32_e32 v31, v30, v38
	v_fma_f32 v32, -v33, v31, v30
	v_fmac_f32_e32 v31, v32, v38
	v_fma_f32 v30, -v33, v31, v30
	v_div_fmas_f32 v30, v30, v38, v31
	v_div_fixup_f32 v28, v30, v28, v1
	v_pk_mul_f32 v[26:27], v[28:29], v[26:27]
	v_lshlrev_b32_e32 v28, 16, v36
	v_cvt_pk_bf16_f32 v25, v26, v27
	global_store_dwordx2 v[34:35], v[24:25], off offset:256
	v_and_b32_e32 v29, 0xffff0000, v36
	v_and_b32_e32 v30, 0xffff0000, v48
	s_waitcnt vmcnt(3)
	v_add_f32_e32 v1, v20, v192
	v_mul_f32_e32 v1, 0xbfb8aa3b, v1
	v_exp_f32_e32 v20, v1
	v_add_f32_e32 v1, v21, v193
	v_mul_f32_e32 v1, 0xbfb8aa3b, v1
	v_exp_f32_e32 v21, v1
	v_lshlrev_b32_e32 v1, 16, v48
	v_mul_f32_e32 v24, 0xbfb8aa3b, v1
	v_exp_f32_e32 v24, v24
	v_pk_add_f32 v[20:21], v[20:21], 1.0 op_sel_hi:[1,0]
	s_nop 0
	v_div_scale_f32 v25, s[6:7], v21, v21, 1.0
	v_rcp_f32_e32 v31, v25
	s_nop 0
	v_fma_f32 v32, -v25, v31, 1.0
	v_fmac_f32_e32 v31, v32, v31
	v_div_scale_f32 v32, vcc, 1.0, v21, 1.0
	v_mul_f32_e32 v33, v32, v31
	v_fma_f32 v36, -v25, v33, v32
	v_fmac_f32_e32 v33, v36, v31
	v_fma_f32 v25, -v25, v33, v32
	v_div_scale_f32 v32, s[6:7], v20, v20, 1.0
	v_rcp_f32_e32 v36, v32
	v_div_fmas_f32 v25, v25, v31, v33
	v_div_fixup_f32 v21, v25, v21, 1.0
	v_div_scale_f32 v31, vcc, 1.0, v20, 1.0
	v_fma_f32 v25, -v32, v36, 1.0
	v_fmac_f32_e32 v36, v25, v36
	v_mul_f32_e32 v25, 0xbfb8aa3b, v30
	v_exp_f32_e32 v25, v25
	v_mul_f32_e32 v33, v31, v36
	v_fma_f32 v38, -v32, v33, v31
	v_fmac_f32_e32 v33, v38, v36
	v_pk_add_f32 v[24:25], v[24:25], 1.0 op_sel_hi:[1,0]
	v_fma_f32 v31, -v32, v33, v31
	v_div_scale_f32 v32, s[6:7], v25, v25, v30
	v_rcp_f32_e32 v38, v32
	v_div_fmas_f32 v31, v31, v36, v33
	v_div_fixup_f32 v20, v31, v20, 1.0
	v_pk_mul_f32 v[20:21], v[20:21], v[28:29]
	v_fma_f32 v28, -v32, v38, 1.0
	v_fmac_f32_e32 v38, v28, v38
	v_div_scale_f32 v28, vcc, v30, v25, v30
	v_mul_f32_e32 v29, v28, v38
	v_fma_f32 v31, -v32, v29, v28
	v_fmac_f32_e32 v29, v31, v38
	v_div_scale_f32 v31, s[6:7], v24, v24, v1
	v_fma_f32 v28, -v32, v29, v28
	v_rcp_f32_e32 v32, v31
	v_div_fmas_f32 v28, v28, v38, v29
	v_div_fixup_f32 v25, v28, v25, v30
	v_fma_f32 v28, -v31, v32, 1.0
	v_fmac_f32_e32 v32, v28, v32
	v_div_scale_f32 v28, vcc, v1, v24, v1
	v_mul_f32_e32 v29, v28, v32
	v_fma_f32 v30, -v31, v29, v28
	v_fmac_f32_e32 v29, v30, v32
	v_fma_f32 v28, -v31, v29, v28
	v_div_fmas_f32 v28, v28, v32, v29
	v_div_fixup_f32 v24, v28, v24, v1
	v_add_f32_e32 v1, v22, v194
	v_mul_f32_e32 v1, 0xbfb8aa3b, v1
	v_exp_f32_e32 v22, v1
	v_add_f32_e32 v1, v23, v195
	v_mul_f32_e32 v1, 0xbfb8aa3b, v1
	v_exp_f32_e32 v23, v1
	v_pk_mul_f32 v[20:21], v[24:25], v[20:21]
	v_lshlrev_b32_e32 v1, 16, v49
	v_and_b32_e32 v28, 0xffff0000, v49
	v_pk_add_f32 v[22:23], v[22:23], 1.0 op_sel_hi:[1,0]
	v_mul_f32_e32 v24, 0xbfb8aa3b, v1
	v_div_scale_f32 v25, s[6:7], v23, v23, 1.0
	v_rcp_f32_e32 v29, v25
	v_exp_f32_e32 v24, v24
	v_lshlrev_b32_e32 v26, 16, v37
	v_and_b32_e32 v27, 0xffff0000, v37
	v_fma_f32 v30, -v25, v29, 1.0
	v_fmac_f32_e32 v29, v30, v29
	v_div_scale_f32 v30, vcc, 1.0, v23, 1.0
	v_mul_f32_e32 v31, v30, v29
	v_fma_f32 v32, -v25, v31, v30
	v_fmac_f32_e32 v31, v32, v29
	v_fma_f32 v25, -v25, v31, v30
	v_div_scale_f32 v30, s[6:7], v22, v22, 1.0
	v_rcp_f32_e32 v32, v30
	v_div_fmas_f32 v25, v25, v29, v31
	v_div_fixup_f32 v23, v25, v23, 1.0
	v_div_scale_f32 v29, vcc, 1.0, v22, 1.0
	v_fma_f32 v25, -v30, v32, 1.0
	v_fmac_f32_e32 v32, v25, v32
	v_mul_f32_e32 v25, 0xbfb8aa3b, v28
	v_exp_f32_e32 v25, v25
	v_mul_f32_e32 v31, v29, v32
	v_fma_f32 v33, -v30, v31, v29
	v_fmac_f32_e32 v31, v33, v32
	v_pk_add_f32 v[24:25], v[24:25], 1.0 op_sel_hi:[1,0]
	v_fma_f32 v29, -v30, v31, v29
	v_div_scale_f32 v30, s[6:7], v25, v25, v28
	v_rcp_f32_e32 v33, v30
	v_div_fmas_f32 v29, v29, v32, v31
	v_div_fixup_f32 v22, v29, v22, 1.0
	v_pk_mul_f32 v[22:23], v[22:23], v[26:27]
	v_fma_f32 v26, -v30, v33, 1.0
	v_fmac_f32_e32 v33, v26, v33
	v_div_scale_f32 v26, vcc, v28, v25, v28
	v_mul_f32_e32 v27, v26, v33
	v_fma_f32 v29, -v30, v27, v26
	v_fmac_f32_e32 v27, v29, v33
	v_div_scale_f32 v29, s[6:7], v24, v24, v1
	v_fma_f32 v26, -v30, v27, v26
	v_rcp_f32_e32 v30, v29
	v_div_fmas_f32 v26, v26, v33, v27
	v_div_fixup_f32 v25, v26, v25, v28
	v_cvt_pk_bf16_f32 v20, v20, v21
	v_fma_f32 v26, -v29, v30, 1.0
	v_fmac_f32_e32 v30, v26, v30
	v_div_scale_f32 v26, vcc, v1, v24, v1
	v_mul_f32_e32 v27, v26, v30
	v_fma_f32 v28, -v29, v27, v26
	v_fmac_f32_e32 v27, v28, v30
	v_fma_f32 v26, -v29, v27, v26
	v_div_fmas_f32 v26, v26, v30, v27
	v_div_fixup_f32 v24, v26, v24, v1
	v_pk_mul_f32 v[22:23], v[24:25], v[22:23]
	v_add_u32_e32 v24, 0xb0, v138
	v_cvt_pk_bf16_f32 v21, v22, v23
	global_store_dwordx2 v[34:35], v[20:21], off offset:288
	v_ashrrev_i32_e32 v25, 31, v24
	v_lshlrev_b64 v[26:27], 13, v[24:25]
	v_lshl_add_u64 v[26:27], s[26:27], 0, v[26:27]
	v_lshl_add_u64 v[32:33], v[26:27], 0, v[136:137]
	global_load_dwordx2 v[28:29], v[32:33], off offset:3072
	v_mad_i64_i32 v[26:27], s[6:7], v24, s81, v[140:141]
	v_lshl_add_u64 v[30:31], v[26:27], 0, v[136:137]
	global_load_dwordx2 v[26:27], v[30:31], off
	v_lshlrev_b64 v[24:25], 12, v[24:25]
	s_waitcnt vmcnt(6)
	v_add_f32_e32 v1, v16, v180
	v_mul_f32_e32 v1, 0xbfb8aa3b, v1
	v_exp_f32_e32 v20, v1
	v_add_f32_e32 v1, v17, v181
	v_mul_f32_e32 v1, 0xbfb8aa3b, v1
	v_exp_f32_e32 v21, v1
	s_waitcnt vmcnt(1)
	v_lshlrev_b32_e32 v1, 16, v28
	v_mul_f32_e32 v36, 0xbfb8aa3b, v1
	global_load_dwordx2 v[16:17], v[32:33], off offset:3104
	global_load_dwordx2 v[34:35], v[32:33], off offset:3328
	s_nop 0
	global_load_dwordx2 v[32:33], v[32:33], off offset:3360
	v_pk_add_f32 v[40:41], v[20:21], 1.0 op_sel_hi:[1,0]
	v_exp_f32_e32 v38, v36
	v_div_scale_f32 v39, s[6:7], v41, v41, 1.0
	v_rcp_f32_e32 v44, v39
	global_load_dwordx2 v[42:43], v[30:31], off offset:32
	global_load_dwordx2 v[36:37], v[30:31], off offset:256
	global_load_dwordx2 v[20:21], v[30:31], off offset:288
	s_waitcnt vmcnt(6)
	v_lshlrev_b32_e32 v30, 16, v26
	v_and_b32_e32 v31, 0xffff0000, v26
	v_fma_f32 v26, -v39, v44, 1.0
	v_fmac_f32_e32 v44, v26, v44
	v_div_scale_f32 v26, vcc, 1.0, v41, 1.0
	v_mul_f32_e32 v45, v26, v44
	v_fma_f32 v46, -v39, v45, v26
	v_fmac_f32_e32 v45, v46, v44
	v_div_scale_f32 v46, s[6:7], v40, v40, 1.0
	v_rcp_f32_e32 v47, v46
	v_and_b32_e32 v28, 0xffff0000, v28
	v_fma_f32 v26, -v39, v45, v26
	v_mul_f32_e32 v39, 0xbfb8aa3b, v28
	v_div_fmas_f32 v26, v26, v44, v45
	v_exp_f32_e32 v39, v39
	v_div_fixup_f32 v41, v26, v41, 1.0
	v_fma_f32 v26, -v46, v47, 1.0
	v_fmac_f32_e32 v47, v26, v47
	v_div_scale_f32 v26, vcc, 1.0, v40, 1.0
	v_mul_f32_e32 v44, v26, v47
	v_fma_f32 v45, -v46, v44, v26
	v_pk_add_f32 v[38:39], v[38:39], 1.0 op_sel_hi:[1,0]
	v_fmac_f32_e32 v44, v45, v47
	v_div_scale_f32 v45, s[6:7], v39, v39, v28
	v_fma_f32 v26, -v46, v44, v26
	v_rcp_f32_e32 v46, v45
	v_div_fmas_f32 v26, v26, v47, v44
	v_div_fixup_f32 v40, v26, v40, 1.0
	v_pk_mul_f32 v[30:31], v[40:41], v[30:31]
	v_fma_f32 v26, -v45, v46, 1.0
	v_fmac_f32_e32 v46, v26, v46
	v_div_scale_f32 v26, vcc, v28, v39, v28
	v_mul_f32_e32 v40, v26, v46
	v_fma_f32 v41, -v45, v40, v26
	v_fmac_f32_e32 v40, v41, v46
	v_div_scale_f32 v41, s[6:7], v38, v38, v1
	v_rcp_f32_e32 v44, v41
	v_fma_f32 v26, -v45, v40, v26
	v_div_fmas_f32 v26, v26, v46, v40
	v_div_fixup_f32 v39, v26, v39, v28
	v_fma_f32 v26, -v41, v44, 1.0
	v_fmac_f32_e32 v44, v26, v44
	v_div_scale_f32 v26, vcc, v1, v38, v1
	v_mul_f32_e32 v28, v26, v44
	v_fma_f32 v40, -v41, v28, v26
	v_fmac_f32_e32 v28, v40, v44
	v_fma_f32 v26, -v41, v28, v26
	v_div_fmas_f32 v26, v26, v44, v28
	v_div_fixup_f32 v38, v26, v38, v1
	v_add_f32_e32 v1, v18, v182
	v_mul_f32_e32 v1, 0xbfb8aa3b, v1
	v_exp_f32_e32 v18, v1
	v_add_f32_e32 v1, v19, v183
	v_mul_f32_e32 v1, 0xbfb8aa3b, v1
	v_exp_f32_e32 v19, v1
	v_lshlrev_b32_e32 v1, 16, v29
	v_and_b32_e32 v28, 0xffff0000, v29
	v_pk_mul_f32 v[30:31], v[38:39], v[30:31]
	v_pk_add_f32 v[18:19], v[18:19], 1.0 op_sel_hi:[1,0]
	v_mul_f32_e32 v22, 0xbfb8aa3b, v1
	v_div_scale_f32 v23, s[6:7], v19, v19, 1.0
	v_rcp_f32_e32 v29, v23
	v_exp_f32_e32 v22, v22
	v_lshlrev_b32_e32 v26, 16, v27
	v_and_b32_e32 v27, 0xffff0000, v27
	v_fma_f32 v38, -v23, v29, 1.0
	v_fmac_f32_e32 v29, v38, v29
	v_div_scale_f32 v38, vcc, 1.0, v19, 1.0
	v_mul_f32_e32 v39, v38, v29
	v_fma_f32 v40, -v23, v39, v38
	v_fmac_f32_e32 v39, v40, v29
	v_fma_f32 v23, -v23, v39, v38
	v_div_scale_f32 v38, s[6:7], v18, v18, 1.0
	v_rcp_f32_e32 v40, v38
	v_div_fmas_f32 v23, v23, v29, v39
	v_div_fixup_f32 v19, v23, v19, 1.0
	v_div_scale_f32 v29, vcc, 1.0, v18, 1.0
	v_fma_f32 v23, -v38, v40, 1.0
	v_fmac_f32_e32 v40, v23, v40
	v_mul_f32_e32 v23, 0xbfb8aa3b, v28
	v_exp_f32_e32 v23, v23
	v_mul_f32_e32 v39, v29, v40
	v_fma_f32 v41, -v38, v39, v29
	v_fmac_f32_e32 v39, v41, v40
	v_pk_add_f32 v[22:23], v[22:23], 1.0 op_sel_hi:[1,0]
	v_fma_f32 v29, -v38, v39, v29
	v_div_scale_f32 v38, s[6:7], v23, v23, v28
	v_rcp_f32_e32 v41, v38
	v_div_fmas_f32 v29, v29, v40, v39
	v_div_fixup_f32 v18, v29, v18, 1.0
	v_pk_mul_f32 v[18:19], v[18:19], v[26:27]
	v_fma_f32 v26, -v38, v41, 1.0
	v_fmac_f32_e32 v41, v26, v41
	v_div_scale_f32 v26, vcc, v28, v23, v28
	v_mul_f32_e32 v27, v26, v41
	v_fma_f32 v29, -v38, v27, v26
	v_fmac_f32_e32 v27, v29, v41
	v_div_scale_f32 v29, s[6:7], v22, v22, v1
	v_fma_f32 v26, -v38, v27, v26
	v_rcp_f32_e32 v38, v29
	v_div_fmas_f32 v26, v26, v41, v27
	v_div_fixup_f32 v23, v26, v23, v28
	v_fma_f32 v26, -v29, v38, 1.0
	v_fmac_f32_e32 v38, v26, v38
	v_div_scale_f32 v26, vcc, v1, v22, v1
	v_mul_f32_e32 v27, v26, v38
	v_fma_f32 v28, -v29, v27, v26
	v_fmac_f32_e32 v27, v28, v38
	v_fma_f32 v26, -v29, v27, v26
	v_div_fmas_f32 v26, v26, v38, v27
	v_div_fixup_f32 v22, v26, v22, v1
	v_pk_mul_f32 v[18:19], v[22:23], v[18:19]
	v_cvt_pk_bf16_f32 v22, v30, v31
	v_cvt_pk_bf16_f32 v23, v18, v19
	v_lshl_add_u64 v[18:19], s[24:25], 0, v[24:25]
	v_lshl_add_u64 v[18:19], v[18:19], 0, v[136:137]
	global_store_dwordx2 v[18:19], v[22:23], off
	s_waitcnt vmcnt(3)
	v_lshlrev_b32_e32 v26, 16, v42
	v_and_b32_e32 v27, 0xffff0000, v42
	s_waitcnt vmcnt(1)
	v_add_f32_e32 v1, v12, v184
	v_mul_f32_e32 v1, 0xbfb8aa3b, v1
	v_exp_f32_e32 v12, v1
	v_add_f32_e32 v1, v13, v185
	v_mul_f32_e32 v1, 0xbfb8aa3b, v1
	v_exp_f32_e32 v13, v1
	v_lshlrev_b32_e32 v1, 16, v16
	v_and_b32_e32 v16, 0xffff0000, v16
	v_mul_f32_e32 v22, 0xbfb8aa3b, v1
	v_pk_add_f32 v[12:13], v[12:13], 1.0 op_sel_hi:[1,0]
	v_exp_f32_e32 v22, v22
	v_div_scale_f32 v23, s[6:7], v13, v13, 1.0
	v_rcp_f32_e32 v28, v23
	s_nop 0
	v_fma_f32 v29, -v23, v28, 1.0
	v_fmac_f32_e32 v28, v29, v28
	v_div_scale_f32 v29, vcc, 1.0, v13, 1.0
	v_mul_f32_e32 v30, v29, v28
	v_fma_f32 v31, -v23, v30, v29
	v_fmac_f32_e32 v30, v31, v28
	v_fma_f32 v23, -v23, v30, v29
	v_div_scale_f32 v29, s[6:7], v12, v12, 1.0
	v_rcp_f32_e32 v31, v29
	v_div_fmas_f32 v23, v23, v28, v30
	v_div_fixup_f32 v13, v23, v13, 1.0
	v_div_scale_f32 v28, vcc, 1.0, v12, 1.0
	v_fma_f32 v23, -v29, v31, 1.0
	v_fmac_f32_e32 v31, v23, v31
	v_mul_f32_e32 v23, 0xbfb8aa3b, v16
	v_exp_f32_e32 v23, v23
	v_mul_f32_e32 v30, v28, v31
	v_fma_f32 v38, -v29, v30, v28
	v_fmac_f32_e32 v30, v38, v31
	v_pk_add_f32 v[22:23], v[22:23], 1.0 op_sel_hi:[1,0]
	v_fma_f32 v28, -v29, v30, v28
	v_div_scale_f32 v29, s[6:7], v23, v23, v16
	v_rcp_f32_e32 v38, v29
	v_div_fmas_f32 v28, v28, v31, v30
	v_div_fixup_f32 v12, v28, v12, 1.0
	v_pk_mul_f32 v[12:13], v[12:13], v[26:27]
	v_fma_f32 v26, -v29, v38, 1.0
	v_fmac_f32_e32 v38, v26, v38
	v_div_scale_f32 v26, vcc, v16, v23, v16
	v_mul_f32_e32 v27, v26, v38
	v_fma_f32 v28, -v29, v27, v26
	v_fmac_f32_e32 v27, v28, v38
	v_div_scale_f32 v28, s[6:7], v22, v22, v1
	v_fma_f32 v26, -v29, v27, v26
	v_rcp_f32_e32 v29, v28
	v_div_fmas_f32 v26, v26, v38, v27
	v_div_fixup_f32 v23, v26, v23, v16
	v_fma_f32 v16, -v28, v29, 1.0
	v_fmac_f32_e32 v29, v16, v29
	v_div_scale_f32 v16, vcc, v1, v22, v1
	v_mul_f32_e32 v26, v16, v29
	v_fma_f32 v27, -v28, v26, v16
	v_fmac_f32_e32 v26, v27, v29
	v_fma_f32 v16, -v28, v26, v16
	v_div_fmas_f32 v16, v16, v29, v26
	v_div_fixup_f32 v22, v16, v22, v1
	v_add_f32_e32 v1, v14, v186
	v_mul_f32_e32 v1, 0xbfb8aa3b, v1
	v_exp_f32_e32 v14, v1
	v_add_f32_e32 v1, v15, v187
	v_mul_f32_e32 v1, 0xbfb8aa3b, v1
	v_exp_f32_e32 v15, v1
	v_lshlrev_b32_e32 v1, 16, v17
	v_and_b32_e32 v24, 0xffff0000, v17
	v_mul_f32_e32 v16, 0xbfb8aa3b, v1
	v_pk_add_f32 v[14:15], v[14:15], 1.0 op_sel_hi:[1,0]
	v_exp_f32_e32 v16, v16
	v_div_scale_f32 v17, s[6:7], v15, v15, 1.0
	v_rcp_f32_e32 v25, v17
	v_pk_mul_f32 v[12:13], v[22:23], v[12:13]
	v_lshlrev_b32_e32 v22, 16, v43
	v_and_b32_e32 v23, 0xffff0000, v43
	v_fma_f32 v26, -v17, v25, 1.0
	v_fmac_f32_e32 v25, v26, v25
	v_div_scale_f32 v26, vcc, 1.0, v15, 1.0
	v_mul_f32_e32 v27, v26, v25
	v_fma_f32 v28, -v17, v27, v26
	v_fmac_f32_e32 v27, v28, v25
	v_fma_f32 v17, -v17, v27, v26
	v_div_scale_f32 v26, s[6:7], v14, v14, 1.0
	v_rcp_f32_e32 v28, v26
	v_div_fmas_f32 v17, v17, v25, v27
	v_div_fixup_f32 v15, v17, v15, 1.0
	v_div_scale_f32 v25, vcc, 1.0, v14, 1.0
	v_fma_f32 v17, -v26, v28, 1.0
	v_fmac_f32_e32 v28, v17, v28
	v_mul_f32_e32 v17, 0xbfb8aa3b, v24
	v_exp_f32_e32 v17, v17
	v_mul_f32_e32 v27, v25, v28
	v_fma_f32 v29, -v26, v27, v25
	v_fmac_f32_e32 v27, v29, v28
	v_pk_add_f32 v[16:17], v[16:17], 1.0 op_sel_hi:[1,0]
	v_fma_f32 v25, -v26, v27, v25
	v_div_scale_f32 v26, s[6:7], v17, v17, v24
	v_rcp_f32_e32 v29, v26
	v_div_fmas_f32 v25, v25, v28, v27
	v_div_fixup_f32 v14, v25, v14, 1.0
	v_pk_mul_f32 v[14:15], v[14:15], v[22:23]
	v_fma_f32 v22, -v26, v29, 1.0
	v_fmac_f32_e32 v29, v22, v29
	v_div_scale_f32 v22, vcc, v24, v17, v24
	v_mul_f32_e32 v23, v22, v29
	v_fma_f32 v25, -v26, v23, v22
	v_fmac_f32_e32 v23, v25, v29
	v_div_scale_f32 v25, s[6:7], v16, v16, v1
	v_fma_f32 v22, -v26, v23, v22
	v_rcp_f32_e32 v26, v25
	v_div_fmas_f32 v22, v22, v29, v23
	v_div_fixup_f32 v17, v22, v17, v24
	v_cvt_pk_bf16_f32 v12, v12, v13
	v_fma_f32 v22, -v25, v26, 1.0
	v_fmac_f32_e32 v26, v22, v26
	v_div_scale_f32 v22, vcc, v1, v16, v1
	v_mul_f32_e32 v23, v22, v26
	v_fma_f32 v24, -v25, v23, v22
	v_fmac_f32_e32 v23, v24, v26
	v_fma_f32 v22, -v25, v23, v22
	v_div_fmas_f32 v22, v22, v26, v23
	v_div_fixup_f32 v16, v22, v16, v1
	v_pk_mul_f32 v[14:15], v[16:17], v[14:15]
	v_and_b32_e32 v22, 0xffff0000, v34
	v_cvt_pk_bf16_f32 v13, v14, v15
	global_store_dwordx2 v[18:19], v[12:13], off offset:32
	v_lshlrev_b32_e32 v16, 16, v36
	v_and_b32_e32 v17, 0xffff0000, v36
	s_waitcnt vmcnt(2)
	v_add_f32_e32 v1, v8, v188
	v_mul_f32_e32 v1, 0xbfb8aa3b, v1
	v_exp_f32_e32 v8, v1
	v_add_f32_e32 v1, v9, v189
	v_mul_f32_e32 v1, 0xbfb8aa3b, v1
	v_exp_f32_e32 v9, v1
	v_lshlrev_b32_e32 v1, 16, v34
	v_mul_f32_e32 v12, 0xbfb8aa3b, v1
	v_exp_f32_e32 v12, v12
	v_pk_add_f32 v[8:9], v[8:9], 1.0 op_sel_hi:[1,0]
	s_nop 0
	v_div_scale_f32 v13, s[6:7], v9, v9, 1.0
	v_rcp_f32_e32 v23, v13
	s_nop 0
	v_fma_f32 v24, -v13, v23, 1.0
	v_fmac_f32_e32 v23, v24, v23
	v_div_scale_f32 v24, vcc, 1.0, v9, 1.0
	v_mul_f32_e32 v25, v24, v23
	v_fma_f32 v26, -v13, v25, v24
	v_fmac_f32_e32 v25, v26, v23
	v_fma_f32 v13, -v13, v25, v24
	v_div_scale_f32 v24, s[6:7], v8, v8, 1.0
	v_rcp_f32_e32 v26, v24
	v_div_fmas_f32 v13, v13, v23, v25
	v_div_fixup_f32 v9, v13, v9, 1.0
	v_div_scale_f32 v23, vcc, 1.0, v8, 1.0
	v_fma_f32 v13, -v24, v26, 1.0
	v_fmac_f32_e32 v26, v13, v26
	v_mul_f32_e32 v13, 0xbfb8aa3b, v22
	v_exp_f32_e32 v13, v13
	v_mul_f32_e32 v25, v23, v26
	v_fma_f32 v27, -v24, v25, v23
	v_fmac_f32_e32 v25, v27, v26
	v_pk_add_f32 v[12:13], v[12:13], 1.0 op_sel_hi:[1,0]
	v_fma_f32 v23, -v24, v25, v23
	v_div_scale_f32 v24, s[6:7], v13, v13, v22
	v_rcp_f32_e32 v27, v24
	v_div_fmas_f32 v23, v23, v26, v25
	v_div_fixup_f32 v8, v23, v8, 1.0
	v_pk_mul_f32 v[8:9], v[8:9], v[16:17]
	v_fma_f32 v16, -v24, v27, 1.0
	v_fmac_f32_e32 v27, v16, v27
	v_div_scale_f32 v16, vcc, v22, v13, v22
	v_mul_f32_e32 v17, v16, v27
	v_fma_f32 v23, -v24, v17, v16
	v_fmac_f32_e32 v17, v23, v27
	v_div_scale_f32 v23, s[6:7], v12, v12, v1
	v_fma_f32 v16, -v24, v17, v16
	v_rcp_f32_e32 v24, v23
	v_div_fmas_f32 v16, v16, v27, v17
	v_div_fixup_f32 v13, v16, v13, v22
	v_fma_f32 v16, -v23, v24, 1.0
	v_fmac_f32_e32 v24, v16, v24
	v_div_scale_f32 v16, vcc, v1, v12, v1
	v_mul_f32_e32 v17, v16, v24
	v_fma_f32 v22, -v23, v17, v16
	v_fmac_f32_e32 v17, v22, v24
	v_fma_f32 v16, -v23, v17, v16
	v_div_fmas_f32 v16, v16, v24, v17
	v_div_fixup_f32 v12, v16, v12, v1
	v_add_f32_e32 v1, v10, v190
	v_mul_f32_e32 v1, 0xbfb8aa3b, v1
	v_exp_f32_e32 v10, v1
	v_add_f32_e32 v1, v11, v191
	v_mul_f32_e32 v1, 0xbfb8aa3b, v1
	v_exp_f32_e32 v11, v1
	v_pk_mul_f32 v[8:9], v[12:13], v[8:9]
	v_lshlrev_b32_e32 v1, 16, v35
	v_and_b32_e32 v16, 0xffff0000, v35
	v_pk_add_f32 v[10:11], v[10:11], 1.0 op_sel_hi:[1,0]
	v_mul_f32_e32 v12, 0xbfb8aa3b, v1
	v_div_scale_f32 v13, s[6:7], v11, v11, 1.0
	v_rcp_f32_e32 v17, v13
	v_exp_f32_e32 v12, v12
	v_lshlrev_b32_e32 v14, 16, v37
	v_and_b32_e32 v15, 0xffff0000, v37
	v_fma_f32 v22, -v13, v17, 1.0
	v_fmac_f32_e32 v17, v22, v17
	v_div_scale_f32 v22, vcc, 1.0, v11, 1.0
	v_mul_f32_e32 v23, v22, v17
	v_fma_f32 v24, -v13, v23, v22
	v_fmac_f32_e32 v23, v24, v17
	v_fma_f32 v13, -v13, v23, v22
	v_div_scale_f32 v22, s[6:7], v10, v10, 1.0
	v_rcp_f32_e32 v24, v22
	v_div_fmas_f32 v13, v13, v17, v23
	v_div_fixup_f32 v11, v13, v11, 1.0
	v_div_scale_f32 v17, vcc, 1.0, v10, 1.0
	v_fma_f32 v13, -v22, v24, 1.0
	v_fmac_f32_e32 v24, v13, v24
	v_mul_f32_e32 v13, 0xbfb8aa3b, v16
	v_exp_f32_e32 v13, v13
	v_mul_f32_e32 v23, v17, v24
	v_fma_f32 v25, -v22, v23, v17
	v_fmac_f32_e32 v23, v25, v24
	v_pk_add_f32 v[12:13], v[12:13], 1.0 op_sel_hi:[1,0]
	v_fma_f32 v17, -v22, v23, v17
	v_div_scale_f32 v22, s[6:7], v13, v13, v16
	v_rcp_f32_e32 v25, v22
	v_div_fmas_f32 v17, v17, v24, v23
	v_div_fixup_f32 v10, v17, v10, 1.0
	v_pk_mul_f32 v[10:11], v[10:11], v[14:15]
	v_fma_f32 v14, -v22, v25, 1.0
	v_fmac_f32_e32 v25, v14, v25
	v_div_scale_f32 v14, vcc, v16, v13, v16
	v_mul_f32_e32 v15, v14, v25
	v_fma_f32 v17, -v22, v15, v14
	v_fmac_f32_e32 v15, v17, v25
	v_div_scale_f32 v17, s[6:7], v12, v12, v1
	v_fma_f32 v14, -v22, v15, v14
	v_rcp_f32_e32 v22, v17
	v_div_fmas_f32 v14, v14, v25, v15
	v_div_fixup_f32 v13, v14, v13, v16
	v_cvt_pk_bf16_f32 v8, v8, v9
	v_fma_f32 v14, -v17, v22, 1.0
	v_fmac_f32_e32 v22, v14, v22
	v_div_scale_f32 v14, vcc, v1, v12, v1
	v_mul_f32_e32 v15, v14, v22
	v_fma_f32 v16, -v17, v15, v14
	v_fmac_f32_e32 v15, v16, v22
	v_fma_f32 v14, -v17, v15, v14
	v_div_fmas_f32 v14, v14, v22, v15
	v_div_fixup_f32 v12, v14, v12, v1
	v_pk_mul_f32 v[10:11], v[12:13], v[10:11]
	v_and_b32_e32 v12, 0xffff0000, v32
	v_cvt_pk_bf16_f32 v9, v10, v11
	global_store_dwordx2 v[18:19], v[8:9], off offset:256
	s_waitcnt vmcnt(3)
	v_add_f32_e32 v1, v4, v192
	v_mul_f32_e32 v1, 0xbfb8aa3b, v1
	v_exp_f32_e32 v2, v1
	v_add_f32_e32 v1, v5, v193
	v_mul_f32_e32 v1, 0xbfb8aa3b, v1
	v_exp_f32_e32 v3, v1
	v_lshlrev_b32_e32 v1, 16, v32
	v_mul_f32_e32 v4, 0xbfb8aa3b, v1
	v_exp_f32_e32 v4, v4
	v_pk_add_f32 v[2:3], v[2:3], 1.0 op_sel_hi:[1,0]
	v_lshlrev_b32_e32 v8, 16, v20
	v_div_scale_f32 v5, s[6:7], v3, v3, 1.0
	v_rcp_f32_e32 v13, v5
	v_and_b32_e32 v9, 0xffff0000, v20
	v_fma_f32 v14, -v5, v13, 1.0
	v_fmac_f32_e32 v13, v14, v13
	v_div_scale_f32 v14, vcc, 1.0, v3, 1.0
	v_mul_f32_e32 v15, v14, v13
	v_fma_f32 v16, -v5, v15, v14
	v_fmac_f32_e32 v15, v16, v13
	v_fma_f32 v5, -v5, v15, v14
	v_div_scale_f32 v14, s[6:7], v2, v2, 1.0
	v_rcp_f32_e32 v16, v14
	v_div_fmas_f32 v5, v5, v13, v15
	v_div_fixup_f32 v3, v5, v3, 1.0
	v_div_scale_f32 v13, vcc, 1.0, v2, 1.0
	v_fma_f32 v5, -v14, v16, 1.0
	v_fmac_f32_e32 v16, v5, v16
	v_mul_f32_e32 v5, 0xbfb8aa3b, v12
	v_exp_f32_e32 v5, v5
	v_mul_f32_e32 v15, v13, v16
	v_fma_f32 v17, -v14, v15, v13
	v_fmac_f32_e32 v15, v17, v16
	v_pk_add_f32 v[4:5], v[4:5], 1.0 op_sel_hi:[1,0]
	v_fma_f32 v13, -v14, v15, v13
	v_div_scale_f32 v14, s[6:7], v5, v5, v12
	v_rcp_f32_e32 v17, v14
	v_div_fmas_f32 v13, v13, v16, v15
	v_div_fixup_f32 v2, v13, v2, 1.0
	v_pk_mul_f32 v[2:3], v[2:3], v[8:9]
	v_fma_f32 v8, -v14, v17, 1.0
	v_fmac_f32_e32 v17, v8, v17
	v_div_scale_f32 v8, vcc, v12, v5, v12
	v_mul_f32_e32 v9, v8, v17
	v_fma_f32 v13, -v14, v9, v8
	v_fmac_f32_e32 v9, v13, v17
	v_div_scale_f32 v13, s[6:7], v4, v4, v1
	v_fma_f32 v8, -v14, v9, v8
	v_rcp_f32_e32 v14, v13
	v_div_fmas_f32 v8, v8, v17, v9
	v_div_fixup_f32 v5, v8, v5, v12
	v_fma_f32 v8, -v13, v14, 1.0
	v_fmac_f32_e32 v14, v8, v14
	v_div_scale_f32 v8, vcc, v1, v4, v1
	v_mul_f32_e32 v9, v8, v14
	v_fma_f32 v12, -v13, v9, v8
	v_fmac_f32_e32 v9, v12, v14
	v_fma_f32 v8, -v13, v9, v8
	v_div_fmas_f32 v8, v8, v14, v9
	v_div_fixup_f32 v4, v8, v4, v1
	v_add_f32_e32 v1, v6, v194
	v_mul_f32_e32 v1, 0xbfb8aa3b, v1
	v_pk_mul_f32 v[2:3], v[4:5], v[2:3]
	v_exp_f32_e32 v4, v1
	v_add_f32_e32 v1, v7, v195
	v_mul_f32_e32 v1, 0xbfb8aa3b, v1
	v_exp_f32_e32 v5, v1
	v_lshlrev_b32_e32 v1, 16, v33
	v_and_b32_e32 v10, 0xffff0000, v33
	v_mul_f32_e32 v6, 0xbfb8aa3b, v1
	v_pk_add_f32 v[4:5], v[4:5], 1.0 op_sel_hi:[1,0]
	v_exp_f32_e32 v6, v6
	v_div_scale_f32 v7, s[6:7], v5, v5, 1.0
	v_rcp_f32_e32 v11, v7
	v_lshlrev_b32_e32 v8, 16, v21
	v_and_b32_e32 v9, 0xffff0000, v21
	v_cvt_pk_bf16_f32 v2, v2, v3
	v_fma_f32 v12, -v7, v11, 1.0
	v_fmac_f32_e32 v11, v12, v11
	v_div_scale_f32 v12, vcc, 1.0, v5, 1.0
	v_mul_f32_e32 v13, v12, v11
	v_fma_f32 v14, -v7, v13, v12
	v_fmac_f32_e32 v13, v14, v11
	v_fma_f32 v7, -v7, v13, v12
	v_div_scale_f32 v12, s[6:7], v4, v4, 1.0
	v_rcp_f32_e32 v14, v12
	v_div_fmas_f32 v7, v7, v11, v13
	v_div_fixup_f32 v5, v7, v5, 1.0
	v_div_scale_f32 v11, vcc, 1.0, v4, 1.0
	v_fma_f32 v7, -v12, v14, 1.0
	v_fmac_f32_e32 v14, v7, v14
	v_mul_f32_e32 v7, 0xbfb8aa3b, v10
	v_exp_f32_e32 v7, v7
	v_mul_f32_e32 v13, v11, v14
	v_fma_f32 v15, -v12, v13, v11
	v_fmac_f32_e32 v13, v15, v14
	v_pk_add_f32 v[6:7], v[6:7], 1.0 op_sel_hi:[1,0]
	v_fma_f32 v11, -v12, v13, v11
	v_div_scale_f32 v12, s[6:7], v7, v7, v10
	v_rcp_f32_e32 v15, v12
	v_div_fmas_f32 v11, v11, v14, v13
	v_div_fixup_f32 v4, v11, v4, 1.0
	v_pk_mul_f32 v[4:5], v[4:5], v[8:9]
	v_fma_f32 v8, -v12, v15, 1.0
	v_fmac_f32_e32 v15, v8, v15
	v_div_scale_f32 v8, vcc, v10, v7, v10
	v_mul_f32_e32 v9, v8, v15
	v_fma_f32 v11, -v12, v9, v8
	v_fmac_f32_e32 v9, v11, v15
	v_div_scale_f32 v11, s[6:7], v6, v6, v1
	v_fma_f32 v8, -v12, v9, v8
	v_rcp_f32_e32 v12, v11
	v_div_fmas_f32 v8, v8, v15, v9
	v_div_fixup_f32 v7, v8, v7, v10
	s_mov_b64 s[6:7], s[40:41]
	v_fma_f32 v8, -v11, v12, 1.0
	v_fmac_f32_e32 v12, v8, v12
	v_div_scale_f32 v8, vcc, v1, v6, v1
	v_mul_f32_e32 v9, v8, v12
	v_fma_f32 v10, -v11, v9, v8
	v_fmac_f32_e32 v9, v10, v12
	v_fma_f32 v8, -v11, v9, v8
	v_div_fmas_f32 v8, v8, v12, v9
	v_div_fixup_f32 v6, v8, v6, v1
	v_pk_mul_f32 v[4:5], v[6:7], v[4:5]
	s_and_b64 vcc, exec, s[38:39]
	v_cvt_pk_bf16_f32 v3, v4, v5
	global_store_dwordx2 v[18:19], v[2:3], off offset:288
	s_cbranch_vccnz .LBB0_435

	.amdhsa_kernel _Z10fwd_kernel6Params
		.amdhsa_group_segment_fixed_size 0
		.amdhsa_private_segment_fixed_size 0
		.amdhsa_kernarg_size 512
		.amdhsa_user_sgpr_count 2
		.amdhsa_user_sgpr_dispatch_ptr 0
		.amdhsa_user_sgpr_queue_ptr 0
		.amdhsa_user_sgpr_kernarg_segment_ptr 1
		.amdhsa_user_sgpr_dispatch_id 0
		.amdhsa_user_sgpr_kernarg_preload_length 0
		.amdhsa_user_sgpr_kernarg_preload_offset 0
		.amdhsa_user_sgpr_private_segment_size 0
		.amdhsa_uses_dynamic_stack 0
		.amdhsa_enable_private_segment 0
		.amdhsa_system_sgpr_workgroup_id_x 1
		.amdhsa_system_sgpr_workgroup_id_y 0
		.amdhsa_system_sgpr_workgroup_id_z 0
		.amdhsa_system_sgpr_workgroup_info 0
		.amdhsa_system_vgpr_workitem_id 2
		.amdhsa_next_free_vgpr 256
		.amdhsa_next_free_sgpr 102
		.amdhsa_accum_offset 256
		.amdhsa_reserve_vcc 1
		.amdhsa_float_round_mode_32 0
		.amdhsa_float_round_mode_16_64 0
		.amdhsa_float_denorm_mode_32 3
		.amdhsa_float_denorm_mode_16_64 3
		.amdhsa_dx10_clamp 1
		.amdhsa_ieee_mode 1
		.amdhsa_fp16_overflow 0
		.amdhsa_tg_split 0
		.amdhsa_exception_fp_ieee_invalid_op 0
		.amdhsa_exception_fp_denorm_src 0
		.amdhsa_exception_fp_ieee_div_zero 0
		.amdhsa_exception_fp_ieee_overflow 0
		.amdhsa_exception_fp_ieee_underflow 0
		.amdhsa_exception_fp_ieee_inexact 0
		.amdhsa_exception_int_div_zero 0
	.end_amdhsa_kernel

amdhsa.kernels:
  - .agpr_count:     0
    .args:
      - .offset:         0
        .size:           256
        .value_kind:     by_value
      - .offset:         256
        .size:           4
        .value_kind:     hidden_block_count_x
      - .offset:         260
        .size:           4
        .value_kind:     hidden_block_count_y
      - .offset:         264
        .size:           4
        .value_kind:     hidden_block_count_z
      - .offset:         268
        .size:           2
        .value_kind:     hidden_group_size_x
      - .offset:         270
        .size:           2
        .value_kind:     hidden_group_size_y
      - .offset:         272
        .size:           2
        .value_kind:     hidden_group_size_z
      - .offset:         274
        .size:           2
        .value_kind:     hidden_remainder_x
      - .offset:         276
        .size:           2
        .value_kind:     hidden_remainder_y
      - .offset:         278
        .size:           2
        .value_kind:     hidden_remainder_z
      - .offset:         296
        .size:           8
        .value_kind:     hidden_global_offset_x
      - .offset:         304
        .size:           8
        .value_kind:     hidden_global_offset_y
      - .offset:         312
        .size:           8
        .value_kind:     hidden_global_offset_z
      - .offset:         320
        .size:           2
        .value_kind:     hidden_grid_dims
      - .offset:         344
        .size:           8
        .value_kind:     hidden_multigrid_sync_arg
      - .offset:         376
        .size:           4
        .value_kind:     hidden_dynamic_lds_size
    .group_segment_fixed_size: 0
    .kernarg_segment_align: 8
    .kernarg_segment_size: 512
    .language:       OpenCL C
    .language_version:
      - 2
      - 0
    .max_flat_workgroup_size: 512
    .name:           _Z10fwd_kernel6Params
    .private_segment_fixed_size: 0
    .sgpr_count:     108
    .sgpr_spill_count: 2
    .symbol:         _Z10fwd_kernel6Params.kd
    .uniform_work_group_size: 1
    .uses_dynamic_stack: false
    .vgpr_count:     256
    .vgpr_spill_count: 0
    .wavefront_size: 64
